# 48 compiler-duplicated s_waitcnt lgkmcnt(0) behind the K-loop's own lgkmcnt(0) removed
# speedup vs baseline: 1.0163x; 1.0049x over previous
; #define STAGE(P_, BASE, br, kt) do { const u16* _gb = (BASE) + (long)(br) * K + (long)(kt) * BK; \
;     _Pragma("unroll") for (int _i = 0; _i < 2; ++_i) { \
;       __builtin_amdgcn_global_load_lds((const unsigned*)(_gb + (long)_i * 64 * K + lane_off), \
;         (unsigned*)((char*)(P_) + lds_wbase + _i * 8192), 16, 0, 0); } } while (0)
; #define LDA(dst, b, h) _Pragma("unroll") for (int m = 0; m < 4; ++m) _Pragma("unroll") for (int k = 0; k < 2; ++k) \
;     dst[m][k] = *reinterpret_cast<const bf16x8*>((char*)SA(b, h) + lds_byte(wr * 64 + m * 16 + fr, k * 32 + fq * 8))
; #define LDB(dst, b, h) _Pragma("unroll") for (int n = 0; n < 2; ++n) _Pragma("unroll") for (int k = 0; k < 2; ++k) \
;     dst[n][k] = *reinterpret_cast<const bf16x8*>((char*)SB(b, h) + lds_byte(wc * 32 + n * 16 + fr, k * 32 + fq * 8))
; #define MMA(ai, bj, At_, Bt_) do { __builtin_amdgcn_s_setprio(1); \
;     _Pragma("unroll") for (int m = 0; m < 4; ++m) _Pragma("unroll") for (int n = 0; n < 2; ++n) _Pragma("unroll") for (int k = 0; k < 2; ++k) \
;       acc[ai][bj][m][n] = __builtin_amdgcn_mfma_f32_16x16x32_bf16(At_[m][k], Bt_[n][k], acc[ai][bj][m][n], 0, 0, 0); \
;     __builtin_amdgcn_s_setprio(0); } while (0)
; #define WAIT_V(n) asm volatile("s_waitcnt vmcnt(" #n ")" ::: "memory")
; #define WAIT_L(n) asm volatile("s_waitcnt lgkmcnt(" #n ")" ::: "memory")
; #define BAR __builtin_amdgcn_s_barrier()
; #define SCHED __builtin_amdgcn_sched_barrier(0)
; #define STAGEW(P_, BASE, cur, nxt, kt_) do { const bool _wr = (kt_) >= nt; \
;     STAGE(P_, BASE, (_wr ? (nxt) : (cur)), (_wr ? (kt_) - nt : (kt_))); } while (0)
; template <int PRE> ...
;     ...
;   for (int t = 0; t < nt; t += 2) {
;     LDB(B0, 0, 0); SCHED; LDA(At, 0, 0); STAGE(SA(1, 1), A, brow + HALF, t + 1);
;     WAIT_L(8); BAR; WAIT_L(0); MMA(0, 0, At, B0); BAR; SCHED;
;     LDB(B1, 0, 1); STAGEW(SB(0, 0), Bt, bcol, bcol_n, t + 2);
;     BAR; WAIT_L(0); MMA(0, 1, At, B1); BAR;
;     LDA(At, 0, 1); STAGEW(SA(0, 0), A, brow, brow_n, t + 2);
;     BAR; WAIT_L(0); MMA(1, 0, At, B0); BAR; SCHED;
;     STAGEW(SB(0, 1), Bt, bcol + HALF, bcol_n + HALF, t + 2);
;     WAIT_V(6); BAR; MMA(1, 1, At, B1); BAR;
.LBB0_181:
	v_add_u32_e32 v149, s81, v141
	ds_read_b128 v[136:139], v149
	ds_read_b128 v[150:153], v149 offset:1024
	ds_read_b128 v[154:157], v149 offset:2048
	ds_read_b128 v[158:161], v149 offset:3072
	s_add_i32 m0, s12, 0xc000
	ds_read_b128 v[168:171], v142
	ds_read_b128 v[172:175], v142 offset:1024
	ds_read_b128 v[176:179], v143
	ds_read_b128 v[180:183], v143 offset:1024
	ds_read_b128 v[184:187], v144
	ds_read_b128 v[188:191], v144 offset:1024
	ds_read_b128 v[192:195], v146
	ds_read_b128 v[210:213], v146 offset:1024
	global_load_lds_dwordx4 v[134:135], off
	v_lshl_add_u64 v[162:163], v[134:135], 0, s[86:87]
	s_add_i32 m0, s12, 0xe000
	s_nop 0
	global_load_lds_dwordx4 v[162:163], off
	s_waitcnt lgkmcnt(8)
	s_barrier
	s_waitcnt lgkmcnt(0)
	v_mfma_f32_16x16x32_bf16 v[126:129], v[168:171], v[136:139], v[126:129]
	v_mfma_f32_16x16x32_bf16 v[122:125], v[168:171], v[154:157], v[122:125]
	v_mfma_f32_16x16x32_bf16 v[118:121], v[176:179], v[136:139], v[118:121]
	v_mfma_f32_16x16x32_bf16 v[114:117], v[176:179], v[154:157], v[114:117]
	v_mfma_f32_16x16x32_bf16 v[110:113], v[184:187], v[136:139], v[110:113]
	v_mfma_f32_16x16x32_bf16 v[106:109], v[184:187], v[154:157], v[106:109]
	v_mfma_f32_16x16x32_bf16 v[102:105], v[192:195], v[136:139], v[102:105]
	v_mfma_f32_16x16x32_bf16 v[98:101], v[192:195], v[154:157], v[98:101]
	v_mfma_f32_16x16x32_bf16 v[126:129], v[172:175], v[150:153], v[126:129]
	v_mfma_f32_16x16x32_bf16 v[122:125], v[172:175], v[158:161], v[122:125]
	v_mfma_f32_16x16x32_bf16 v[118:121], v[180:183], v[150:153], v[118:121]
	v_mfma_f32_16x16x32_bf16 v[114:117], v[180:183], v[158:161], v[114:117]
	v_mfma_f32_16x16x32_bf16 v[110:113], v[188:191], v[150:153], v[110:113]
	v_mfma_f32_16x16x32_bf16 v[106:109], v[188:191], v[158:161], v[106:109]
	v_mfma_f32_16x16x32_bf16 v[102:105], v[210:213], v[150:153], v[102:105]
	v_mfma_f32_16x16x32_bf16 v[98:101], v[210:213], v[158:161], v[98:101]
	s_barrier
	s_add_i32 s1, s38, 2
	s_cmp_lt_u32 s38, 30
	s_cselect_b64 s[2:3], -1, 0
	s_and_b64 vcc, s[2:3], exec
	s_cselect_b32 s6, s10, s11
	s_cselect_b32 s3, 0, 0xffffffe0
	s_cselect_b32 s40, s0, s31
	s_cselect_b32 s42, s36, s35
	s_cselect_b32 s2, s34, s37
	s_ashr_i32 s7, s6, 31
	s_lshl_b64 s[6:7], s[6:7], 12
	s_add_u32 s39, s52, s6
	s_addc_u32 s41, s53, s7
	s_add_i32 s18, s1, s3
	s_lshl_b64 s[6:7], s[18:19], 7
	s_add_u32 s44, s39, s6
	s_addc_u32 s45, s41, s7
	s_mov_b32 m0, s13
	v_add_u32_e32 v149, s82, v141
	v_lshl_add_u64 v[162:163], s[44:45], 0, v[130:131]
	ds_read_b128 v[214:217], v149
	ds_read_b128 v[218:221], v149 offset:1024
	ds_read_b128 v[222:225], v149 offset:2048
	ds_read_b128 v[226:229], v149 offset:3072
	global_load_lds_dwordx4 v[162:163], off
	v_lshl_add_u64 v[162:163], v[162:163], 0, s[86:87]
	s_mov_b32 m0, s14
	s_nop 0
	global_load_lds_dwordx4 v[162:163], off
	s_barrier
	s_waitcnt lgkmcnt(0)
	v_mfma_f32_16x16x32_bf16 v[94:97], v[168:171], v[214:217], v[94:97]
	v_mfma_f32_16x16x32_bf16 v[90:93], v[168:171], v[222:225], v[90:93]
	v_mfma_f32_16x16x32_bf16 v[86:89], v[176:179], v[214:217], v[86:89]
	v_mfma_f32_16x16x32_bf16 v[82:85], v[176:179], v[222:225], v[82:85]
	v_mfma_f32_16x16x32_bf16 v[78:81], v[184:187], v[214:217], v[78:81]
	v_mfma_f32_16x16x32_bf16 v[74:77], v[184:187], v[222:225], v[74:77]
	v_mfma_f32_16x16x32_bf16 v[70:73], v[192:195], v[214:217], v[70:73]
	v_mfma_f32_16x16x32_bf16 v[64:67], v[192:195], v[222:225], v[64:67]
	v_mfma_f32_16x16x32_bf16 v[94:97], v[172:175], v[218:221], v[94:97]
	v_mfma_f32_16x16x32_bf16 v[90:93], v[172:175], v[226:229], v[90:93]
	v_mfma_f32_16x16x32_bf16 v[86:89], v[180:183], v[218:221], v[86:89]
	v_mfma_f32_16x16x32_bf16 v[82:85], v[180:183], v[226:229], v[82:85]
	v_mfma_f32_16x16x32_bf16 v[78:81], v[188:191], v[218:221], v[78:81]
	v_mfma_f32_16x16x32_bf16 v[74:77], v[188:191], v[226:229], v[74:77]
	v_mfma_f32_16x16x32_bf16 v[70:73], v[210:213], v[218:221], v[70:73]
	v_mfma_f32_16x16x32_bf16 v[64:67], v[210:213], v[226:229], v[64:67]
	s_ashr_i32 s41, s40, 31
	s_lshl_b64 s[40:41], s[40:41], 12
	s_add_u32 s3, s50, s40
	s_addc_u32 s18, s51, s41
	s_add_u32 s40, s3, s6
	s_addc_u32 s41, s18, s7
	s_mov_b32 m0, s12
	v_lshl_add_u64 v[162:163], s[40:41], 0, v[130:131]
	s_barrier
	ds_read_b128 v[168:171], v142 offset:16384
	ds_read_b128 v[172:175], v142 offset:17408
	ds_read_b128 v[176:179], v143 offset:16384
	ds_read_b128 v[180:183], v143 offset:17408
	ds_read_b128 v[184:187], v144 offset:16384
	ds_read_b128 v[188:191], v144 offset:17408
	ds_read_b128 v[192:195], v146 offset:16384
	ds_read_b128 v[210:213], v146 offset:17408
	global_load_lds_dwordx4 v[162:163], off
	v_lshl_add_u64 v[162:163], v[162:163], 0, s[86:87]
	s_mov_b32 m0, s15
	s_nop 0
	global_load_lds_dwordx4 v[162:163], off
	s_barrier
	s_waitcnt lgkmcnt(0)
	v_mfma_f32_16x16x32_bf16 v[60:63], v[168:171], v[136:139], v[60:63]
	v_mfma_f32_16x16x32_bf16 v[56:59], v[168:171], v[154:157], v[56:59]
	v_mfma_f32_16x16x32_bf16 v[52:55], v[176:179], v[136:139], v[52:55]
	v_mfma_f32_16x16x32_bf16 v[48:51], v[176:179], v[154:157], v[48:51]
	v_mfma_f32_16x16x32_bf16 v[44:47], v[184:187], v[136:139], v[44:47]
	v_mfma_f32_16x16x32_bf16 v[40:43], v[184:187], v[154:157], v[40:43]
	v_mfma_f32_16x16x32_bf16 v[36:39], v[192:195], v[136:139], v[36:39]
	v_mfma_f32_16x16x32_bf16 v[32:35], v[192:195], v[154:157], v[32:35]
	v_mfma_f32_16x16x32_bf16 v[60:63], v[172:175], v[150:153], v[60:63]
	v_mfma_f32_16x16x32_bf16 v[56:59], v[172:175], v[158:161], v[56:59]
	v_mfma_f32_16x16x32_bf16 v[52:55], v[180:183], v[150:153], v[52:55]
	v_mfma_f32_16x16x32_bf16 v[48:51], v[180:183], v[158:161], v[48:51]
	v_mfma_f32_16x16x32_bf16 v[44:47], v[188:191], v[150:153], v[44:47]
	v_mfma_f32_16x16x32_bf16 v[40:43], v[188:191], v[158:161], v[40:43]
	v_mfma_f32_16x16x32_bf16 v[36:39], v[210:213], v[150:153], v[36:39]
	v_mfma_f32_16x16x32_bf16 v[32:35], v[210:213], v[158:161], v[32:35]
	s_barrier
; #define LDA(dst, b, h) _Pragma("unroll") for (int m = 0; m < 4; ++m) _Pragma("unroll") for (int k = 0; k < 2; ++k) \
;     dst[m][k] = *reinterpret_cast<const bf16x8*>((char*)SA(b, h) + lds_byte(wr * 64 + m * 16 + fr, k * 32 + fq * 8))
; #define LDB(dst, b, h) _Pragma("unroll") for (int n = 0; n < 2; ++n) _Pragma("unroll") for (int k = 0; k < 2; ++k) \
;     dst[n][k] = *reinterpret_cast<const bf16x8*>((char*)SB(b, h) + lds_byte(wc * 32 + n * 16 + fr, k * 32 + fq * 8))
; #define MMA(ai, bj, At_, Bt_) do { __builtin_amdgcn_s_setprio(1); \
;     _Pragma("unroll") for (int m = 0; m < 4; ++m) _Pragma("unroll") for (int n = 0; n < 2; ++n) _Pragma("unroll") for (int k = 0; k < 2; ++k) \
;       acc[ai][bj][m][n] = __builtin_amdgcn_mfma_f32_16x16x32_bf16(At_[m][k], Bt_[n][k], acc[ai][bj][m][n], 0, 0, 0); \
;     __builtin_amdgcn_s_setprio(0); } while (0)
; #define WAIT_V(n) asm volatile("s_waitcnt vmcnt(" #n ")" ::: "memory")
; #define WAIT_L(n) asm volatile("s_waitcnt lgkmcnt(" #n ")" ::: "memory")
; #define BAR __builtin_amdgcn_s_barrier()
; #define SCHED __builtin_amdgcn_sched_barrier(0)
; #define STAGEW(P_, BASE, cur, nxt, kt_) do { const bool _wr = (kt_) >= nt; \
;     STAGE(P_, BASE, (_wr ? (nxt) : (cur)), (_wr ? (kt_) - nt : (kt_))); } while (0)
; template <int PRE> ...
;     ...
;     STAGEW(SB(0, 1), Bt, bcol + HALF, bcol_n + HALF, t + 2);
;     WAIT_V(6); BAR; MMA(1, 1, At, B1); BAR;
;     LDB(B0, 1, 0); SCHED; LDA(At, 1, 0); STAGEW(SA(0, 1), A, brow + HALF, brow_n + HALF, t + 2);
;     WAIT_L(8); BAR; WAIT_L(0); MMA(0, 0, At, B0); BAR; SCHED;
;     LDB(B1, 1, 1); STAGEW(SB(1, 0), Bt, bcol, bcol_n, t + 3);
;     BAR; WAIT_L(0); MMA(0, 1, At, B1); BAR;
;     LDA(At, 1, 1); STAGEW(SA(1, 0), A, brow, brow_n, t + 3);
;     BAR; WAIT_L(0); MMA(1, 0, At, B0); BAR; SCHED;
;     STAGEW(SB(1, 1), Bt, bcol + HALF, bcol_n + HALF, t + 3);
	s_ashr_i32 s43, s42, 31
	s_lshl_b64 s[40:41], s[42:43], 12
	s_add_u32 s3, s52, s40
	s_addc_u32 s18, s53, s41
	s_add_u32 s40, s3, s6
	s_addc_u32 s41, s18, s7
	s_mov_b32 m0, s16
	v_lshl_add_u64 v[136:137], s[40:41], 0, v[130:131]
	global_load_lds_dwordx4 v[136:137], off
	v_lshl_add_u64 v[136:137], v[136:137], 0, s[86:87]
	s_mov_b32 m0, s17
	s_nop 0
	global_load_lds_dwordx4 v[136:137], off
	s_waitcnt vmcnt(6)
	s_barrier
	v_mfma_f32_16x16x32_bf16 v[28:31], v[168:171], v[214:217], v[28:31]
	v_mfma_f32_16x16x32_bf16 v[24:27], v[168:171], v[222:225], v[24:27]
	v_mfma_f32_16x16x32_bf16 v[20:23], v[176:179], v[214:217], v[20:23]
	v_mfma_f32_16x16x32_bf16 v[16:19], v[176:179], v[222:225], v[16:19]
	v_mfma_f32_16x16x32_bf16 v[12:15], v[184:187], v[214:217], v[12:15]
	v_mfma_f32_16x16x32_bf16 v[8:11], v[184:187], v[222:225], v[8:11]
	v_mfma_f32_16x16x32_bf16 v[4:7], v[192:195], v[214:217], v[4:7]
	v_mfma_f32_16x16x32_bf16 v[0:3], v[192:195], v[222:225], v[0:3]
	v_mfma_f32_16x16x32_bf16 v[28:31], v[172:175], v[218:221], v[28:31]
	v_mfma_f32_16x16x32_bf16 v[24:27], v[172:175], v[226:229], v[24:27]
	v_mfma_f32_16x16x32_bf16 v[20:23], v[180:183], v[218:221], v[20:23]
	v_mfma_f32_16x16x32_bf16 v[16:19], v[180:183], v[226:229], v[16:19]
	v_mfma_f32_16x16x32_bf16 v[12:15], v[188:191], v[218:221], v[12:15]
	v_mfma_f32_16x16x32_bf16 v[8:11], v[188:191], v[226:229], v[8:11]
	v_mfma_f32_16x16x32_bf16 v[4:7], v[210:213], v[218:221], v[4:7]
	v_mfma_f32_16x16x32_bf16 v[0:3], v[210:213], v[226:229], v[0:3]
	v_add_u32_e32 v149, s83, v141
	s_barrier
	ds_read_b128 v[136:139], v149
	ds_read_b128 v[150:153], v149 offset:1024
	ds_read_b128 v[154:157], v149 offset:2048
	ds_read_b128 v[158:161], v149 offset:3072
	s_ashr_i32 s3, s2, 31
	s_lshl_b64 s[2:3], s[2:3], 12
	s_add_u32 s2, s50, s2
	s_addc_u32 s3, s51, s3
	s_add_u32 s2, s2, s6
	s_addc_u32 s3, s3, s7
	s_mov_b32 m0, s21
	v_lshl_add_u64 v[162:163], s[2:3], 0, v[130:131]
	ds_read_b128 v[168:171], v142 offset:32768
	ds_read_b128 v[172:175], v142 offset:33792
	ds_read_b128 v[176:179], v143 offset:32768
	ds_read_b128 v[180:183], v143 offset:33792
	ds_read_b128 v[184:187], v144 offset:32768
	ds_read_b128 v[188:191], v144 offset:33792
	ds_read_b128 v[192:195], v146 offset:32768
	ds_read_b128 v[210:213], v146 offset:33792
	global_load_lds_dwordx4 v[162:163], off
	v_lshl_add_u64 v[162:163], v[162:163], 0, s[86:87]
	s_mov_b32 m0, s22
	s_nop 0
	global_load_lds_dwordx4 v[162:163], off
	s_waitcnt lgkmcnt(8)
	s_barrier
	s_waitcnt lgkmcnt(0)
	v_mfma_f32_16x16x32_bf16 v[126:129], v[168:171], v[136:139], v[126:129]
	v_mfma_f32_16x16x32_bf16 v[122:125], v[168:171], v[154:157], v[122:125]
	v_mfma_f32_16x16x32_bf16 v[118:121], v[176:179], v[136:139], v[118:121]
	v_mfma_f32_16x16x32_bf16 v[114:117], v[176:179], v[154:157], v[114:117]
	v_mfma_f32_16x16x32_bf16 v[110:113], v[184:187], v[136:139], v[110:113]
	v_mfma_f32_16x16x32_bf16 v[106:109], v[184:187], v[154:157], v[106:109]
	v_mfma_f32_16x16x32_bf16 v[102:105], v[192:195], v[136:139], v[102:105]
	v_mfma_f32_16x16x32_bf16 v[98:101], v[192:195], v[154:157], v[98:101]
	v_mfma_f32_16x16x32_bf16 v[126:129], v[172:175], v[150:153], v[126:129]
	v_mfma_f32_16x16x32_bf16 v[122:125], v[172:175], v[158:161], v[122:125]
	v_mfma_f32_16x16x32_bf16 v[118:121], v[180:183], v[150:153], v[118:121]
	v_mfma_f32_16x16x32_bf16 v[114:117], v[180:183], v[158:161], v[114:117]
	v_mfma_f32_16x16x32_bf16 v[110:113], v[188:191], v[150:153], v[110:113]
	v_mfma_f32_16x16x32_bf16 v[106:109], v[188:191], v[158:161], v[106:109]
	v_mfma_f32_16x16x32_bf16 v[102:105], v[210:213], v[150:153], v[102:105]
	v_mfma_f32_16x16x32_bf16 v[98:101], v[210:213], v[158:161], v[98:101]
	s_barrier
	s_cmp_lt_u32 s38, 29
	s_cselect_b32 s2, s10, s11
	s_cselect_b32 s7, 0, 0xffffffe0
	s_cselect_b32 s6, s0, s31
	s_cselect_b32 s40, s36, s35
	s_ashr_i32 s3, s2, 31
	s_lshl_b64 s[2:3], s[2:3], 12
	s_add_u32 s39, s52, s2
	s_addc_u32 s41, s53, s3
	s_add_i32 s2, s7, s38
	s_add_i32 s18, s2, 3
	s_lshl_b64 s[2:3], s[18:19], 7
	s_add_u32 s38, s39, s2
	s_addc_u32 s39, s41, s3
	s_mov_b32 m0, s23
	v_add_u32_e32 v149, s84, v141
	v_lshl_add_u64 v[162:163], s[38:39], 0, v[130:131]
	ds_read_b128 v[214:217], v149
	ds_read_b128 v[218:221], v149 offset:1024
	ds_read_b128 v[222:225], v149 offset:2048
	ds_read_b128 v[226:229], v149 offset:3072
	global_load_lds_dwordx4 v[162:163], off
	v_lshl_add_u64 v[162:163], v[162:163], 0, s[86:87]
	s_mov_b32 m0, s24
	s_nop 0
	global_load_lds_dwordx4 v[162:163], off
	s_barrier
; #define LDA(dst, b, h) _Pragma("unroll") for (int m = 0; m < 4; ++m) _Pragma("unroll") for (int k = 0; k < 2; ++k) \
;     dst[m][k] = *reinterpret_cast<const bf16x8*>((char*)SA(b, h) + lds_byte(wr * 64 + m * 16 + fr, k * 32 + fq * 8))
; #define LDB(dst, b, h) _Pragma("unroll") for (int n = 0; n < 2; ++n) _Pragma("unroll") for (int k = 0; k < 2; ++k) \
;     dst[n][k] = *reinterpret_cast<const bf16x8*>((char*)SB(b, h) + lds_byte(wc * 32 + n * 16 + fr, k * 32 + fq * 8))
; #define MMA(ai, bj, At_, Bt_) do { __builtin_amdgcn_s_setprio(1); \
;     _Pragma("unroll") for (int m = 0; m < 4; ++m) _Pragma("unroll") for (int n = 0; n < 2; ++n) _Pragma("unroll") for (int k = 0; k < 2; ++k) \
;       acc[ai][bj][m][n] = __builtin_amdgcn_mfma_f32_16x16x32_bf16(At_[m][k], Bt_[n][k], acc[ai][bj][m][n], 0, 0, 0); \
;     __builtin_amdgcn_s_setprio(0); } while (0)
; #define WAIT_V(n) asm volatile("s_waitcnt vmcnt(" #n ")" ::: "memory")
; #define WAIT_L(n) asm volatile("s_waitcnt lgkmcnt(" #n ")" ::: "memory")
; #define BAR __builtin_amdgcn_s_barrier()
; #define SCHED __builtin_amdgcn_sched_barrier(0)
; #define STAGEW(P_, BASE, cur, nxt, kt_) do { const bool _wr = (kt_) >= nt; \
;     STAGE(P_, BASE, (_wr ? (nxt) : (cur)), (_wr ? (kt_) - nt : (kt_))); } while (0)
; template <int PRE> ...
;     ...
;     LDB(B1, 1, 1); STAGEW(SB(1, 0), Bt, bcol, bcol_n, t + 3);
;     BAR; WAIT_L(0); MMA(0, 1, At, B1); BAR;
;     LDA(At, 1, 1); STAGEW(SA(1, 0), A, brow, brow_n, t + 3);
;     BAR; WAIT_L(0); MMA(1, 0, At, B0); BAR; SCHED;
;     STAGEW(SB(1, 1), Bt, bcol + HALF, bcol_n + HALF, t + 3);
;     WAIT_V(6); BAR; MMA(1, 1, At, B1); BAR;
;   }
;   if (wr == 0) BAR;
	s_waitcnt lgkmcnt(0)
	v_mfma_f32_16x16x32_bf16 v[94:97], v[168:171], v[214:217], v[94:97]
	v_mfma_f32_16x16x32_bf16 v[90:93], v[168:171], v[222:225], v[90:93]
	v_mfma_f32_16x16x32_bf16 v[86:89], v[176:179], v[214:217], v[86:89]
	v_mfma_f32_16x16x32_bf16 v[82:85], v[176:179], v[222:225], v[82:85]
	v_mfma_f32_16x16x32_bf16 v[78:81], v[184:187], v[214:217], v[78:81]
	v_mfma_f32_16x16x32_bf16 v[74:77], v[184:187], v[222:225], v[74:77]
	v_mfma_f32_16x16x32_bf16 v[70:73], v[192:195], v[214:217], v[70:73]
	v_mfma_f32_16x16x32_bf16 v[64:67], v[192:195], v[222:225], v[64:67]
	v_mfma_f32_16x16x32_bf16 v[94:97], v[172:175], v[218:221], v[94:97]
	v_mfma_f32_16x16x32_bf16 v[90:93], v[172:175], v[226:229], v[90:93]
	v_mfma_f32_16x16x32_bf16 v[86:89], v[180:183], v[218:221], v[86:89]
	v_mfma_f32_16x16x32_bf16 v[82:85], v[180:183], v[226:229], v[82:85]
	v_mfma_f32_16x16x32_bf16 v[78:81], v[188:191], v[218:221], v[78:81]
	v_mfma_f32_16x16x32_bf16 v[74:77], v[188:191], v[226:229], v[74:77]
	v_mfma_f32_16x16x32_bf16 v[70:73], v[210:213], v[218:221], v[70:73]
	v_mfma_f32_16x16x32_bf16 v[64:67], v[210:213], v[226:229], v[64:67]
	s_ashr_i32 s7, s6, 31
	s_lshl_b64 s[6:7], s[6:7], 12
	s_add_u32 s6, s50, s6
	s_addc_u32 s7, s51, s7
	s_add_u32 s6, s6, s2
	s_addc_u32 s7, s7, s3
	s_mov_b32 m0, s25
	v_lshl_add_u64 v[162:163], s[6:7], 0, v[130:131]
	s_barrier
	ds_read_b128 v[168:171], v142 offset:49152
	ds_read_b128 v[172:175], v142 offset:50176
	ds_read_b128 v[176:179], v143 offset:49152
	ds_read_b128 v[180:183], v143 offset:50176
	ds_read_b128 v[184:187], v144 offset:49152
	ds_read_b128 v[188:191], v144 offset:50176
	ds_read_b128 v[192:195], v146 offset:49152
	ds_read_b128 v[210:213], v146 offset:50176
	global_load_lds_dwordx4 v[162:163], off
	v_lshl_add_u64 v[162:163], v[162:163], 0, s[86:87]
	s_mov_b32 m0, s26
	s_nop 0
	global_load_lds_dwordx4 v[162:163], off
	s_barrier
	s_waitcnt lgkmcnt(0)
	v_mfma_f32_16x16x32_bf16 v[60:63], v[168:171], v[136:139], v[60:63]
	v_mfma_f32_16x16x32_bf16 v[56:59], v[168:171], v[154:157], v[56:59]
	v_mfma_f32_16x16x32_bf16 v[52:55], v[176:179], v[136:139], v[52:55]
	v_mfma_f32_16x16x32_bf16 v[48:51], v[176:179], v[154:157], v[48:51]
	v_mfma_f32_16x16x32_bf16 v[44:47], v[184:187], v[136:139], v[44:47]
	v_mfma_f32_16x16x32_bf16 v[40:43], v[184:187], v[154:157], v[40:43]
	v_mfma_f32_16x16x32_bf16 v[36:39], v[192:195], v[136:139], v[36:39]
	v_mfma_f32_16x16x32_bf16 v[32:35], v[192:195], v[154:157], v[32:35]
	v_mfma_f32_16x16x32_bf16 v[60:63], v[172:175], v[150:153], v[60:63]
	v_mfma_f32_16x16x32_bf16 v[56:59], v[172:175], v[158:161], v[56:59]
	v_mfma_f32_16x16x32_bf16 v[52:55], v[180:183], v[150:153], v[52:55]
	v_mfma_f32_16x16x32_bf16 v[48:51], v[180:183], v[158:161], v[48:51]
	v_mfma_f32_16x16x32_bf16 v[44:47], v[188:191], v[150:153], v[44:47]
	v_mfma_f32_16x16x32_bf16 v[40:43], v[188:191], v[158:161], v[40:43]
	v_mfma_f32_16x16x32_bf16 v[36:39], v[210:213], v[150:153], v[36:39]
	v_mfma_f32_16x16x32_bf16 v[32:35], v[210:213], v[158:161], v[32:35]
	s_barrier
	s_ashr_i32 s41, s40, 31
	s_lshl_b64 s[6:7], s[40:41], 12
	s_add_u32 s6, s52, s6
	s_addc_u32 s7, s53, s7
	s_add_u32 s2, s6, s2
	s_addc_u32 s3, s7, s3
	s_mov_b32 m0, s27
	v_lshl_add_u64 v[136:137], s[2:3], 0, v[130:131]
	global_load_lds_dwordx4 v[136:137], off
	v_lshl_add_u64 v[136:137], v[136:137], 0, s[86:87]
	s_mov_b32 m0, s28
	s_nop 0
	global_load_lds_dwordx4 v[136:137], off
	s_waitcnt vmcnt(6)
	s_barrier
	v_mfma_f32_16x16x32_bf16 v[28:31], v[168:171], v[214:217], v[28:31]
	v_mfma_f32_16x16x32_bf16 v[24:27], v[168:171], v[222:225], v[24:27]
	v_mfma_f32_16x16x32_bf16 v[20:23], v[176:179], v[214:217], v[20:23]
	v_mfma_f32_16x16x32_bf16 v[16:19], v[176:179], v[222:225], v[16:19]
	v_mfma_f32_16x16x32_bf16 v[12:15], v[184:187], v[214:217], v[12:15]
	v_mfma_f32_16x16x32_bf16 v[8:11], v[184:187], v[222:225], v[8:11]
	v_mfma_f32_16x16x32_bf16 v[4:7], v[192:195], v[214:217], v[4:7]
	v_mfma_f32_16x16x32_bf16 v[0:3], v[192:195], v[222:225], v[0:3]
	v_mfma_f32_16x16x32_bf16 v[28:31], v[172:175], v[218:221], v[28:31]
	v_mfma_f32_16x16x32_bf16 v[24:27], v[172:175], v[226:229], v[24:27]
	v_mfma_f32_16x16x32_bf16 v[20:23], v[180:183], v[218:221], v[20:23]
	v_mfma_f32_16x16x32_bf16 v[16:19], v[180:183], v[226:229], v[16:19]
	v_mfma_f32_16x16x32_bf16 v[12:15], v[188:191], v[218:221], v[12:15]
	v_mfma_f32_16x16x32_bf16 v[8:11], v[188:191], v[226:229], v[8:11]
	v_mfma_f32_16x16x32_bf16 v[4:7], v[210:213], v[218:221], v[4:7]
	v_mfma_f32_16x16x32_bf16 v[0:3], v[210:213], v[226:229], v[0:3]
	v_lshl_add_u64 v[134:135], v[134:135], 0, s[46:47]
	s_mov_b32 s38, s1
	s_barrier
	s_cbranch_vccnz .LBB0_181
	s_andn2_b64 vcc, exec, s[58:59]
	s_cbranch_vccnz .LBB0_184
	s_barrier

; #define STAGE(P_, BASE, br, kt) do { const u16* _gb = (BASE) + (long)(br) * K + (long)(kt) * BK; \
;     _Pragma("unroll") for (int _i = 0; _i < 2; ++_i) { \
;       __builtin_amdgcn_global_load_lds((const unsigned*)(_gb + (long)_i * 64 * K + lane_off), \
;         (unsigned*)((char*)(P_) + lds_wbase + _i * 8192), 16, 0, 0); } } while (0)
; #define LDA(dst, b, h) _Pragma("unroll") for (int m = 0; m < 4; ++m) _Pragma("unroll") for (int k = 0; k < 2; ++k) \
;     dst[m][k] = *reinterpret_cast<const bf16x8*>((char*)SA(b, h) + lds_byte(wr * 64 + m * 16 + fr, k * 32 + fq * 8))
; #define LDB(dst, b, h) _Pragma("unroll") for (int n = 0; n < 2; ++n) _Pragma("unroll") for (int k = 0; k < 2; ++k) \
;     dst[n][k] = *reinterpret_cast<const bf16x8*>((char*)SB(b, h) + lds_byte(wc * 32 + n * 16 + fr, k * 32 + fq * 8))
; #define MMA(ai, bj, At_, Bt_) do { __builtin_amdgcn_s_setprio(1); \
;     _Pragma("unroll") for (int m = 0; m < 4; ++m) _Pragma("unroll") for (int n = 0; n < 2; ++n) _Pragma("unroll") for (int k = 0; k < 2; ++k) \
;       acc[ai][bj][m][n] = __builtin_amdgcn_mfma_f32_16x16x32_bf16(At_[m][k], Bt_[n][k], acc[ai][bj][m][n], 0, 0, 0); \
;     __builtin_amdgcn_s_setprio(0); } while (0)
; #define WAIT_V(n) asm volatile("s_waitcnt vmcnt(" #n ")" ::: "memory")
; #define WAIT_L(n) asm volatile("s_waitcnt lgkmcnt(" #n ")" ::: "memory")
; #define BAR __builtin_amdgcn_s_barrier()
; #define SCHED __builtin_amdgcn_sched_barrier(0)
; #define STAGEW(P_, BASE, cur, nxt, kt_) do { const bool _wr = (kt_) >= nt; \
;     STAGE(P_, BASE, (_wr ? (nxt) : (cur)), (_wr ? (kt_) - nt : (kt_))); } while (0)
; template <int PRE> ...
;     ...
;   for (int t = 0; t < nt; t += 2) {
;     LDB(B0, 0, 0); SCHED; LDA(At, 0, 0); STAGE(SA(1, 1), A, brow + HALF, t + 1);
;     WAIT_L(8); BAR; WAIT_L(0); MMA(0, 0, At, B0); BAR; SCHED;
;     LDB(B1, 0, 1); STAGEW(SB(0, 0), Bt, bcol, bcol_n, t + 2);
;     BAR; WAIT_L(0); MMA(0, 1, At, B1); BAR;
;     LDA(At, 0, 1); STAGEW(SA(0, 0), A, brow, brow_n, t + 2);
;     BAR; WAIT_L(0); MMA(1, 0, At, B0); BAR; SCHED;
;     STAGEW(SB(0, 1), Bt, bcol + HALF, bcol_n + HALF, t + 2);
;     WAIT_V(6); BAR; MMA(1, 1, At, B1); BAR;
.LBB0_456:
	v_add_u32_e32 v136, s81, v139
	ds_read_b128 v[148:151], v136
	ds_read_b128 v[152:155], v136 offset:1024
	ds_read_b128 v[156:159], v136 offset:2048
	ds_read_b128 v[160:163], v136 offset:3072
	s_add_i32 m0, s14, 0xc000
	ds_read_b128 v[168:171], v140
	ds_read_b128 v[172:175], v140 offset:1024
	ds_read_b128 v[176:179], v141
	ds_read_b128 v[180:183], v141 offset:1024
	ds_read_b128 v[184:187], v142
	ds_read_b128 v[188:191], v142 offset:1024
	ds_read_b128 v[192:195], v143
	ds_read_b128 v[210:213], v143 offset:1024
	global_load_lds_dwordx4 v[134:135], off
	v_lshl_add_u64 v[136:137], v[134:135], 0, s[86:87]
	s_add_i32 m0, s14, 0xe000
	s_nop 0
	global_load_lds_dwordx4 v[136:137], off
	s_waitcnt lgkmcnt(8)
	s_barrier
	s_waitcnt lgkmcnt(0)
	v_mfma_f32_16x16x32_bf16 v[126:129], v[168:171], v[148:151], v[126:129]
	v_mfma_f32_16x16x32_bf16 v[122:125], v[168:171], v[156:159], v[122:125]
	v_mfma_f32_16x16x32_bf16 v[118:121], v[176:179], v[148:151], v[118:121]
	v_mfma_f32_16x16x32_bf16 v[114:117], v[176:179], v[156:159], v[114:117]
	v_mfma_f32_16x16x32_bf16 v[110:113], v[184:187], v[148:151], v[110:113]
	v_mfma_f32_16x16x32_bf16 v[106:109], v[184:187], v[156:159], v[106:109]
	v_mfma_f32_16x16x32_bf16 v[102:105], v[192:195], v[148:151], v[102:105]
	v_mfma_f32_16x16x32_bf16 v[98:101], v[192:195], v[156:159], v[98:101]
	v_mfma_f32_16x16x32_bf16 v[126:129], v[172:175], v[152:155], v[126:129]
	v_mfma_f32_16x16x32_bf16 v[122:125], v[172:175], v[160:163], v[122:125]
	v_mfma_f32_16x16x32_bf16 v[118:121], v[180:183], v[152:155], v[118:121]
	v_mfma_f32_16x16x32_bf16 v[114:117], v[180:183], v[160:163], v[114:117]
	v_mfma_f32_16x16x32_bf16 v[110:113], v[188:191], v[152:155], v[110:113]
	v_mfma_f32_16x16x32_bf16 v[106:109], v[188:191], v[160:163], v[106:109]
	v_mfma_f32_16x16x32_bf16 v[102:105], v[210:213], v[152:155], v[102:105]
	v_mfma_f32_16x16x32_bf16 v[98:101], v[210:213], v[160:163], v[98:101]
	s_barrier
	s_add_i32 s41, s1, 2
	s_cmp_lt_u32 s1, 30
	s_cselect_b64 s[2:3], -1, 0
	s_and_b64 vcc, s[2:3], exec
	s_cselect_b32 s6, s8, s9
	s_cselect_b32 s3, 0, 0xffffffe0
	s_cselect_b32 s42, s0, s36
	s_cselect_b32 s44, s39, s38
	s_cselect_b32 s2, s37, s40
	s_ashr_i32 s7, s6, 31
	s_lshl_b64 s[6:7], s[6:7], 12
	s_add_u32 s43, s33, s6
	s_addc_u32 s45, s92, s7
	s_add_i32 s18, s41, s3
	s_lshl_b64 s[6:7], s[18:19], 7
	s_add_u32 s46, s43, s6
	v_add_u32_e32 v136, s82, v139
	s_addc_u32 s47, s45, s7
	s_mov_b32 m0, s15
	ds_read_b128 v[214:217], v136
	ds_read_b128 v[218:221], v136 offset:1024
	ds_read_b128 v[222:225], v136 offset:2048
	ds_read_b128 v[226:229], v136 offset:3072
	v_lshl_add_u64 v[136:137], s[46:47], 0, v[130:131]
	global_load_lds_dwordx4 v[136:137], off
	v_lshl_add_u64 v[136:137], v[136:137], 0, s[86:87]
	s_mov_b32 m0, s16
	s_mov_b64 s[46:47], 0x100
	global_load_lds_dwordx4 v[136:137], off
	s_barrier
	s_waitcnt lgkmcnt(0)
	v_mfma_f32_16x16x32_bf16 v[94:97], v[168:171], v[214:217], v[94:97]
	v_mfma_f32_16x16x32_bf16 v[90:93], v[168:171], v[222:225], v[90:93]
	v_mfma_f32_16x16x32_bf16 v[86:89], v[176:179], v[214:217], v[86:89]
	v_mfma_f32_16x16x32_bf16 v[82:85], v[176:179], v[222:225], v[82:85]
	v_mfma_f32_16x16x32_bf16 v[78:81], v[184:187], v[214:217], v[78:81]
	v_mfma_f32_16x16x32_bf16 v[74:77], v[184:187], v[222:225], v[74:77]
	v_mfma_f32_16x16x32_bf16 v[70:73], v[192:195], v[214:217], v[70:73]
	v_mfma_f32_16x16x32_bf16 v[64:67], v[192:195], v[222:225], v[64:67]
	v_mfma_f32_16x16x32_bf16 v[94:97], v[172:175], v[218:221], v[94:97]
	v_mfma_f32_16x16x32_bf16 v[90:93], v[172:175], v[226:229], v[90:93]
	v_mfma_f32_16x16x32_bf16 v[86:89], v[180:183], v[218:221], v[86:89]
	v_mfma_f32_16x16x32_bf16 v[82:85], v[180:183], v[226:229], v[82:85]
	v_mfma_f32_16x16x32_bf16 v[78:81], v[188:191], v[218:221], v[78:81]
	v_mfma_f32_16x16x32_bf16 v[74:77], v[188:191], v[226:229], v[74:77]
	v_mfma_f32_16x16x32_bf16 v[70:73], v[210:213], v[218:221], v[70:73]
	v_mfma_f32_16x16x32_bf16 v[64:67], v[210:213], v[226:229], v[64:67]
	s_ashr_i32 s43, s42, 31
	s_lshl_b64 s[42:43], s[42:43], 12
	s_add_u32 s3, s94, s42
	s_addc_u32 s18, s95, s43
	s_add_u32 s42, s3, s6
	s_addc_u32 s43, s18, s7
	s_mov_b32 m0, s14
	v_lshl_add_u64 v[136:137], s[42:43], 0, v[130:131]
	s_barrier
	ds_read_b128 v[168:171], v140 offset:16384
	ds_read_b128 v[172:175], v140 offset:17408
	ds_read_b128 v[176:179], v141 offset:16384
	ds_read_b128 v[180:183], v141 offset:17408
	ds_read_b128 v[184:187], v142 offset:16384
	ds_read_b128 v[188:191], v142 offset:17408
	ds_read_b128 v[192:195], v143 offset:16384
	ds_read_b128 v[210:213], v143 offset:17408
	global_load_lds_dwordx4 v[136:137], off
	v_lshl_add_u64 v[136:137], v[136:137], 0, s[86:87]
	s_mov_b32 m0, s17
	s_nop 0
	global_load_lds_dwordx4 v[136:137], off
	s_barrier
	s_waitcnt lgkmcnt(0)
	v_mfma_f32_16x16x32_bf16 v[60:63], v[168:171], v[148:151], v[60:63]
	v_mfma_f32_16x16x32_bf16 v[56:59], v[168:171], v[156:159], v[56:59]
	v_mfma_f32_16x16x32_bf16 v[52:55], v[176:179], v[148:151], v[52:55]
	v_mfma_f32_16x16x32_bf16 v[48:51], v[176:179], v[156:159], v[48:51]
	v_mfma_f32_16x16x32_bf16 v[44:47], v[184:187], v[148:151], v[44:47]
	v_mfma_f32_16x16x32_bf16 v[40:43], v[184:187], v[156:159], v[40:43]
	v_mfma_f32_16x16x32_bf16 v[36:39], v[192:195], v[148:151], v[36:39]
	v_mfma_f32_16x16x32_bf16 v[32:35], v[192:195], v[156:159], v[32:35]
	v_mfma_f32_16x16x32_bf16 v[60:63], v[172:175], v[152:155], v[60:63]
	v_mfma_f32_16x16x32_bf16 v[56:59], v[172:175], v[160:163], v[56:59]
	v_mfma_f32_16x16x32_bf16 v[52:55], v[180:183], v[152:155], v[52:55]
	v_mfma_f32_16x16x32_bf16 v[48:51], v[180:183], v[160:163], v[48:51]
	v_mfma_f32_16x16x32_bf16 v[44:47], v[188:191], v[152:155], v[44:47]
	v_mfma_f32_16x16x32_bf16 v[40:43], v[188:191], v[160:163], v[40:43]
	v_mfma_f32_16x16x32_bf16 v[36:39], v[210:213], v[152:155], v[36:39]
	v_mfma_f32_16x16x32_bf16 v[32:35], v[210:213], v[160:163], v[32:35]
	s_barrier
; #define LDA(dst, b, h) _Pragma("unroll") for (int m = 0; m < 4; ++m) _Pragma("unroll") for (int k = 0; k < 2; ++k) \
;     dst[m][k] = *reinterpret_cast<const bf16x8*>((char*)SA(b, h) + lds_byte(wr * 64 + m * 16 + fr, k * 32 + fq * 8))
; #define LDB(dst, b, h) _Pragma("unroll") for (int n = 0; n < 2; ++n) _Pragma("unroll") for (int k = 0; k < 2; ++k) \
;     dst[n][k] = *reinterpret_cast<const bf16x8*>((char*)SB(b, h) + lds_byte(wc * 32 + n * 16 + fr, k * 32 + fq * 8))
; #define MMA(ai, bj, At_, Bt_) do { __builtin_amdgcn_s_setprio(1); \
;     _Pragma("unroll") for (int m = 0; m < 4; ++m) _Pragma("unroll") for (int n = 0; n < 2; ++n) _Pragma("unroll") for (int k = 0; k < 2; ++k) \
;       acc[ai][bj][m][n] = __builtin_amdgcn_mfma_f32_16x16x32_bf16(At_[m][k], Bt_[n][k], acc[ai][bj][m][n], 0, 0, 0); \
;     __builtin_amdgcn_s_setprio(0); } while (0)
; #define WAIT_V(n) asm volatile("s_waitcnt vmcnt(" #n ")" ::: "memory")
; #define WAIT_L(n) asm volatile("s_waitcnt lgkmcnt(" #n ")" ::: "memory")
; #define BAR __builtin_amdgcn_s_barrier()
; #define SCHED __builtin_amdgcn_sched_barrier(0)
; #define STAGEW(P_, BASE, cur, nxt, kt_) do { const bool _wr = (kt_) >= nt; \
;     STAGE(P_, BASE, (_wr ? (nxt) : (cur)), (_wr ? (kt_) - nt : (kt_))); } while (0)
; template <int PRE> ...
;     ...
;     STAGEW(SB(0, 1), Bt, bcol + HALF, bcol_n + HALF, t + 2);
;     WAIT_V(6); BAR; MMA(1, 1, At, B1); BAR;
;     LDB(B0, 1, 0); SCHED; LDA(At, 1, 0); STAGEW(SA(0, 1), A, brow + HALF, brow_n + HALF, t + 2);
;     WAIT_L(8); BAR; WAIT_L(0); MMA(0, 0, At, B0); BAR; SCHED;
;     LDB(B1, 1, 1); STAGEW(SB(1, 0), Bt, bcol, bcol_n, t + 3);
;     BAR; WAIT_L(0); MMA(0, 1, At, B1); BAR;
;     LDA(At, 1, 1); STAGEW(SA(1, 0), A, brow, brow_n, t + 3);
;     BAR; WAIT_L(0); MMA(1, 0, At, B0); BAR; SCHED;
;     STAGEW(SB(1, 1), Bt, bcol + HALF, bcol_n + HALF, t + 3);
	s_ashr_i32 s45, s44, 31
	s_lshl_b64 s[42:43], s[44:45], 12
	s_add_u32 s3, s33, s42
	s_addc_u32 s18, s92, s43
	s_add_u32 s42, s3, s6
	s_addc_u32 s43, s18, s7
	s_mov_b32 m0, s20
	v_lshl_add_u64 v[136:137], s[42:43], 0, v[130:131]
	global_load_lds_dwordx4 v[136:137], off
	v_lshl_add_u64 v[136:137], v[136:137], 0, s[86:87]
	s_mov_b32 m0, s21
	s_nop 0
	global_load_lds_dwordx4 v[136:137], off
	s_waitcnt vmcnt(6)
	s_barrier
	v_mfma_f32_16x16x32_bf16 v[28:31], v[168:171], v[214:217], v[28:31]
	v_mfma_f32_16x16x32_bf16 v[24:27], v[168:171], v[222:225], v[24:27]
	v_mfma_f32_16x16x32_bf16 v[20:23], v[176:179], v[214:217], v[20:23]
	v_mfma_f32_16x16x32_bf16 v[16:19], v[176:179], v[222:225], v[16:19]
	v_mfma_f32_16x16x32_bf16 v[12:15], v[184:187], v[214:217], v[12:15]
	v_mfma_f32_16x16x32_bf16 v[8:11], v[184:187], v[222:225], v[8:11]
	v_mfma_f32_16x16x32_bf16 v[4:7], v[192:195], v[214:217], v[4:7]
	v_mfma_f32_16x16x32_bf16 v[0:3], v[192:195], v[222:225], v[0:3]
	v_mfma_f32_16x16x32_bf16 v[28:31], v[172:175], v[218:221], v[28:31]
	v_mfma_f32_16x16x32_bf16 v[24:27], v[172:175], v[226:229], v[24:27]
	v_mfma_f32_16x16x32_bf16 v[20:23], v[180:183], v[218:221], v[20:23]
	v_mfma_f32_16x16x32_bf16 v[16:19], v[180:183], v[226:229], v[16:19]
	v_mfma_f32_16x16x32_bf16 v[12:15], v[188:191], v[218:221], v[12:15]
	v_mfma_f32_16x16x32_bf16 v[8:11], v[188:191], v[226:229], v[8:11]
	v_mfma_f32_16x16x32_bf16 v[4:7], v[210:213], v[218:221], v[4:7]
	v_mfma_f32_16x16x32_bf16 v[0:3], v[210:213], v[226:229], v[0:3]
	v_add_u32_e32 v136, s83, v139
	s_barrier
	ds_read_b128 v[148:151], v136
	ds_read_b128 v[152:155], v136 offset:1024
	ds_read_b128 v[156:159], v136 offset:2048
	ds_read_b128 v[160:163], v136 offset:3072
	s_ashr_i32 s3, s2, 31
	s_lshl_b64 s[2:3], s[2:3], 12
	s_add_u32 s2, s94, s2
	s_addc_u32 s3, s95, s3
	s_add_u32 s2, s2, s6
	s_addc_u32 s3, s3, s7
	s_mov_b32 m0, s22
	v_lshl_add_u64 v[136:137], s[2:3], 0, v[130:131]
	ds_read_b128 v[168:171], v140 offset:32768
	ds_read_b128 v[172:175], v140 offset:33792
	ds_read_b128 v[176:179], v141 offset:32768
	ds_read_b128 v[180:183], v141 offset:33792
	ds_read_b128 v[184:187], v142 offset:32768
	ds_read_b128 v[188:191], v142 offset:33792
	ds_read_b128 v[192:195], v143 offset:32768
	ds_read_b128 v[210:213], v143 offset:33792
	global_load_lds_dwordx4 v[136:137], off
	v_lshl_add_u64 v[136:137], v[136:137], 0, s[86:87]
	s_mov_b32 m0, s23
	s_nop 0
	global_load_lds_dwordx4 v[136:137], off
	s_waitcnt lgkmcnt(8)
	s_barrier
	s_waitcnt lgkmcnt(0)
	v_mfma_f32_16x16x32_bf16 v[126:129], v[168:171], v[148:151], v[126:129]
	v_mfma_f32_16x16x32_bf16 v[122:125], v[168:171], v[156:159], v[122:125]
	v_mfma_f32_16x16x32_bf16 v[118:121], v[176:179], v[148:151], v[118:121]
	v_mfma_f32_16x16x32_bf16 v[114:117], v[176:179], v[156:159], v[114:117]
	v_mfma_f32_16x16x32_bf16 v[110:113], v[184:187], v[148:151], v[110:113]
	v_mfma_f32_16x16x32_bf16 v[106:109], v[184:187], v[156:159], v[106:109]
	v_mfma_f32_16x16x32_bf16 v[102:105], v[192:195], v[148:151], v[102:105]
	v_mfma_f32_16x16x32_bf16 v[98:101], v[192:195], v[156:159], v[98:101]
	v_mfma_f32_16x16x32_bf16 v[126:129], v[172:175], v[152:155], v[126:129]
	v_mfma_f32_16x16x32_bf16 v[122:125], v[172:175], v[160:163], v[122:125]
	v_mfma_f32_16x16x32_bf16 v[118:121], v[180:183], v[152:155], v[118:121]
	v_mfma_f32_16x16x32_bf16 v[114:117], v[180:183], v[160:163], v[114:117]
	v_mfma_f32_16x16x32_bf16 v[110:113], v[188:191], v[152:155], v[110:113]
	v_mfma_f32_16x16x32_bf16 v[106:109], v[188:191], v[160:163], v[106:109]
	v_mfma_f32_16x16x32_bf16 v[102:105], v[210:213], v[152:155], v[102:105]
	v_mfma_f32_16x16x32_bf16 v[98:101], v[210:213], v[160:163], v[98:101]
	s_barrier
	s_cmp_lt_u32 s1, 29
	s_cselect_b32 s2, s8, s9
	s_cselect_b32 s7, 0, 0xffffffe0
	s_cselect_b32 s6, s0, s36
	s_cselect_b32 s42, s39, s38
	s_ashr_i32 s3, s2, 31
	s_lshl_b64 s[2:3], s[2:3], 12
	s_add_u32 s43, s33, s2
	s_addc_u32 s45, s92, s3
	s_add_i32 s1, s7, s1
	s_add_i32 s18, s1, 3
	s_lshl_b64 s[2:3], s[18:19], 7
	s_add_u32 s44, s43, s2
	v_add_u32_e32 v136, s84, v139
	s_addc_u32 s45, s45, s3
	s_mov_b32 m0, s24
	ds_read_b128 v[214:217], v136
	ds_read_b128 v[218:221], v136 offset:1024
	ds_read_b128 v[222:225], v136 offset:2048
	ds_read_b128 v[226:229], v136 offset:3072
	v_lshl_add_u64 v[136:137], s[44:45], 0, v[130:131]
	global_load_lds_dwordx4 v[136:137], off
	v_lshl_add_u64 v[136:137], v[136:137], 0, s[86:87]
	s_mov_b32 m0, s25
	s_nop 0
	global_load_lds_dwordx4 v[136:137], off
	s_barrier
; #define LDA(dst, b, h) _Pragma("unroll") for (int m = 0; m < 4; ++m) _Pragma("unroll") for (int k = 0; k < 2; ++k) \
;     dst[m][k] = *reinterpret_cast<const bf16x8*>((char*)SA(b, h) + lds_byte(wr * 64 + m * 16 + fr, k * 32 + fq * 8))
; #define LDB(dst, b, h) _Pragma("unroll") for (int n = 0; n < 2; ++n) _Pragma("unroll") for (int k = 0; k < 2; ++k) \
;     dst[n][k] = *reinterpret_cast<const bf16x8*>((char*)SB(b, h) + lds_byte(wc * 32 + n * 16 + fr, k * 32 + fq * 8))
; #define MMA(ai, bj, At_, Bt_) do { __builtin_amdgcn_s_setprio(1); \
;     _Pragma("unroll") for (int m = 0; m < 4; ++m) _Pragma("unroll") for (int n = 0; n < 2; ++n) _Pragma("unroll") for (int k = 0; k < 2; ++k) \
;       acc[ai][bj][m][n] = __builtin_amdgcn_mfma_f32_16x16x32_bf16(At_[m][k], Bt_[n][k], acc[ai][bj][m][n], 0, 0, 0); \
;     __builtin_amdgcn_s_setprio(0); } while (0)
; #define WAIT_V(n) asm volatile("s_waitcnt vmcnt(" #n ")" ::: "memory")
; #define WAIT_L(n) asm volatile("s_waitcnt lgkmcnt(" #n ")" ::: "memory")
; #define BAR __builtin_amdgcn_s_barrier()
; #define SCHED __builtin_amdgcn_sched_barrier(0)
; #define STAGEW(P_, BASE, cur, nxt, kt_) do { const bool _wr = (kt_) >= nt; \
;     STAGE(P_, BASE, (_wr ? (nxt) : (cur)), (_wr ? (kt_) - nt : (kt_))); } while (0)
; template <int PRE> ...
;     ...
;     LDB(B1, 1, 1); STAGEW(SB(1, 0), Bt, bcol, bcol_n, t + 3);
;     BAR; WAIT_L(0); MMA(0, 1, At, B1); BAR;
;     LDA(At, 1, 1); STAGEW(SA(1, 0), A, brow, brow_n, t + 3);
;     BAR; WAIT_L(0); MMA(1, 0, At, B0); BAR; SCHED;
;     STAGEW(SB(1, 1), Bt, bcol + HALF, bcol_n + HALF, t + 3);
;     WAIT_V(6); BAR; MMA(1, 1, At, B1); BAR;
;   }
;   if (wr == 0) BAR;
	s_waitcnt lgkmcnt(0)
	v_mfma_f32_16x16x32_bf16 v[94:97], v[168:171], v[214:217], v[94:97]
	v_mfma_f32_16x16x32_bf16 v[90:93], v[168:171], v[222:225], v[90:93]
	v_mfma_f32_16x16x32_bf16 v[86:89], v[176:179], v[214:217], v[86:89]
	v_mfma_f32_16x16x32_bf16 v[82:85], v[176:179], v[222:225], v[82:85]
	v_mfma_f32_16x16x32_bf16 v[78:81], v[184:187], v[214:217], v[78:81]
	v_mfma_f32_16x16x32_bf16 v[74:77], v[184:187], v[222:225], v[74:77]
	v_mfma_f32_16x16x32_bf16 v[70:73], v[192:195], v[214:217], v[70:73]
	v_mfma_f32_16x16x32_bf16 v[64:67], v[192:195], v[222:225], v[64:67]
	v_mfma_f32_16x16x32_bf16 v[94:97], v[172:175], v[218:221], v[94:97]
	v_mfma_f32_16x16x32_bf16 v[90:93], v[172:175], v[226:229], v[90:93]
	v_mfma_f32_16x16x32_bf16 v[86:89], v[180:183], v[218:221], v[86:89]
	v_mfma_f32_16x16x32_bf16 v[82:85], v[180:183], v[226:229], v[82:85]
	v_mfma_f32_16x16x32_bf16 v[78:81], v[188:191], v[218:221], v[78:81]
	v_mfma_f32_16x16x32_bf16 v[74:77], v[188:191], v[226:229], v[74:77]
	v_mfma_f32_16x16x32_bf16 v[70:73], v[210:213], v[218:221], v[70:73]
	v_mfma_f32_16x16x32_bf16 v[64:67], v[210:213], v[226:229], v[64:67]
	s_ashr_i32 s7, s6, 31
	s_lshl_b64 s[6:7], s[6:7], 12
	s_add_u32 s1, s94, s6
	s_addc_u32 s7, s95, s7
	s_add_u32 s6, s1, s2
	s_addc_u32 s7, s7, s3
	s_mov_b32 m0, s26
	v_lshl_add_u64 v[136:137], s[6:7], 0, v[130:131]
	s_barrier
	ds_read_b128 v[168:171], v140 offset:49152
	ds_read_b128 v[172:175], v140 offset:50176
	ds_read_b128 v[176:179], v141 offset:49152
	ds_read_b128 v[180:183], v141 offset:50176
	ds_read_b128 v[184:187], v142 offset:49152
	ds_read_b128 v[188:191], v142 offset:50176
	ds_read_b128 v[192:195], v143 offset:49152
	ds_read_b128 v[210:213], v143 offset:50176
	global_load_lds_dwordx4 v[136:137], off
	v_lshl_add_u64 v[136:137], v[136:137], 0, s[86:87]
	s_mov_b32 m0, s27
	s_nop 0
	global_load_lds_dwordx4 v[136:137], off
	s_barrier
	s_waitcnt lgkmcnt(0)
	v_mfma_f32_16x16x32_bf16 v[60:63], v[168:171], v[148:151], v[60:63]
	v_mfma_f32_16x16x32_bf16 v[56:59], v[168:171], v[156:159], v[56:59]
	v_mfma_f32_16x16x32_bf16 v[52:55], v[176:179], v[148:151], v[52:55]
	v_mfma_f32_16x16x32_bf16 v[48:51], v[176:179], v[156:159], v[48:51]
	v_mfma_f32_16x16x32_bf16 v[44:47], v[184:187], v[148:151], v[44:47]
	v_mfma_f32_16x16x32_bf16 v[40:43], v[184:187], v[156:159], v[40:43]
	v_mfma_f32_16x16x32_bf16 v[36:39], v[192:195], v[148:151], v[36:39]
	v_mfma_f32_16x16x32_bf16 v[32:35], v[192:195], v[156:159], v[32:35]
	v_mfma_f32_16x16x32_bf16 v[60:63], v[172:175], v[152:155], v[60:63]
	v_mfma_f32_16x16x32_bf16 v[56:59], v[172:175], v[160:163], v[56:59]
	v_mfma_f32_16x16x32_bf16 v[52:55], v[180:183], v[152:155], v[52:55]
	v_mfma_f32_16x16x32_bf16 v[48:51], v[180:183], v[160:163], v[48:51]
	v_mfma_f32_16x16x32_bf16 v[44:47], v[188:191], v[152:155], v[44:47]
	v_mfma_f32_16x16x32_bf16 v[40:43], v[188:191], v[160:163], v[40:43]
	v_mfma_f32_16x16x32_bf16 v[36:39], v[210:213], v[152:155], v[36:39]
	v_mfma_f32_16x16x32_bf16 v[32:35], v[210:213], v[160:163], v[32:35]
	s_barrier
	s_ashr_i32 s43, s42, 31
	s_lshl_b64 s[6:7], s[42:43], 12
	s_add_u32 s1, s33, s6
	s_addc_u32 s6, s92, s7
	s_add_u32 s2, s1, s2
	s_addc_u32 s3, s6, s3
	s_mov_b32 m0, s28
	v_lshl_add_u64 v[136:137], s[2:3], 0, v[130:131]
	global_load_lds_dwordx4 v[136:137], off
	v_lshl_add_u64 v[136:137], v[136:137], 0, s[86:87]
	s_mov_b32 m0, s29
	s_nop 0
	global_load_lds_dwordx4 v[136:137], off
	s_waitcnt vmcnt(6)
	s_barrier
	v_mfma_f32_16x16x32_bf16 v[28:31], v[168:171], v[214:217], v[28:31]
	v_mfma_f32_16x16x32_bf16 v[24:27], v[168:171], v[222:225], v[24:27]
	v_mfma_f32_16x16x32_bf16 v[20:23], v[176:179], v[214:217], v[20:23]
	v_mfma_f32_16x16x32_bf16 v[16:19], v[176:179], v[222:225], v[16:19]
	v_mfma_f32_16x16x32_bf16 v[12:15], v[184:187], v[214:217], v[12:15]
	v_mfma_f32_16x16x32_bf16 v[8:11], v[184:187], v[222:225], v[8:11]
	v_mfma_f32_16x16x32_bf16 v[4:7], v[192:195], v[214:217], v[4:7]
	v_mfma_f32_16x16x32_bf16 v[0:3], v[192:195], v[222:225], v[0:3]
	v_mfma_f32_16x16x32_bf16 v[28:31], v[172:175], v[218:221], v[28:31]
	v_mfma_f32_16x16x32_bf16 v[24:27], v[172:175], v[226:229], v[24:27]
	v_mfma_f32_16x16x32_bf16 v[20:23], v[180:183], v[218:221], v[20:23]
	v_mfma_f32_16x16x32_bf16 v[16:19], v[180:183], v[226:229], v[16:19]
	v_mfma_f32_16x16x32_bf16 v[12:15], v[188:191], v[218:221], v[12:15]
	v_mfma_f32_16x16x32_bf16 v[8:11], v[188:191], v[226:229], v[8:11]
	v_mfma_f32_16x16x32_bf16 v[4:7], v[210:213], v[218:221], v[4:7]
	v_mfma_f32_16x16x32_bf16 v[0:3], v[210:213], v[226:229], v[0:3]
	v_lshl_add_u64 v[134:135], v[134:135], 0, s[46:47]
	s_mov_b32 s1, s41
	s_barrier
	s_cbranch_vccnz .LBB0_456
	s_andn2_b64 vcc, exec, s[58:59]
	s_cbranch_vccnz .LBB0_459
	s_barrier

; #define STAGE(P_, BASE, br, kt) do { const u16* _gb = (BASE) + (long)(br) * K + (long)(kt) * BK; \
;     _Pragma("unroll") for (int _i = 0; _i < 2; ++_i) { \
;       __builtin_amdgcn_global_load_lds((const unsigned*)(_gb + (long)_i * 64 * K + lane_off), \
;         (unsigned*)((char*)(P_) + lds_wbase + _i * 8192), 16, 0, 0); } } while (0)
; #define LDA(dst, b, h) _Pragma("unroll") for (int m = 0; m < 4; ++m) _Pragma("unroll") for (int k = 0; k < 2; ++k) \
;     dst[m][k] = *reinterpret_cast<const bf16x8*>((char*)SA(b, h) + lds_byte(wr * 64 + m * 16 + fr, k * 32 + fq * 8))
; #define LDB(dst, b, h) _Pragma("unroll") for (int n = 0; n < 2; ++n) _Pragma("unroll") for (int k = 0; k < 2; ++k) \
;     dst[n][k] = *reinterpret_cast<const bf16x8*>((char*)SB(b, h) + lds_byte(wc * 32 + n * 16 + fr, k * 32 + fq * 8))
; #define MMA(ai, bj, At_, Bt_) do { __builtin_amdgcn_s_setprio(1); \
;     _Pragma("unroll") for (int m = 0; m < 4; ++m) _Pragma("unroll") for (int n = 0; n < 2; ++n) _Pragma("unroll") for (int k = 0; k < 2; ++k) \
;       acc[ai][bj][m][n] = __builtin_amdgcn_mfma_f32_16x16x32_bf16(At_[m][k], Bt_[n][k], acc[ai][bj][m][n], 0, 0, 0); \
;     __builtin_amdgcn_s_setprio(0); } while (0)
; #define WAIT_V(n) asm volatile("s_waitcnt vmcnt(" #n ")" ::: "memory")
; #define WAIT_L(n) asm volatile("s_waitcnt lgkmcnt(" #n ")" ::: "memory")
; #define BAR __builtin_amdgcn_s_barrier()
; #define SCHED __builtin_amdgcn_sched_barrier(0)
; #define STAGEW(P_, BASE, cur, nxt, kt_) do { const bool _wr = (kt_) >= nt; \
;     STAGE(P_, BASE, (_wr ? (nxt) : (cur)), (_wr ? (kt_) - nt : (kt_))); } while (0)
; template <int PRE> ...
;     ...
;   for (int t = 0; t < nt; t += 2) {
;     LDB(B0, 0, 0); SCHED; LDA(At, 0, 0); STAGE(SA(1, 1), A, brow + HALF, t + 1);
;     WAIT_L(8); BAR; WAIT_L(0); MMA(0, 0, At, B0); BAR; SCHED;
;     LDB(B1, 0, 1); STAGEW(SB(0, 0), Bt, bcol, bcol_n, t + 2);
;     BAR; WAIT_L(0); MMA(0, 1, At, B1); BAR;
;     LDA(At, 0, 1); STAGEW(SA(0, 0), A, brow, brow_n, t + 2);
;     BAR; WAIT_L(0); MMA(1, 0, At, B0); BAR; SCHED;
;     STAGEW(SB(0, 1), Bt, bcol + HALF, bcol_n + HALF, t + 2);
;     WAIT_V(6); BAR; MMA(1, 1, At, B1); BAR;
.LBB0_550:
	v_add_u32_e32 v144, s81, v139
	ds_read_b128 v[146:149], v144
	ds_read_b128 v[150:153], v144 offset:1024
	ds_read_b128 v[154:157], v144 offset:2048
	ds_read_b128 v[158:161], v144 offset:3072
	s_add_i32 m0, s1, 0xc000
	ds_read_b128 v[168:171], v140
	ds_read_b128 v[172:175], v140 offset:1024
	ds_read_b128 v[176:179], v141
	ds_read_b128 v[180:183], v141 offset:1024
	ds_read_b128 v[184:187], v142
	ds_read_b128 v[188:191], v142 offset:1024
	ds_read_b128 v[192:195], v143
	ds_read_b128 v[210:213], v143 offset:1024
	global_load_lds_dwordx4 v[136:137], off
	v_lshl_add_u64 v[162:163], v[136:137], 0, s[86:87]
	s_add_i32 m0, s1, 0xe000
	s_nop 0
	global_load_lds_dwordx4 v[162:163], off
	s_waitcnt lgkmcnt(8)
	s_barrier
	s_waitcnt lgkmcnt(0)
	v_mfma_f32_16x16x32_bf16 v[124:127], v[168:171], v[146:149], v[124:127]
	v_mfma_f32_16x16x32_bf16 v[120:123], v[168:171], v[154:157], v[120:123]
	v_mfma_f32_16x16x32_bf16 v[116:119], v[176:179], v[146:149], v[116:119]
	v_mfma_f32_16x16x32_bf16 v[112:115], v[176:179], v[154:157], v[112:115]
	v_mfma_f32_16x16x32_bf16 v[108:111], v[184:187], v[146:149], v[108:111]
	v_mfma_f32_16x16x32_bf16 v[104:107], v[184:187], v[154:157], v[104:107]
	v_mfma_f32_16x16x32_bf16 v[100:103], v[192:195], v[146:149], v[100:103]
	v_mfma_f32_16x16x32_bf16 v[96:99], v[192:195], v[154:157], v[96:99]
	v_mfma_f32_16x16x32_bf16 v[124:127], v[172:175], v[150:153], v[124:127]
	v_mfma_f32_16x16x32_bf16 v[120:123], v[172:175], v[158:161], v[120:123]
	v_mfma_f32_16x16x32_bf16 v[116:119], v[180:183], v[150:153], v[116:119]
	v_mfma_f32_16x16x32_bf16 v[112:115], v[180:183], v[158:161], v[112:115]
	v_mfma_f32_16x16x32_bf16 v[108:111], v[188:191], v[150:153], v[108:111]
	v_mfma_f32_16x16x32_bf16 v[104:107], v[188:191], v[158:161], v[104:107]
	v_mfma_f32_16x16x32_bf16 v[100:103], v[210:213], v[150:153], v[100:103]
	v_mfma_f32_16x16x32_bf16 v[96:99], v[210:213], v[158:161], v[96:99]
	s_barrier
	s_add_i32 s22, s21, 2
	s_cmp_lt_u32 s21, 30
	s_cselect_b64 s[4:5], -1, 0
	s_and_b64 vcc, s[4:5], exec
	s_cselect_b32 s4, 0, 0xffffffe0
	s_add_i32 s18, s22, s4
	s_lshl_b64 s[4:5], s[18:19], 7
	s_mov_b32 m0, s6
	v_add_u32_e32 v144, s82, v139
	v_lshl_add_u64 v[162:163], v[128:129], 0, s[4:5]
	ds_read_b128 v[214:217], v144
	ds_read_b128 v[218:221], v144 offset:1024
	ds_read_b128 v[222:225], v144 offset:2048
	ds_read_b128 v[226:229], v144 offset:3072
	global_load_lds_dwordx4 v[162:163], off
	v_lshl_add_u64 v[162:163], v[162:163], 0, s[86:87]
	s_mov_b32 m0, s7
	s_nop 0
	global_load_lds_dwordx4 v[162:163], off
	s_barrier
	s_waitcnt lgkmcnt(0)
	v_mfma_f32_16x16x32_bf16 v[92:95], v[168:171], v[214:217], v[92:95]
	v_mfma_f32_16x16x32_bf16 v[88:91], v[168:171], v[222:225], v[88:91]
	v_mfma_f32_16x16x32_bf16 v[84:87], v[176:179], v[214:217], v[84:87]
	v_mfma_f32_16x16x32_bf16 v[80:83], v[176:179], v[222:225], v[80:83]
	v_mfma_f32_16x16x32_bf16 v[76:79], v[184:187], v[214:217], v[76:79]
	v_mfma_f32_16x16x32_bf16 v[72:75], v[184:187], v[222:225], v[72:75]
	v_mfma_f32_16x16x32_bf16 v[68:71], v[192:195], v[214:217], v[68:71]
	v_mfma_f32_16x16x32_bf16 v[64:67], v[192:195], v[222:225], v[64:67]
	v_mfma_f32_16x16x32_bf16 v[92:95], v[172:175], v[218:221], v[92:95]
	v_mfma_f32_16x16x32_bf16 v[88:91], v[172:175], v[226:229], v[88:91]
	v_mfma_f32_16x16x32_bf16 v[84:87], v[180:183], v[218:221], v[84:87]
	v_mfma_f32_16x16x32_bf16 v[80:83], v[180:183], v[226:229], v[80:83]
	v_mfma_f32_16x16x32_bf16 v[76:79], v[188:191], v[218:221], v[76:79]
	v_mfma_f32_16x16x32_bf16 v[72:75], v[188:191], v[226:229], v[72:75]
	v_mfma_f32_16x16x32_bf16 v[68:71], v[210:213], v[218:221], v[68:71]
	v_mfma_f32_16x16x32_bf16 v[64:67], v[210:213], v[226:229], v[64:67]
	s_mov_b32 m0, s1
	v_lshl_add_u64 v[162:163], v[130:131], 0, s[4:5]
	s_barrier
	ds_read_b128 v[168:171], v140 offset:16384
	ds_read_b128 v[172:175], v140 offset:17408
	ds_read_b128 v[176:179], v141 offset:16384
	ds_read_b128 v[180:183], v141 offset:17408
	ds_read_b128 v[184:187], v142 offset:16384
	ds_read_b128 v[188:191], v142 offset:17408
	ds_read_b128 v[192:195], v143 offset:16384
	ds_read_b128 v[210:213], v143 offset:17408
	global_load_lds_dwordx4 v[162:163], off
	v_lshl_add_u64 v[162:163], v[162:163], 0, s[86:87]
	s_mov_b32 m0, s3
	s_nop 0
	global_load_lds_dwordx4 v[162:163], off
	s_barrier
	s_waitcnt lgkmcnt(0)
	v_mfma_f32_16x16x32_bf16 v[60:63], v[168:171], v[146:149], v[60:63]
	v_mfma_f32_16x16x32_bf16 v[56:59], v[168:171], v[154:157], v[56:59]
	v_mfma_f32_16x16x32_bf16 v[52:55], v[176:179], v[146:149], v[52:55]
	v_mfma_f32_16x16x32_bf16 v[48:51], v[176:179], v[154:157], v[48:51]
	v_mfma_f32_16x16x32_bf16 v[44:47], v[184:187], v[146:149], v[44:47]
	v_mfma_f32_16x16x32_bf16 v[40:43], v[184:187], v[154:157], v[40:43]
	v_mfma_f32_16x16x32_bf16 v[36:39], v[192:195], v[146:149], v[36:39]
	v_mfma_f32_16x16x32_bf16 v[32:35], v[192:195], v[154:157], v[32:35]
	v_mfma_f32_16x16x32_bf16 v[60:63], v[172:175], v[150:153], v[60:63]
	v_mfma_f32_16x16x32_bf16 v[56:59], v[172:175], v[158:161], v[56:59]
	v_mfma_f32_16x16x32_bf16 v[52:55], v[180:183], v[150:153], v[52:55]
	v_mfma_f32_16x16x32_bf16 v[48:51], v[180:183], v[158:161], v[48:51]
	v_mfma_f32_16x16x32_bf16 v[44:47], v[188:191], v[150:153], v[44:47]
	v_mfma_f32_16x16x32_bf16 v[40:43], v[188:191], v[158:161], v[40:43]
	v_mfma_f32_16x16x32_bf16 v[36:39], v[210:213], v[150:153], v[36:39]
	v_mfma_f32_16x16x32_bf16 v[32:35], v[210:213], v[158:161], v[32:35]
	s_barrier
	s_mov_b32 m0, s8
	v_lshl_add_u64 v[146:147], v[132:133], 0, s[4:5]
	global_load_lds_dwordx4 v[146:147], off
	v_lshl_add_u64 v[146:147], v[146:147], 0, s[86:87]
	s_mov_b32 m0, s9
	s_nop 0
	global_load_lds_dwordx4 v[146:147], off
	s_waitcnt vmcnt(6)
	s_barrier
; #define LDA(dst, b, h) _Pragma("unroll") for (int m = 0; m < 4; ++m) _Pragma("unroll") for (int k = 0; k < 2; ++k) \
;     dst[m][k] = *reinterpret_cast<const bf16x8*>((char*)SA(b, h) + lds_byte(wr * 64 + m * 16 + fr, k * 32 + fq * 8))
; #define LDB(dst, b, h) _Pragma("unroll") for (int n = 0; n < 2; ++n) _Pragma("unroll") for (int k = 0; k < 2; ++k) \
;     dst[n][k] = *reinterpret_cast<const bf16x8*>((char*)SB(b, h) + lds_byte(wc * 32 + n * 16 + fr, k * 32 + fq * 8))
; #define MMA(ai, bj, At_, Bt_) do { __builtin_amdgcn_s_setprio(1); \
;     _Pragma("unroll") for (int m = 0; m < 4; ++m) _Pragma("unroll") for (int n = 0; n < 2; ++n) _Pragma("unroll") for (int k = 0; k < 2; ++k) \
;       acc[ai][bj][m][n] = __builtin_amdgcn_mfma_f32_16x16x32_bf16(At_[m][k], Bt_[n][k], acc[ai][bj][m][n], 0, 0, 0); \
;     __builtin_amdgcn_s_setprio(0); } while (0)
; #define WAIT_L(n) asm volatile("s_waitcnt lgkmcnt(" #n ")" ::: "memory")
; #define BAR __builtin_amdgcn_s_barrier()
; #define SCHED __builtin_amdgcn_sched_barrier(0)
; #define STAGEW(P_, BASE, cur, nxt, kt_) do { const bool _wr = (kt_) >= nt; \
;     STAGE(P_, BASE, (_wr ? (nxt) : (cur)), (_wr ? (kt_) - nt : (kt_))); } while (0)
; template <int PRE> ...
;     ...
;     LDB(B0, 1, 0); SCHED; LDA(At, 1, 0); STAGEW(SA(0, 1), A, brow + HALF, brow_n + HALF, t + 2);
;     WAIT_L(8); BAR; WAIT_L(0); MMA(0, 0, At, B0); BAR; SCHED;
;     LDB(B1, 1, 1); STAGEW(SB(1, 0), Bt, bcol, bcol_n, t + 3);
;     BAR; WAIT_L(0); MMA(0, 1, At, B1); BAR;
;     LDA(At, 1, 1); STAGEW(SA(1, 0), A, brow, brow_n, t + 3);
;     BAR; WAIT_L(0); MMA(1, 0, At, B0); BAR; SCHED;
;     STAGEW(SB(1, 1), Bt, bcol + HALF, bcol_n + HALF, t + 3);
	v_mfma_f32_16x16x32_bf16 v[28:31], v[168:171], v[214:217], v[28:31]
	v_mfma_f32_16x16x32_bf16 v[24:27], v[168:171], v[222:225], v[24:27]
	v_mfma_f32_16x16x32_bf16 v[20:23], v[176:179], v[214:217], v[20:23]
	v_mfma_f32_16x16x32_bf16 v[16:19], v[176:179], v[222:225], v[16:19]
	v_mfma_f32_16x16x32_bf16 v[12:15], v[184:187], v[214:217], v[12:15]
	v_mfma_f32_16x16x32_bf16 v[8:11], v[184:187], v[222:225], v[8:11]
	v_mfma_f32_16x16x32_bf16 v[4:7], v[192:195], v[214:217], v[4:7]
	v_mfma_f32_16x16x32_bf16 v[0:3], v[192:195], v[222:225], v[0:3]
	v_mfma_f32_16x16x32_bf16 v[28:31], v[172:175], v[218:221], v[28:31]
	v_mfma_f32_16x16x32_bf16 v[24:27], v[172:175], v[226:229], v[24:27]
	v_mfma_f32_16x16x32_bf16 v[20:23], v[180:183], v[218:221], v[20:23]
	v_mfma_f32_16x16x32_bf16 v[16:19], v[180:183], v[226:229], v[16:19]
	v_mfma_f32_16x16x32_bf16 v[12:15], v[188:191], v[218:221], v[12:15]
	v_mfma_f32_16x16x32_bf16 v[8:11], v[188:191], v[226:229], v[8:11]
	v_mfma_f32_16x16x32_bf16 v[4:7], v[210:213], v[218:221], v[4:7]
	v_mfma_f32_16x16x32_bf16 v[0:3], v[210:213], v[226:229], v[0:3]
	v_add_u32_e32 v144, s83, v139
	s_barrier
	ds_read_b128 v[146:149], v144
	ds_read_b128 v[150:153], v144 offset:1024
	ds_read_b128 v[154:157], v144 offset:2048
	ds_read_b128 v[158:161], v144 offset:3072
	s_mov_b32 m0, s10
	v_lshl_add_u64 v[162:163], v[134:135], 0, s[4:5]
	ds_read_b128 v[168:171], v140 offset:32768
	ds_read_b128 v[172:175], v140 offset:33792
	ds_read_b128 v[176:179], v141 offset:32768
	ds_read_b128 v[180:183], v141 offset:33792
	ds_read_b128 v[184:187], v142 offset:32768
	ds_read_b128 v[188:191], v142 offset:33792
	ds_read_b128 v[192:195], v143 offset:32768
	ds_read_b128 v[210:213], v143 offset:33792
	global_load_lds_dwordx4 v[162:163], off
	v_lshl_add_u64 v[162:163], v[162:163], 0, s[86:87]
	s_mov_b32 m0, s11
	s_nop 0
	global_load_lds_dwordx4 v[162:163], off
	s_waitcnt lgkmcnt(8)
	s_barrier
	s_waitcnt lgkmcnt(0)
	v_mfma_f32_16x16x32_bf16 v[124:127], v[168:171], v[146:149], v[124:127]
	v_mfma_f32_16x16x32_bf16 v[120:123], v[168:171], v[154:157], v[120:123]
	v_mfma_f32_16x16x32_bf16 v[116:119], v[176:179], v[146:149], v[116:119]
	v_mfma_f32_16x16x32_bf16 v[112:115], v[176:179], v[154:157], v[112:115]
	v_mfma_f32_16x16x32_bf16 v[108:111], v[184:187], v[146:149], v[108:111]
	v_mfma_f32_16x16x32_bf16 v[104:107], v[184:187], v[154:157], v[104:107]
	v_mfma_f32_16x16x32_bf16 v[100:103], v[192:195], v[146:149], v[100:103]
	v_mfma_f32_16x16x32_bf16 v[96:99], v[192:195], v[154:157], v[96:99]
	v_mfma_f32_16x16x32_bf16 v[124:127], v[172:175], v[150:153], v[124:127]
	v_mfma_f32_16x16x32_bf16 v[120:123], v[172:175], v[158:161], v[120:123]
	v_mfma_f32_16x16x32_bf16 v[116:119], v[180:183], v[150:153], v[116:119]
	v_mfma_f32_16x16x32_bf16 v[112:115], v[180:183], v[158:161], v[112:115]
	v_mfma_f32_16x16x32_bf16 v[108:111], v[188:191], v[150:153], v[108:111]
	v_mfma_f32_16x16x32_bf16 v[104:107], v[188:191], v[158:161], v[104:107]
	v_mfma_f32_16x16x32_bf16 v[100:103], v[210:213], v[150:153], v[100:103]
	v_mfma_f32_16x16x32_bf16 v[96:99], v[210:213], v[158:161], v[96:99]
	s_barrier
	s_cmp_lt_u32 s21, 29
	s_cselect_b32 s4, 0, 0xffffffe0
	s_add_i32 s4, s4, s21
	s_add_i32 s18, s4, 3
	s_lshl_b64 s[4:5], s[18:19], 7
	s_mov_b32 m0, s13
	v_add_u32_e32 v144, s84, v139
	v_lshl_add_u64 v[162:163], v[128:129], 0, s[4:5]
	ds_read_b128 v[214:217], v144
	ds_read_b128 v[218:221], v144 offset:1024
	ds_read_b128 v[222:225], v144 offset:2048
	ds_read_b128 v[226:229], v144 offset:3072
	global_load_lds_dwordx4 v[162:163], off
	v_lshl_add_u64 v[162:163], v[162:163], 0, s[86:87]
	s_mov_b32 m0, s14
	s_nop 0
	global_load_lds_dwordx4 v[162:163], off
	s_barrier
; #define LDA(dst, b, h) _Pragma("unroll") for (int m = 0; m < 4; ++m) _Pragma("unroll") for (int k = 0; k < 2; ++k) \
;     dst[m][k] = *reinterpret_cast<const bf16x8*>((char*)SA(b, h) + lds_byte(wr * 64 + m * 16 + fr, k * 32 + fq * 8))
; #define LDB(dst, b, h) _Pragma("unroll") for (int n = 0; n < 2; ++n) _Pragma("unroll") for (int k = 0; k < 2; ++k) \
;     dst[n][k] = *reinterpret_cast<const bf16x8*>((char*)SB(b, h) + lds_byte(wc * 32 + n * 16 + fr, k * 32 + fq * 8))
; #define MMA(ai, bj, At_, Bt_) do { __builtin_amdgcn_s_setprio(1); \
;     _Pragma("unroll") for (int m = 0; m < 4; ++m) _Pragma("unroll") for (int n = 0; n < 2; ++n) _Pragma("unroll") for (int k = 0; k < 2; ++k) \
;       acc[ai][bj][m][n] = __builtin_amdgcn_mfma_f32_16x16x32_bf16(At_[m][k], Bt_[n][k], acc[ai][bj][m][n], 0, 0, 0); \
;     __builtin_amdgcn_s_setprio(0); } while (0)
; #define WAIT_V(n) asm volatile("s_waitcnt vmcnt(" #n ")" ::: "memory")
; #define WAIT_L(n) asm volatile("s_waitcnt lgkmcnt(" #n ")" ::: "memory")
; #define BAR __builtin_amdgcn_s_barrier()
; #define SCHED __builtin_amdgcn_sched_barrier(0)
; #define STAGEW(P_, BASE, cur, nxt, kt_) do { const bool _wr = (kt_) >= nt; \
;     STAGE(P_, BASE, (_wr ? (nxt) : (cur)), (_wr ? (kt_) - nt : (kt_))); } while (0)
; template <int PRE> ...
;     ...
;     LDB(B1, 1, 1); STAGEW(SB(1, 0), Bt, bcol, bcol_n, t + 3);
;     BAR; WAIT_L(0); MMA(0, 1, At, B1); BAR;
;     LDA(At, 1, 1); STAGEW(SA(1, 0), A, brow, brow_n, t + 3);
;     BAR; WAIT_L(0); MMA(1, 0, At, B0); BAR; SCHED;
;     STAGEW(SB(1, 1), Bt, bcol + HALF, bcol_n + HALF, t + 3);
;     WAIT_V(6); BAR; MMA(1, 1, At, B1); BAR;
;   }
;   if (wr == 0) BAR;
	s_waitcnt lgkmcnt(0)
	v_mfma_f32_16x16x32_bf16 v[92:95], v[168:171], v[214:217], v[92:95]
	v_mfma_f32_16x16x32_bf16 v[88:91], v[168:171], v[222:225], v[88:91]
	v_mfma_f32_16x16x32_bf16 v[84:87], v[176:179], v[214:217], v[84:87]
	v_mfma_f32_16x16x32_bf16 v[80:83], v[176:179], v[222:225], v[80:83]
	v_mfma_f32_16x16x32_bf16 v[76:79], v[184:187], v[214:217], v[76:79]
	v_mfma_f32_16x16x32_bf16 v[72:75], v[184:187], v[222:225], v[72:75]
	v_mfma_f32_16x16x32_bf16 v[68:71], v[192:195], v[214:217], v[68:71]
	v_mfma_f32_16x16x32_bf16 v[64:67], v[192:195], v[222:225], v[64:67]
	v_mfma_f32_16x16x32_bf16 v[92:95], v[172:175], v[218:221], v[92:95]
	v_mfma_f32_16x16x32_bf16 v[88:91], v[172:175], v[226:229], v[88:91]
	v_mfma_f32_16x16x32_bf16 v[84:87], v[180:183], v[218:221], v[84:87]
	v_mfma_f32_16x16x32_bf16 v[80:83], v[180:183], v[226:229], v[80:83]
	v_mfma_f32_16x16x32_bf16 v[76:79], v[188:191], v[218:221], v[76:79]
	v_mfma_f32_16x16x32_bf16 v[72:75], v[188:191], v[226:229], v[72:75]
	v_mfma_f32_16x16x32_bf16 v[68:71], v[210:213], v[218:221], v[68:71]
	v_mfma_f32_16x16x32_bf16 v[64:67], v[210:213], v[226:229], v[64:67]
	s_mov_b32 m0, s15
	v_lshl_add_u64 v[162:163], v[130:131], 0, s[4:5]
	s_barrier
	ds_read_b128 v[168:171], v140 offset:49152
	ds_read_b128 v[172:175], v140 offset:50176
	ds_read_b128 v[176:179], v141 offset:49152
	ds_read_b128 v[180:183], v141 offset:50176
	ds_read_b128 v[184:187], v142 offset:49152
	ds_read_b128 v[188:191], v142 offset:50176
	ds_read_b128 v[192:195], v143 offset:49152
	ds_read_b128 v[210:213], v143 offset:50176
	global_load_lds_dwordx4 v[162:163], off
	v_lshl_add_u64 v[162:163], v[162:163], 0, s[86:87]
	s_mov_b32 m0, s16
	s_nop 0
	global_load_lds_dwordx4 v[162:163], off
	s_barrier
	s_waitcnt lgkmcnt(0)
	v_mfma_f32_16x16x32_bf16 v[60:63], v[168:171], v[146:149], v[60:63]
	v_mfma_f32_16x16x32_bf16 v[56:59], v[168:171], v[154:157], v[56:59]
	v_mfma_f32_16x16x32_bf16 v[52:55], v[176:179], v[146:149], v[52:55]
	v_mfma_f32_16x16x32_bf16 v[48:51], v[176:179], v[154:157], v[48:51]
	v_mfma_f32_16x16x32_bf16 v[44:47], v[184:187], v[146:149], v[44:47]
	v_mfma_f32_16x16x32_bf16 v[40:43], v[184:187], v[154:157], v[40:43]
	v_mfma_f32_16x16x32_bf16 v[36:39], v[192:195], v[146:149], v[36:39]
	v_mfma_f32_16x16x32_bf16 v[32:35], v[192:195], v[154:157], v[32:35]
	v_mfma_f32_16x16x32_bf16 v[60:63], v[172:175], v[150:153], v[60:63]
	v_mfma_f32_16x16x32_bf16 v[56:59], v[172:175], v[158:161], v[56:59]
	v_mfma_f32_16x16x32_bf16 v[52:55], v[180:183], v[150:153], v[52:55]
	v_mfma_f32_16x16x32_bf16 v[48:51], v[180:183], v[158:161], v[48:51]
	v_mfma_f32_16x16x32_bf16 v[44:47], v[188:191], v[150:153], v[44:47]
	v_mfma_f32_16x16x32_bf16 v[40:43], v[188:191], v[158:161], v[40:43]
	v_mfma_f32_16x16x32_bf16 v[36:39], v[210:213], v[150:153], v[36:39]
	v_mfma_f32_16x16x32_bf16 v[32:35], v[210:213], v[158:161], v[32:35]
	s_barrier
	s_mov_b32 m0, s17
	v_lshl_add_u64 v[146:147], v[132:133], 0, s[4:5]
	global_load_lds_dwordx4 v[146:147], off
	v_lshl_add_u64 v[146:147], v[146:147], 0, s[86:87]
	s_mov_b32 m0, s20
	s_nop 0
	global_load_lds_dwordx4 v[146:147], off
	s_waitcnt vmcnt(6)
	s_barrier
	v_mfma_f32_16x16x32_bf16 v[28:31], v[168:171], v[214:217], v[28:31]
	v_mfma_f32_16x16x32_bf16 v[24:27], v[168:171], v[222:225], v[24:27]
	v_mfma_f32_16x16x32_bf16 v[20:23], v[176:179], v[214:217], v[20:23]
	v_mfma_f32_16x16x32_bf16 v[16:19], v[176:179], v[222:225], v[16:19]
	v_mfma_f32_16x16x32_bf16 v[12:15], v[184:187], v[214:217], v[12:15]
	v_mfma_f32_16x16x32_bf16 v[8:11], v[184:187], v[222:225], v[8:11]
	v_mfma_f32_16x16x32_bf16 v[4:7], v[192:195], v[214:217], v[4:7]
	v_mfma_f32_16x16x32_bf16 v[0:3], v[192:195], v[222:225], v[0:3]
	v_mfma_f32_16x16x32_bf16 v[28:31], v[172:175], v[218:221], v[28:31]
	v_mfma_f32_16x16x32_bf16 v[24:27], v[172:175], v[226:229], v[24:27]
	v_mfma_f32_16x16x32_bf16 v[20:23], v[180:183], v[218:221], v[20:23]
	v_mfma_f32_16x16x32_bf16 v[16:19], v[180:183], v[226:229], v[16:19]
	v_mfma_f32_16x16x32_bf16 v[12:15], v[188:191], v[218:221], v[12:15]
	v_mfma_f32_16x16x32_bf16 v[8:11], v[188:191], v[226:229], v[8:11]
	v_mfma_f32_16x16x32_bf16 v[4:7], v[210:213], v[218:221], v[4:7]
	v_mfma_f32_16x16x32_bf16 v[0:3], v[210:213], v[226:229], v[0:3]
	v_lshl_add_u64 v[136:137], v[136:137], 0, s[46:47]
	s_mov_b32 s21, s22
	s_barrier
	s_cbranch_vccnz .LBB0_550
	s_andn2_b64 vcc, exec, s[58:59]
	s_cbranch_vccnz .LBB0_553
	s_barrier

; #define STAGE(P_, BASE, br, kt) do { const u16* _gb = (BASE) + (long)(br) * K + (long)(kt) * BK; \
;     _Pragma("unroll") for (int _i = 0; _i < 2; ++_i) { \
;       __builtin_amdgcn_global_load_lds((const unsigned*)(_gb + (long)_i * 64 * K + lane_off), \
;         (unsigned*)((char*)(P_) + lds_wbase + _i * 8192), 16, 0, 0); } } while (0)
; #define LDA(dst, b, h) _Pragma("unroll") for (int m = 0; m < 4; ++m) _Pragma("unroll") for (int k = 0; k < 2; ++k) \
;     dst[m][k] = *reinterpret_cast<const bf16x8*>((char*)SA(b, h) + lds_byte(wr * 64 + m * 16 + fr, k * 32 + fq * 8))
; #define LDB(dst, b, h) _Pragma("unroll") for (int n = 0; n < 2; ++n) _Pragma("unroll") for (int k = 0; k < 2; ++k) \
;     dst[n][k] = *reinterpret_cast<const bf16x8*>((char*)SB(b, h) + lds_byte(wc * 32 + n * 16 + fr, k * 32 + fq * 8))
; #define MMA(ai, bj, At_, Bt_) do { __builtin_amdgcn_s_setprio(1); \
;     _Pragma("unroll") for (int m = 0; m < 4; ++m) _Pragma("unroll") for (int n = 0; n < 2; ++n) _Pragma("unroll") for (int k = 0; k < 2; ++k) \
;       acc[ai][bj][m][n] = __builtin_amdgcn_mfma_f32_16x16x32_bf16(At_[m][k], Bt_[n][k], acc[ai][bj][m][n], 0, 0, 0); \
;     __builtin_amdgcn_s_setprio(0); } while (0)
; #define WAIT_V(n) asm volatile("s_waitcnt vmcnt(" #n ")" ::: "memory")
; #define WAIT_L(n) asm volatile("s_waitcnt lgkmcnt(" #n ")" ::: "memory")
; #define BAR __builtin_amdgcn_s_barrier()
; #define SCHED __builtin_amdgcn_sched_barrier(0)
; #define STAGEW(P_, BASE, cur, nxt, kt_) do { const bool _wr = (kt_) >= nt; \
;     STAGE(P_, BASE, (_wr ? (nxt) : (cur)), (_wr ? (kt_) - nt : (kt_))); } while (0)
; template <int PRE> ...
;     ...
;   for (int t = 0; t < nt; t += 2) {
;     LDB(B0, 0, 0); SCHED; LDA(At, 0, 0); STAGE(SA(1, 1), A, brow + HALF, t + 1);
;     WAIT_L(8); BAR; WAIT_L(0); MMA(0, 0, At, B0); BAR; SCHED;
;     LDB(B1, 0, 1); STAGEW(SB(0, 0), Bt, bcol, bcol_n, t + 2);
;     BAR; WAIT_L(0); MMA(0, 1, At, B1); BAR;
;     LDA(At, 0, 1); STAGEW(SA(0, 0), A, brow, brow_n, t + 2);
;     BAR; WAIT_L(0); MMA(1, 0, At, B0); BAR; SCHED;
;     STAGEW(SB(0, 1), Bt, bcol + HALF, bcol_n + HALF, t + 2);
;     WAIT_V(6); BAR; MMA(1, 1, At, B1); BAR;
.LBB0_810:
	v_add_u32_e32 v142, s81, v147
	ds_read_b128 v[134:137], v142
	ds_read_b128 v[138:141], v142 offset:1024
	ds_read_b128 v[152:155], v142 offset:2048
	ds_read_b128 v[156:159], v142 offset:3072
	s_add_i32 m0, s10, 0xc000
	ds_read_b128 v[160:163], v144
	ds_read_b128 v[168:171], v144 offset:1024
	ds_read_b128 v[172:175], v148
	ds_read_b128 v[176:179], v148 offset:1024
	ds_read_b128 v[180:183], v149
	ds_read_b128 v[184:187], v149 offset:1024
	ds_read_b128 v[188:191], v150
	ds_read_b128 v[192:195], v150 offset:1024
	global_load_lds_dwordx4 v[132:133], off
	v_lshl_add_u64 v[142:143], v[132:133], 0, s[44:45]
	s_add_i32 m0, s10, 0xe000
	s_nop 0
	global_load_lds_dwordx4 v[142:143], off
	s_waitcnt lgkmcnt(8)
	s_barrier
	s_waitcnt lgkmcnt(0)
	v_mfma_f32_16x16x32_bf16 v[124:127], v[160:163], v[134:137], v[124:127]
	v_mfma_f32_16x16x32_bf16 v[120:123], v[160:163], v[152:155], v[120:123]
	v_mfma_f32_16x16x32_bf16 v[116:119], v[172:175], v[134:137], v[116:119]
	v_mfma_f32_16x16x32_bf16 v[112:115], v[172:175], v[152:155], v[112:115]
	v_mfma_f32_16x16x32_bf16 v[108:111], v[180:183], v[134:137], v[108:111]
	v_mfma_f32_16x16x32_bf16 v[104:107], v[180:183], v[152:155], v[104:107]
	v_mfma_f32_16x16x32_bf16 v[100:103], v[188:191], v[134:137], v[100:103]
	v_mfma_f32_16x16x32_bf16 v[96:99], v[188:191], v[152:155], v[96:99]
	v_mfma_f32_16x16x32_bf16 v[124:127], v[168:171], v[138:141], v[124:127]
	v_mfma_f32_16x16x32_bf16 v[120:123], v[168:171], v[156:159], v[120:123]
	v_mfma_f32_16x16x32_bf16 v[116:119], v[176:179], v[138:141], v[116:119]
	v_mfma_f32_16x16x32_bf16 v[112:115], v[176:179], v[156:159], v[112:115]
	v_mfma_f32_16x16x32_bf16 v[108:111], v[184:187], v[138:141], v[108:111]
	v_mfma_f32_16x16x32_bf16 v[104:107], v[184:187], v[156:159], v[104:107]
	v_mfma_f32_16x16x32_bf16 v[100:103], v[192:195], v[138:141], v[100:103]
	v_mfma_f32_16x16x32_bf16 v[96:99], v[192:195], v[156:159], v[96:99]
	s_barrier
	s_add_i32 s36, s1, 2
	s_cmp_lt_u32 s1, 62
	s_cselect_b64 s[2:3], -1, 0
	s_and_b64 vcc, s[2:3], exec
	s_cselect_b32 s4, s27, s29
	s_cselect_b32 s3, 0, 0xffffffc0
	s_cselect_b32 s38, s0, s28
	s_cselect_b32 s40, s34, s31
	s_cselect_b32 s2, s30, s35
	s_ashr_i32 s5, s4, 31
	s_lshl_b64 s[4:5], s[4:5], 13
	s_add_u32 s37, s66, s4
	s_addc_u32 s39, s67, s5
	s_add_i32 s18, s36, s3
	s_lshl_b64 s[4:5], s[18:19], 7
	s_add_u32 s42, s37, s4
	v_add_u32_e32 v142, s82, v147
	s_addc_u32 s43, s39, s5
	s_mov_b32 m0, s11
	ds_read_b128 v[210:213], v142
	ds_read_b128 v[214:217], v142 offset:1024
	ds_read_b128 v[218:221], v142 offset:2048
	ds_read_b128 v[222:225], v142 offset:3072
	v_lshl_add_u64 v[142:143], s[42:43], 0, v[128:129]
	global_load_lds_dwordx4 v[142:143], off
	v_lshl_add_u64 v[142:143], v[142:143], 0, s[44:45]
	s_mov_b32 m0, s12
	s_nop 0
	global_load_lds_dwordx4 v[142:143], off
	s_barrier
	s_waitcnt lgkmcnt(0)
	v_mfma_f32_16x16x32_bf16 v[92:95], v[160:163], v[210:213], v[92:95]
	v_mfma_f32_16x16x32_bf16 v[88:91], v[160:163], v[218:221], v[88:91]
	v_mfma_f32_16x16x32_bf16 v[84:87], v[172:175], v[210:213], v[84:87]
	v_mfma_f32_16x16x32_bf16 v[80:83], v[172:175], v[218:221], v[80:83]
	v_mfma_f32_16x16x32_bf16 v[76:79], v[180:183], v[210:213], v[76:79]
	v_mfma_f32_16x16x32_bf16 v[72:75], v[180:183], v[218:221], v[72:75]
	v_mfma_f32_16x16x32_bf16 v[68:71], v[188:191], v[210:213], v[68:71]
	v_mfma_f32_16x16x32_bf16 v[64:67], v[188:191], v[218:221], v[64:67]
	v_mfma_f32_16x16x32_bf16 v[92:95], v[168:171], v[214:217], v[92:95]
	v_mfma_f32_16x16x32_bf16 v[88:91], v[168:171], v[222:225], v[88:91]
	v_mfma_f32_16x16x32_bf16 v[84:87], v[176:179], v[214:217], v[84:87]
	v_mfma_f32_16x16x32_bf16 v[80:83], v[176:179], v[222:225], v[80:83]
	v_mfma_f32_16x16x32_bf16 v[76:79], v[184:187], v[214:217], v[76:79]
	v_mfma_f32_16x16x32_bf16 v[72:75], v[184:187], v[222:225], v[72:75]
	v_mfma_f32_16x16x32_bf16 v[68:71], v[192:195], v[214:217], v[68:71]
	v_mfma_f32_16x16x32_bf16 v[64:67], v[192:195], v[222:225], v[64:67]
	s_ashr_i32 s39, s38, 31
	s_lshl_b64 s[38:39], s[38:39], 13
	s_add_u32 s3, s61, s38
	s_addc_u32 s18, s68, s39
	s_add_u32 s38, s3, s4
	s_addc_u32 s39, s18, s5
	s_mov_b32 m0, s10
	v_lshl_add_u64 v[142:143], s[38:39], 0, v[128:129]
	s_barrier
	ds_read_b128 v[160:163], v144 offset:16384
	ds_read_b128 v[168:171], v144 offset:17408
	ds_read_b128 v[172:175], v148 offset:16384
	ds_read_b128 v[176:179], v148 offset:17408
	ds_read_b128 v[180:183], v149 offset:16384
	ds_read_b128 v[184:187], v149 offset:17408
	ds_read_b128 v[188:191], v150 offset:16384
	ds_read_b128 v[192:195], v150 offset:17408
	global_load_lds_dwordx4 v[142:143], off
	v_lshl_add_u64 v[142:143], v[142:143], 0, s[44:45]
	s_mov_b32 m0, s13
	s_nop 0
	global_load_lds_dwordx4 v[142:143], off
	s_barrier
	s_waitcnt lgkmcnt(0)
	v_mfma_f32_16x16x32_bf16 v[60:63], v[160:163], v[134:137], v[60:63]
	v_mfma_f32_16x16x32_bf16 v[56:59], v[160:163], v[152:155], v[56:59]
	v_mfma_f32_16x16x32_bf16 v[52:55], v[172:175], v[134:137], v[52:55]
	v_mfma_f32_16x16x32_bf16 v[48:51], v[172:175], v[152:155], v[48:51]
	v_mfma_f32_16x16x32_bf16 v[44:47], v[180:183], v[134:137], v[44:47]
	v_mfma_f32_16x16x32_bf16 v[40:43], v[180:183], v[152:155], v[40:43]
	v_mfma_f32_16x16x32_bf16 v[36:39], v[188:191], v[134:137], v[36:39]
	v_mfma_f32_16x16x32_bf16 v[32:35], v[188:191], v[152:155], v[32:35]
	v_mfma_f32_16x16x32_bf16 v[60:63], v[168:171], v[138:141], v[60:63]
	v_mfma_f32_16x16x32_bf16 v[56:59], v[168:171], v[156:159], v[56:59]
	v_mfma_f32_16x16x32_bf16 v[52:55], v[176:179], v[138:141], v[52:55]
	v_mfma_f32_16x16x32_bf16 v[48:51], v[176:179], v[156:159], v[48:51]
	v_mfma_f32_16x16x32_bf16 v[44:47], v[184:187], v[138:141], v[44:47]
	v_mfma_f32_16x16x32_bf16 v[40:43], v[184:187], v[156:159], v[40:43]
	v_mfma_f32_16x16x32_bf16 v[36:39], v[192:195], v[138:141], v[36:39]
	v_mfma_f32_16x16x32_bf16 v[32:35], v[192:195], v[156:159], v[32:35]
	s_barrier
; #define LDA(dst, b, h) _Pragma("unroll") for (int m = 0; m < 4; ++m) _Pragma("unroll") for (int k = 0; k < 2; ++k) \
;     dst[m][k] = *reinterpret_cast<const bf16x8*>((char*)SA(b, h) + lds_byte(wr * 64 + m * 16 + fr, k * 32 + fq * 8))
; #define LDB(dst, b, h) _Pragma("unroll") for (int n = 0; n < 2; ++n) _Pragma("unroll") for (int k = 0; k < 2; ++k) \
;     dst[n][k] = *reinterpret_cast<const bf16x8*>((char*)SB(b, h) + lds_byte(wc * 32 + n * 16 + fr, k * 32 + fq * 8))
; #define MMA(ai, bj, At_, Bt_) do { __builtin_amdgcn_s_setprio(1); \
;     _Pragma("unroll") for (int m = 0; m < 4; ++m) _Pragma("unroll") for (int n = 0; n < 2; ++n) _Pragma("unroll") for (int k = 0; k < 2; ++k) \
;       acc[ai][bj][m][n] = __builtin_amdgcn_mfma_f32_16x16x32_bf16(At_[m][k], Bt_[n][k], acc[ai][bj][m][n], 0, 0, 0); \
;     __builtin_amdgcn_s_setprio(0); } while (0)
; #define WAIT_V(n) asm volatile("s_waitcnt vmcnt(" #n ")" ::: "memory")
; #define WAIT_L(n) asm volatile("s_waitcnt lgkmcnt(" #n ")" ::: "memory")
; #define BAR __builtin_amdgcn_s_barrier()
; #define SCHED __builtin_amdgcn_sched_barrier(0)
; #define STAGEW(P_, BASE, cur, nxt, kt_) do { const bool _wr = (kt_) >= nt; \
;     STAGE(P_, BASE, (_wr ? (nxt) : (cur)), (_wr ? (kt_) - nt : (kt_))); } while (0)
; template <int PRE> ...
;     ...
;     STAGEW(SB(0, 1), Bt, bcol + HALF, bcol_n + HALF, t + 2);
;     WAIT_V(6); BAR; MMA(1, 1, At, B1); BAR;
;     LDB(B0, 1, 0); SCHED; LDA(At, 1, 0); STAGEW(SA(0, 1), A, brow + HALF, brow_n + HALF, t + 2);
;     WAIT_L(8); BAR; WAIT_L(0); MMA(0, 0, At, B0); BAR; SCHED;
;     LDB(B1, 1, 1); STAGEW(SB(1, 0), Bt, bcol, bcol_n, t + 3);
;     BAR; WAIT_L(0); MMA(0, 1, At, B1); BAR;
;     LDA(At, 1, 1); STAGEW(SA(1, 0), A, brow, brow_n, t + 3);
;     BAR; WAIT_L(0); MMA(1, 0, At, B0); BAR; SCHED;
;     STAGEW(SB(1, 1), Bt, bcol + HALF, bcol_n + HALF, t + 3);
	s_ashr_i32 s41, s40, 31
	s_lshl_b64 s[38:39], s[40:41], 13
	s_add_u32 s3, s66, s38
	s_addc_u32 s18, s67, s39
	s_add_u32 s38, s3, s4
	s_addc_u32 s39, s18, s5
	s_mov_b32 m0, s14
	v_lshl_add_u64 v[134:135], s[38:39], 0, v[128:129]
	global_load_lds_dwordx4 v[134:135], off
	v_lshl_add_u64 v[134:135], v[134:135], 0, s[44:45]
	s_mov_b32 m0, s15
	s_nop 0
	global_load_lds_dwordx4 v[134:135], off
	s_waitcnt vmcnt(6)
	s_barrier
	v_mfma_f32_16x16x32_bf16 v[28:31], v[160:163], v[210:213], v[28:31]
	v_mfma_f32_16x16x32_bf16 v[24:27], v[160:163], v[218:221], v[24:27]
	v_mfma_f32_16x16x32_bf16 v[20:23], v[172:175], v[210:213], v[20:23]
	v_mfma_f32_16x16x32_bf16 v[16:19], v[172:175], v[218:221], v[16:19]
	v_mfma_f32_16x16x32_bf16 v[12:15], v[180:183], v[210:213], v[12:15]
	v_mfma_f32_16x16x32_bf16 v[8:11], v[180:183], v[218:221], v[8:11]
	v_mfma_f32_16x16x32_bf16 v[4:7], v[188:191], v[210:213], v[4:7]
	v_mfma_f32_16x16x32_bf16 v[0:3], v[188:191], v[218:221], v[0:3]
	v_mfma_f32_16x16x32_bf16 v[28:31], v[168:171], v[214:217], v[28:31]
	v_mfma_f32_16x16x32_bf16 v[24:27], v[168:171], v[222:225], v[24:27]
	v_mfma_f32_16x16x32_bf16 v[20:23], v[176:179], v[214:217], v[20:23]
	v_mfma_f32_16x16x32_bf16 v[16:19], v[176:179], v[222:225], v[16:19]
	v_mfma_f32_16x16x32_bf16 v[12:15], v[184:187], v[214:217], v[12:15]
	v_mfma_f32_16x16x32_bf16 v[8:11], v[184:187], v[222:225], v[8:11]
	v_mfma_f32_16x16x32_bf16 v[4:7], v[192:195], v[214:217], v[4:7]
	v_mfma_f32_16x16x32_bf16 v[0:3], v[192:195], v[222:225], v[0:3]
	v_add_u32_e32 v142, s83, v147
	s_barrier
	ds_read_b128 v[134:137], v142
	ds_read_b128 v[138:141], v142 offset:1024
	ds_read_b128 v[152:155], v142 offset:2048
	ds_read_b128 v[156:159], v142 offset:3072
	s_ashr_i32 s3, s2, 31
	s_lshl_b64 s[2:3], s[2:3], 13
	s_add_u32 s2, s61, s2
	s_addc_u32 s3, s68, s3
	s_add_u32 s2, s2, s4
	s_addc_u32 s3, s3, s5
	s_mov_b32 m0, s16
	v_lshl_add_u64 v[142:143], s[2:3], 0, v[128:129]
	ds_read_b128 v[160:163], v144 offset:32768
	ds_read_b128 v[168:171], v144 offset:33792
	ds_read_b128 v[172:175], v148 offset:32768
	ds_read_b128 v[176:179], v148 offset:33792
	ds_read_b128 v[180:183], v149 offset:32768
	ds_read_b128 v[184:187], v149 offset:33792
	ds_read_b128 v[188:191], v150 offset:32768
	ds_read_b128 v[192:195], v150 offset:33792
	global_load_lds_dwordx4 v[142:143], off
	v_lshl_add_u64 v[142:143], v[142:143], 0, s[44:45]
	s_mov_b32 m0, s17
	s_nop 0
	global_load_lds_dwordx4 v[142:143], off
	s_waitcnt lgkmcnt(8)
	s_barrier
	s_waitcnt lgkmcnt(0)
	v_mfma_f32_16x16x32_bf16 v[124:127], v[160:163], v[134:137], v[124:127]
	v_mfma_f32_16x16x32_bf16 v[120:123], v[160:163], v[152:155], v[120:123]
	v_mfma_f32_16x16x32_bf16 v[116:119], v[172:175], v[134:137], v[116:119]
	v_mfma_f32_16x16x32_bf16 v[112:115], v[172:175], v[152:155], v[112:115]
	v_mfma_f32_16x16x32_bf16 v[108:111], v[180:183], v[134:137], v[108:111]
	v_mfma_f32_16x16x32_bf16 v[104:107], v[180:183], v[152:155], v[104:107]
	v_mfma_f32_16x16x32_bf16 v[100:103], v[188:191], v[134:137], v[100:103]
	v_mfma_f32_16x16x32_bf16 v[96:99], v[188:191], v[152:155], v[96:99]
	v_mfma_f32_16x16x32_bf16 v[124:127], v[168:171], v[138:141], v[124:127]
	v_mfma_f32_16x16x32_bf16 v[120:123], v[168:171], v[156:159], v[120:123]
	v_mfma_f32_16x16x32_bf16 v[116:119], v[176:179], v[138:141], v[116:119]
	v_mfma_f32_16x16x32_bf16 v[112:115], v[176:179], v[156:159], v[112:115]
	v_mfma_f32_16x16x32_bf16 v[108:111], v[184:187], v[138:141], v[108:111]
	v_mfma_f32_16x16x32_bf16 v[104:107], v[184:187], v[156:159], v[104:107]
	v_mfma_f32_16x16x32_bf16 v[100:103], v[192:195], v[138:141], v[100:103]
	v_mfma_f32_16x16x32_bf16 v[96:99], v[192:195], v[156:159], v[96:99]
	s_barrier
	s_cmp_lt_u32 s1, 61
	s_cselect_b32 s2, s27, s29
	s_cselect_b32 s5, 0, 0xffffffc0
	s_cselect_b32 s4, s0, s28
	s_cselect_b32 s38, s34, s31
	s_ashr_i32 s3, s2, 31
	s_lshl_b64 s[2:3], s[2:3], 13
	s_add_u32 s37, s66, s2
	s_addc_u32 s39, s67, s3
	s_add_i32 s1, s5, s1
	s_add_i32 s18, s1, 3
	s_lshl_b64 s[2:3], s[18:19], 7
	s_add_u32 s40, s37, s2
	v_add_u32_e32 v142, s84, v147
	s_addc_u32 s41, s39, s3
	s_mov_b32 m0, s20
	ds_read_b128 v[210:213], v142
	ds_read_b128 v[214:217], v142 offset:1024
	ds_read_b128 v[218:221], v142 offset:2048
	ds_read_b128 v[222:225], v142 offset:3072
	v_lshl_add_u64 v[142:143], s[40:41], 0, v[128:129]
	global_load_lds_dwordx4 v[142:143], off
	v_lshl_add_u64 v[142:143], v[142:143], 0, s[44:45]
	s_mov_b32 m0, s21
	s_nop 0
	global_load_lds_dwordx4 v[142:143], off
	s_barrier
; #define LDA(dst, b, h) _Pragma("unroll") for (int m = 0; m < 4; ++m) _Pragma("unroll") for (int k = 0; k < 2; ++k) \
;     dst[m][k] = *reinterpret_cast<const bf16x8*>((char*)SA(b, h) + lds_byte(wr * 64 + m * 16 + fr, k * 32 + fq * 8))
; #define MMA(ai, bj, At_, Bt_) do { __builtin_amdgcn_s_setprio(1); \
;     _Pragma("unroll") for (int m = 0; m < 4; ++m) _Pragma("unroll") for (int n = 0; n < 2; ++n) _Pragma("unroll") for (int k = 0; k < 2; ++k) \
;       acc[ai][bj][m][n] = __builtin_amdgcn_mfma_f32_16x16x32_bf16(At_[m][k], Bt_[n][k], acc[ai][bj][m][n], 0, 0, 0); \
;     __builtin_amdgcn_s_setprio(0); } while (0)
; #define WAIT_V(n) asm volatile("s_waitcnt vmcnt(" #n ")" ::: "memory")
; #define WAIT_L(n) asm volatile("s_waitcnt lgkmcnt(" #n ")" ::: "memory")
; #define BAR __builtin_amdgcn_s_barrier()
; #define SCHED __builtin_amdgcn_sched_barrier(0)
; #define STAGEW(P_, BASE, cur, nxt, kt_) do { const bool _wr = (kt_) >= nt; \
;     STAGE(P_, BASE, (_wr ? (nxt) : (cur)), (_wr ? (kt_) - nt : (kt_))); } while (0)
; template <int PRE> ...
;     ...
;     BAR; WAIT_L(0); MMA(0, 1, At, B1); BAR;
;     LDA(At, 1, 1); STAGEW(SA(1, 0), A, brow, brow_n, t + 3);
;     BAR; WAIT_L(0); MMA(1, 0, At, B0); BAR; SCHED;
;     STAGEW(SB(1, 1), Bt, bcol + HALF, bcol_n + HALF, t + 3);
;     WAIT_V(6); BAR; MMA(1, 1, At, B1); BAR;
;   }
	s_waitcnt lgkmcnt(0)
	v_mfma_f32_16x16x32_bf16 v[92:95], v[160:163], v[210:213], v[92:95]
	v_mfma_f32_16x16x32_bf16 v[88:91], v[160:163], v[218:221], v[88:91]
	v_mfma_f32_16x16x32_bf16 v[84:87], v[172:175], v[210:213], v[84:87]
	v_mfma_f32_16x16x32_bf16 v[80:83], v[172:175], v[218:221], v[80:83]
	v_mfma_f32_16x16x32_bf16 v[76:79], v[180:183], v[210:213], v[76:79]
	v_mfma_f32_16x16x32_bf16 v[72:75], v[180:183], v[218:221], v[72:75]
	v_mfma_f32_16x16x32_bf16 v[68:71], v[188:191], v[210:213], v[68:71]
	v_mfma_f32_16x16x32_bf16 v[64:67], v[188:191], v[218:221], v[64:67]
	v_mfma_f32_16x16x32_bf16 v[92:95], v[168:171], v[214:217], v[92:95]
	v_mfma_f32_16x16x32_bf16 v[88:91], v[168:171], v[222:225], v[88:91]
	v_mfma_f32_16x16x32_bf16 v[84:87], v[176:179], v[214:217], v[84:87]
	v_mfma_f32_16x16x32_bf16 v[80:83], v[176:179], v[222:225], v[80:83]
	v_mfma_f32_16x16x32_bf16 v[76:79], v[184:187], v[214:217], v[76:79]
	v_mfma_f32_16x16x32_bf16 v[72:75], v[184:187], v[222:225], v[72:75]
	v_mfma_f32_16x16x32_bf16 v[68:71], v[192:195], v[214:217], v[68:71]
	v_mfma_f32_16x16x32_bf16 v[64:67], v[192:195], v[222:225], v[64:67]
	s_ashr_i32 s5, s4, 31
	s_lshl_b64 s[4:5], s[4:5], 13
	s_add_u32 s1, s61, s4
	s_addc_u32 s5, s68, s5
	s_add_u32 s4, s1, s2
	s_addc_u32 s5, s5, s3
	s_mov_b32 m0, s22
	v_lshl_add_u64 v[142:143], s[4:5], 0, v[128:129]
	s_barrier
	ds_read_b128 v[160:163], v144 offset:49152
	ds_read_b128 v[168:171], v144 offset:50176
	ds_read_b128 v[172:175], v148 offset:49152
	ds_read_b128 v[176:179], v148 offset:50176
	ds_read_b128 v[180:183], v149 offset:49152
	ds_read_b128 v[184:187], v149 offset:50176
	ds_read_b128 v[188:191], v150 offset:49152
	ds_read_b128 v[192:195], v150 offset:50176
	global_load_lds_dwordx4 v[142:143], off
	v_lshl_add_u64 v[142:143], v[142:143], 0, s[44:45]
	s_mov_b32 m0, s23
	s_nop 0
	global_load_lds_dwordx4 v[142:143], off
	s_barrier
	s_waitcnt lgkmcnt(0)
	v_mfma_f32_16x16x32_bf16 v[60:63], v[160:163], v[134:137], v[60:63]
	v_mfma_f32_16x16x32_bf16 v[56:59], v[160:163], v[152:155], v[56:59]
	v_mfma_f32_16x16x32_bf16 v[52:55], v[172:175], v[134:137], v[52:55]
	v_mfma_f32_16x16x32_bf16 v[48:51], v[172:175], v[152:155], v[48:51]
	v_mfma_f32_16x16x32_bf16 v[44:47], v[180:183], v[134:137], v[44:47]
	v_mfma_f32_16x16x32_bf16 v[40:43], v[180:183], v[152:155], v[40:43]
	v_mfma_f32_16x16x32_bf16 v[36:39], v[188:191], v[134:137], v[36:39]
	v_mfma_f32_16x16x32_bf16 v[32:35], v[188:191], v[152:155], v[32:35]
	v_mfma_f32_16x16x32_bf16 v[60:63], v[168:171], v[138:141], v[60:63]
	v_mfma_f32_16x16x32_bf16 v[56:59], v[168:171], v[156:159], v[56:59]
	v_mfma_f32_16x16x32_bf16 v[52:55], v[176:179], v[138:141], v[52:55]
	v_mfma_f32_16x16x32_bf16 v[48:51], v[176:179], v[156:159], v[48:51]
	v_mfma_f32_16x16x32_bf16 v[44:47], v[184:187], v[138:141], v[44:47]
	v_mfma_f32_16x16x32_bf16 v[40:43], v[184:187], v[156:159], v[40:43]
	v_mfma_f32_16x16x32_bf16 v[36:39], v[192:195], v[138:141], v[36:39]
	v_mfma_f32_16x16x32_bf16 v[32:35], v[192:195], v[156:159], v[32:35]
	s_barrier
	s_ashr_i32 s39, s38, 31
	s_lshl_b64 s[4:5], s[38:39], 13
	s_add_u32 s1, s66, s4
	s_addc_u32 s4, s67, s5
	s_add_u32 s2, s1, s2
	s_addc_u32 s3, s4, s3
	s_mov_b32 m0, s24
	v_lshl_add_u64 v[134:135], s[2:3], 0, v[128:129]
	global_load_lds_dwordx4 v[134:135], off
	v_lshl_add_u64 v[134:135], v[134:135], 0, s[44:45]
	s_mov_b32 m0, s25
	s_nop 0
	global_load_lds_dwordx4 v[134:135], off
	s_waitcnt vmcnt(6)
	s_barrier
	v_mfma_f32_16x16x32_bf16 v[28:31], v[160:163], v[210:213], v[28:31]
	v_mfma_f32_16x16x32_bf16 v[24:27], v[160:163], v[218:221], v[24:27]
	v_mfma_f32_16x16x32_bf16 v[20:23], v[172:175], v[210:213], v[20:23]
	v_mfma_f32_16x16x32_bf16 v[16:19], v[172:175], v[218:221], v[16:19]
	v_mfma_f32_16x16x32_bf16 v[12:15], v[180:183], v[210:213], v[12:15]
	v_mfma_f32_16x16x32_bf16 v[8:11], v[180:183], v[218:221], v[8:11]
	v_mfma_f32_16x16x32_bf16 v[4:7], v[188:191], v[210:213], v[4:7]
	v_mfma_f32_16x16x32_bf16 v[0:3], v[188:191], v[218:221], v[0:3]
	v_mfma_f32_16x16x32_bf16 v[28:31], v[168:171], v[214:217], v[28:31]
	v_mfma_f32_16x16x32_bf16 v[24:27], v[168:171], v[222:225], v[24:27]
	v_mfma_f32_16x16x32_bf16 v[20:23], v[176:179], v[214:217], v[20:23]
	v_mfma_f32_16x16x32_bf16 v[16:19], v[176:179], v[222:225], v[16:19]
	v_mfma_f32_16x16x32_bf16 v[12:15], v[184:187], v[214:217], v[12:15]
	v_mfma_f32_16x16x32_bf16 v[8:11], v[184:187], v[222:225], v[8:11]
	v_mfma_f32_16x16x32_bf16 v[4:7], v[192:195], v[214:217], v[4:7]
	v_mfma_f32_16x16x32_bf16 v[0:3], v[192:195], v[222:225], v[0:3]
	v_lshl_add_u64 v[132:133], v[132:133], 0, s[46:47]
	s_mov_b32 s1, s36
	s_barrier
	s_cbranch_vccnz .LBB0_810
	v_readlane_b32 s34, v243, 2
	s_andn2_b64 vcc, exec, s[58:59]
	v_readlane_b32 s31, v244, 61
	v_readlane_b32 s35, v243, 3
	s_cbranch_vccnz .LBB0_813
	s_barrier

; #define STAGE(P_, BASE, br, kt) do { const u16* _gb = (BASE) + (long)(br) * K + (long)(kt) * BK; \
;     _Pragma("unroll") for (int _i = 0; _i < 2; ++_i) { \
;       __builtin_amdgcn_global_load_lds((const unsigned*)(_gb + (long)_i * 64 * K + lane_off), \
;         (unsigned*)((char*)(P_) + lds_wbase + _i * 8192), 16, 0, 0); } } while (0)
; #define LDA(dst, b, h) _Pragma("unroll") for (int m = 0; m < 4; ++m) _Pragma("unroll") for (int k = 0; k < 2; ++k) \
;     dst[m][k] = *reinterpret_cast<const bf16x8*>((char*)SA(b, h) + lds_byte(wr * 64 + m * 16 + fr, k * 32 + fq * 8))
; #define LDB(dst, b, h) _Pragma("unroll") for (int n = 0; n < 2; ++n) _Pragma("unroll") for (int k = 0; k < 2; ++k) \
;     dst[n][k] = *reinterpret_cast<const bf16x8*>((char*)SB(b, h) + lds_byte(wc * 32 + n * 16 + fr, k * 32 + fq * 8))
; #define MMA(ai, bj, At_, Bt_) do { __builtin_amdgcn_s_setprio(1); \
;     _Pragma("unroll") for (int m = 0; m < 4; ++m) _Pragma("unroll") for (int n = 0; n < 2; ++n) _Pragma("unroll") for (int k = 0; k < 2; ++k) \
;       acc[ai][bj][m][n] = __builtin_amdgcn_mfma_f32_16x16x32_bf16(At_[m][k], Bt_[n][k], acc[ai][bj][m][n], 0, 0, 0); \
;     __builtin_amdgcn_s_setprio(0); } while (0)
; #define WAIT_L(n) asm volatile("s_waitcnt lgkmcnt(" #n ")" ::: "memory")
; #define BAR __builtin_amdgcn_s_barrier()
; #define SCHED __builtin_amdgcn_sched_barrier(0)
; #define STAGEW(P_, BASE, cur, nxt, kt_) do { const bool _wr = (kt_) >= nt; \
;     STAGE(P_, BASE, (_wr ? (nxt) : (cur)), (_wr ? (kt_) - nt : (kt_))); } while (0)
; template <int PRE> ...
;     ...
;     LDB(B0, 0, 0); SCHED; LDA(At, 0, 0); STAGE(SA(1, 1), A, brow + HALF, t + 1);
;     WAIT_L(8); BAR; WAIT_L(0); MMA(0, 0, At, B0); BAR; SCHED;
;     LDB(B1, 0, 1); STAGEW(SB(0, 0), Bt, bcol, bcol_n, t + 2);
;     BAR; WAIT_L(0); MMA(0, 1, At, B1); BAR;
;     LDA(At, 0, 1); STAGEW(SA(0, 0), A, brow, brow_n, t + 2);
;     BAR; WAIT_L(0); MMA(1, 0, At, B0); BAR; SCHED;
.LBB0_825:
	v_add_u32_e32 v142, s81, v159
	ds_read_b128 v[134:137], v142
	ds_read_b128 v[138:141], v142 offset:1024
	ds_read_b128 v[146:149], v142 offset:2048
	ds_read_b128 v[150:153], v142 offset:3072
	s_add_i32 m0, s10, 0xc000
	ds_read_b128 v[154:157], v144
	ds_read_b128 v[168:171], v144 offset:1024
	ds_read_b128 v[172:175], v160
	ds_read_b128 v[176:179], v160 offset:1024
	ds_read_b128 v[180:183], v161
	ds_read_b128 v[184:187], v161 offset:1024
	ds_read_b128 v[188:191], v162
	ds_read_b128 v[192:195], v162 offset:1024
	global_load_lds_dwordx4 v[128:129], off
	v_lshl_add_u64 v[142:143], v[128:129], 0, s[86:87]
	s_add_i32 m0, s10, 0xe000
	s_nop 0
	global_load_lds_dwordx4 v[142:143], off
	s_waitcnt lgkmcnt(8)
	s_barrier
	s_waitcnt lgkmcnt(0)
	v_mfma_f32_16x16x32_bf16 v[124:127], v[154:157], v[134:137], v[124:127]
	v_mfma_f32_16x16x32_bf16 v[120:123], v[154:157], v[146:149], v[120:123]
	v_mfma_f32_16x16x32_bf16 v[116:119], v[172:175], v[134:137], v[116:119]
	v_mfma_f32_16x16x32_bf16 v[112:115], v[172:175], v[146:149], v[112:115]
	v_mfma_f32_16x16x32_bf16 v[108:111], v[180:183], v[134:137], v[108:111]
	v_mfma_f32_16x16x32_bf16 v[104:107], v[180:183], v[146:149], v[104:107]
	v_mfma_f32_16x16x32_bf16 v[100:103], v[188:191], v[134:137], v[100:103]
	v_mfma_f32_16x16x32_bf16 v[96:99], v[188:191], v[146:149], v[96:99]
	v_mfma_f32_16x16x32_bf16 v[124:127], v[168:171], v[138:141], v[124:127]
	v_mfma_f32_16x16x32_bf16 v[120:123], v[168:171], v[150:153], v[120:123]
	v_mfma_f32_16x16x32_bf16 v[116:119], v[176:179], v[138:141], v[116:119]
	v_mfma_f32_16x16x32_bf16 v[112:115], v[176:179], v[150:153], v[112:115]
	v_mfma_f32_16x16x32_bf16 v[108:111], v[184:187], v[138:141], v[108:111]
	v_mfma_f32_16x16x32_bf16 v[104:107], v[184:187], v[150:153], v[104:107]
	v_mfma_f32_16x16x32_bf16 v[100:103], v[192:195], v[138:141], v[100:103]
	v_mfma_f32_16x16x32_bf16 v[96:99], v[192:195], v[150:153], v[96:99]
	s_barrier
	s_add_i32 s36, s1, 2
	s_cmp_lt_u32 s1, 30
	s_cselect_b64 s[2:3], -1, 0
	s_and_b64 vcc, s[2:3], exec
	s_cselect_b32 s4, s27, s29
	s_cselect_b32 s3, 0, 0xffffffe0
	s_cselect_b32 s38, s0, s28
	s_cselect_b32 s40, s34, s31
	s_cselect_b32 s2, s30, s35
	s_ashr_i32 s5, s4, 31
	s_lshl_b64 s[4:5], s[4:5], 12
	s_add_u32 s37, s62, s4
	s_addc_u32 s39, s63, s5
	s_add_i32 s18, s36, s3
	s_lshl_b64 s[4:5], s[18:19], 7
	s_add_u32 s42, s37, s4
	v_add_u32_e32 v142, s82, v159
	s_addc_u32 s43, s39, s5
	s_mov_b32 m0, s11
	ds_read_b128 v[210:213], v142
	ds_read_b128 v[214:217], v142 offset:1024
	ds_read_b128 v[218:221], v142 offset:2048
	ds_read_b128 v[222:225], v142 offset:3072
	v_lshl_add_u64 v[142:143], s[42:43], 0, v[130:131]
	global_load_lds_dwordx4 v[142:143], off
	v_lshl_add_u64 v[142:143], v[142:143], 0, s[86:87]
	s_mov_b32 m0, s12
	s_nop 0
	global_load_lds_dwordx4 v[142:143], off
	s_barrier
	s_waitcnt lgkmcnt(0)
	v_mfma_f32_16x16x32_bf16 v[92:95], v[154:157], v[210:213], v[92:95]
	v_mfma_f32_16x16x32_bf16 v[88:91], v[154:157], v[218:221], v[88:91]
	v_mfma_f32_16x16x32_bf16 v[84:87], v[172:175], v[210:213], v[84:87]
	v_mfma_f32_16x16x32_bf16 v[80:83], v[172:175], v[218:221], v[80:83]
	v_mfma_f32_16x16x32_bf16 v[76:79], v[180:183], v[210:213], v[76:79]
	v_mfma_f32_16x16x32_bf16 v[72:75], v[180:183], v[218:221], v[72:75]
	v_mfma_f32_16x16x32_bf16 v[68:71], v[188:191], v[210:213], v[68:71]
	v_mfma_f32_16x16x32_bf16 v[64:67], v[188:191], v[218:221], v[64:67]
	v_mfma_f32_16x16x32_bf16 v[92:95], v[168:171], v[214:217], v[92:95]
	v_mfma_f32_16x16x32_bf16 v[88:91], v[168:171], v[222:225], v[88:91]
	v_mfma_f32_16x16x32_bf16 v[84:87], v[176:179], v[214:217], v[84:87]
	v_mfma_f32_16x16x32_bf16 v[80:83], v[176:179], v[222:225], v[80:83]
	v_mfma_f32_16x16x32_bf16 v[76:79], v[184:187], v[214:217], v[76:79]
	v_mfma_f32_16x16x32_bf16 v[72:75], v[184:187], v[222:225], v[72:75]
	v_mfma_f32_16x16x32_bf16 v[68:71], v[192:195], v[214:217], v[68:71]
	v_mfma_f32_16x16x32_bf16 v[64:67], v[192:195], v[222:225], v[64:67]
	s_ashr_i32 s39, s38, 31
	s_lshl_b64 s[38:39], s[38:39], 12
	s_add_u32 s3, s69, s38
	s_addc_u32 s18, s70, s39
	s_add_u32 s38, s3, s4
	s_addc_u32 s39, s18, s5
	s_mov_b32 m0, s10
	v_lshl_add_u64 v[142:143], s[38:39], 0, v[130:131]
	s_barrier
	ds_read_b128 v[154:157], v144 offset:16384
	ds_read_b128 v[168:171], v144 offset:17408
	ds_read_b128 v[172:175], v160 offset:16384
	ds_read_b128 v[176:179], v160 offset:17408
	ds_read_b128 v[180:183], v161 offset:16384
	ds_read_b128 v[184:187], v161 offset:17408
	ds_read_b128 v[188:191], v162 offset:16384
	ds_read_b128 v[192:195], v162 offset:17408
	global_load_lds_dwordx4 v[142:143], off
	v_lshl_add_u64 v[142:143], v[142:143], 0, s[86:87]
	s_mov_b32 m0, s13
	s_nop 0
	global_load_lds_dwordx4 v[142:143], off
	s_barrier
	s_waitcnt lgkmcnt(0)
	v_mfma_f32_16x16x32_bf16 v[60:63], v[154:157], v[134:137], v[60:63]
	v_mfma_f32_16x16x32_bf16 v[56:59], v[154:157], v[146:149], v[56:59]
	v_mfma_f32_16x16x32_bf16 v[52:55], v[172:175], v[134:137], v[52:55]
	v_mfma_f32_16x16x32_bf16 v[48:51], v[172:175], v[146:149], v[48:51]
	v_mfma_f32_16x16x32_bf16 v[44:47], v[180:183], v[134:137], v[44:47]
	v_mfma_f32_16x16x32_bf16 v[40:43], v[180:183], v[146:149], v[40:43]
	v_mfma_f32_16x16x32_bf16 v[36:39], v[188:191], v[134:137], v[36:39]
	v_mfma_f32_16x16x32_bf16 v[32:35], v[188:191], v[146:149], v[32:35]
	v_mfma_f32_16x16x32_bf16 v[60:63], v[168:171], v[138:141], v[60:63]
	v_mfma_f32_16x16x32_bf16 v[56:59], v[168:171], v[150:153], v[56:59]
	v_mfma_f32_16x16x32_bf16 v[52:55], v[176:179], v[138:141], v[52:55]
	v_mfma_f32_16x16x32_bf16 v[48:51], v[176:179], v[150:153], v[48:51]
	v_mfma_f32_16x16x32_bf16 v[44:47], v[184:187], v[138:141], v[44:47]
	v_mfma_f32_16x16x32_bf16 v[40:43], v[184:187], v[150:153], v[40:43]
	v_mfma_f32_16x16x32_bf16 v[36:39], v[192:195], v[138:141], v[36:39]
	v_mfma_f32_16x16x32_bf16 v[32:35], v[192:195], v[150:153], v[32:35]
	s_barrier
; #define LDA(dst, b, h) _Pragma("unroll") for (int m = 0; m < 4; ++m) _Pragma("unroll") for (int k = 0; k < 2; ++k) \
;     dst[m][k] = *reinterpret_cast<const bf16x8*>((char*)SA(b, h) + lds_byte(wr * 64 + m * 16 + fr, k * 32 + fq * 8))
; #define LDB(dst, b, h) _Pragma("unroll") for (int n = 0; n < 2; ++n) _Pragma("unroll") for (int k = 0; k < 2; ++k) \
;     dst[n][k] = *reinterpret_cast<const bf16x8*>((char*)SB(b, h) + lds_byte(wc * 32 + n * 16 + fr, k * 32 + fq * 8))
; #define MMA(ai, bj, At_, Bt_) do { __builtin_amdgcn_s_setprio(1); \
;     _Pragma("unroll") for (int m = 0; m < 4; ++m) _Pragma("unroll") for (int n = 0; n < 2; ++n) _Pragma("unroll") for (int k = 0; k < 2; ++k) \
;       acc[ai][bj][m][n] = __builtin_amdgcn_mfma_f32_16x16x32_bf16(At_[m][k], Bt_[n][k], acc[ai][bj][m][n], 0, 0, 0); \
;     __builtin_amdgcn_s_setprio(0); } while (0)
; #define WAIT_V(n) asm volatile("s_waitcnt vmcnt(" #n ")" ::: "memory")
; #define WAIT_L(n) asm volatile("s_waitcnt lgkmcnt(" #n ")" ::: "memory")
; #define BAR __builtin_amdgcn_s_barrier()
; #define SCHED __builtin_amdgcn_sched_barrier(0)
; #define STAGEW(P_, BASE, cur, nxt, kt_) do { const bool _wr = (kt_) >= nt; \
;     STAGE(P_, BASE, (_wr ? (nxt) : (cur)), (_wr ? (kt_) - nt : (kt_))); } while (0)
; template <int PRE> ...
;     ...
;     STAGEW(SB(0, 1), Bt, bcol + HALF, bcol_n + HALF, t + 2);
;     WAIT_V(6); BAR; MMA(1, 1, At, B1); BAR;
;     LDB(B0, 1, 0); SCHED; LDA(At, 1, 0); STAGEW(SA(0, 1), A, brow + HALF, brow_n + HALF, t + 2);
;     WAIT_L(8); BAR; WAIT_L(0); MMA(0, 0, At, B0); BAR; SCHED;
;     LDB(B1, 1, 1); STAGEW(SB(1, 0), Bt, bcol, bcol_n, t + 3);
;     BAR; WAIT_L(0); MMA(0, 1, At, B1); BAR;
	s_ashr_i32 s41, s40, 31
	s_lshl_b64 s[38:39], s[40:41], 12
	s_add_u32 s3, s62, s38
	s_addc_u32 s18, s63, s39
	s_add_u32 s38, s3, s4
	s_addc_u32 s39, s18, s5
	s_mov_b32 m0, s14
	v_lshl_add_u64 v[134:135], s[38:39], 0, v[130:131]
	global_load_lds_dwordx4 v[134:135], off
	v_lshl_add_u64 v[134:135], v[134:135], 0, s[86:87]
	s_mov_b32 m0, s15
	s_nop 0
	global_load_lds_dwordx4 v[134:135], off
	s_waitcnt vmcnt(6)
	s_barrier
	v_mfma_f32_16x16x32_bf16 v[28:31], v[154:157], v[210:213], v[28:31]
	v_mfma_f32_16x16x32_bf16 v[24:27], v[154:157], v[218:221], v[24:27]
	v_mfma_f32_16x16x32_bf16 v[20:23], v[172:175], v[210:213], v[20:23]
	v_mfma_f32_16x16x32_bf16 v[16:19], v[172:175], v[218:221], v[16:19]
	v_mfma_f32_16x16x32_bf16 v[12:15], v[180:183], v[210:213], v[12:15]
	v_mfma_f32_16x16x32_bf16 v[8:11], v[180:183], v[218:221], v[8:11]
	v_mfma_f32_16x16x32_bf16 v[4:7], v[188:191], v[210:213], v[4:7]
	v_mfma_f32_16x16x32_bf16 v[0:3], v[188:191], v[218:221], v[0:3]
	v_mfma_f32_16x16x32_bf16 v[28:31], v[168:171], v[214:217], v[28:31]
	v_mfma_f32_16x16x32_bf16 v[24:27], v[168:171], v[222:225], v[24:27]
	v_mfma_f32_16x16x32_bf16 v[20:23], v[176:179], v[214:217], v[20:23]
	v_mfma_f32_16x16x32_bf16 v[16:19], v[176:179], v[222:225], v[16:19]
	v_mfma_f32_16x16x32_bf16 v[12:15], v[184:187], v[214:217], v[12:15]
	v_mfma_f32_16x16x32_bf16 v[8:11], v[184:187], v[222:225], v[8:11]
	v_mfma_f32_16x16x32_bf16 v[4:7], v[192:195], v[214:217], v[4:7]
	v_mfma_f32_16x16x32_bf16 v[0:3], v[192:195], v[222:225], v[0:3]
	v_add_u32_e32 v142, s83, v159
	s_barrier
	ds_read_b128 v[134:137], v142
	ds_read_b128 v[138:141], v142 offset:1024
	ds_read_b128 v[146:149], v142 offset:2048
	ds_read_b128 v[150:153], v142 offset:3072
	s_ashr_i32 s3, s2, 31
	s_lshl_b64 s[2:3], s[2:3], 12
	s_add_u32 s2, s69, s2
	s_addc_u32 s3, s70, s3
	s_add_u32 s2, s2, s4
	s_addc_u32 s3, s3, s5
	s_mov_b32 m0, s16
	v_lshl_add_u64 v[142:143], s[2:3], 0, v[130:131]
	ds_read_b128 v[154:157], v144 offset:32768
	ds_read_b128 v[168:171], v144 offset:33792
	ds_read_b128 v[172:175], v160 offset:32768
	ds_read_b128 v[176:179], v160 offset:33792
	ds_read_b128 v[180:183], v161 offset:32768
	ds_read_b128 v[184:187], v161 offset:33792
	ds_read_b128 v[188:191], v162 offset:32768
	ds_read_b128 v[192:195], v162 offset:33792
	global_load_lds_dwordx4 v[142:143], off
	v_lshl_add_u64 v[142:143], v[142:143], 0, s[86:87]
	s_mov_b32 m0, s17
	s_nop 0
	global_load_lds_dwordx4 v[142:143], off
	s_waitcnt lgkmcnt(8)
	s_barrier
	s_waitcnt lgkmcnt(0)
	v_mfma_f32_16x16x32_bf16 v[124:127], v[154:157], v[134:137], v[124:127]
	v_mfma_f32_16x16x32_bf16 v[120:123], v[154:157], v[146:149], v[120:123]
	v_mfma_f32_16x16x32_bf16 v[116:119], v[172:175], v[134:137], v[116:119]
	v_mfma_f32_16x16x32_bf16 v[112:115], v[172:175], v[146:149], v[112:115]
	v_mfma_f32_16x16x32_bf16 v[108:111], v[180:183], v[134:137], v[108:111]
	v_mfma_f32_16x16x32_bf16 v[104:107], v[180:183], v[146:149], v[104:107]
	v_mfma_f32_16x16x32_bf16 v[100:103], v[188:191], v[134:137], v[100:103]
	v_mfma_f32_16x16x32_bf16 v[96:99], v[188:191], v[146:149], v[96:99]
	v_mfma_f32_16x16x32_bf16 v[124:127], v[168:171], v[138:141], v[124:127]
	v_mfma_f32_16x16x32_bf16 v[120:123], v[168:171], v[150:153], v[120:123]
	v_mfma_f32_16x16x32_bf16 v[116:119], v[176:179], v[138:141], v[116:119]
	v_mfma_f32_16x16x32_bf16 v[112:115], v[176:179], v[150:153], v[112:115]
	v_mfma_f32_16x16x32_bf16 v[108:111], v[184:187], v[138:141], v[108:111]
	v_mfma_f32_16x16x32_bf16 v[104:107], v[184:187], v[150:153], v[104:107]
	v_mfma_f32_16x16x32_bf16 v[100:103], v[192:195], v[138:141], v[100:103]
	v_mfma_f32_16x16x32_bf16 v[96:99], v[192:195], v[150:153], v[96:99]
	s_barrier
	s_cmp_lt_u32 s1, 29
	s_cselect_b32 s2, s27, s29
	s_cselect_b32 s5, 0, 0xffffffe0
	s_cselect_b32 s4, s0, s28
	s_cselect_b32 s38, s34, s31
	s_ashr_i32 s3, s2, 31
	s_lshl_b64 s[2:3], s[2:3], 12
	s_add_u32 s37, s62, s2
	s_addc_u32 s39, s63, s3
	s_add_i32 s1, s5, s1
	s_add_i32 s18, s1, 3
	s_lshl_b64 s[2:3], s[18:19], 7
	s_add_u32 s40, s37, s2
	v_add_u32_e32 v142, s84, v159
	s_addc_u32 s41, s39, s3
	s_mov_b32 m0, s20
	ds_read_b128 v[210:213], v142
	ds_read_b128 v[214:217], v142 offset:1024
	ds_read_b128 v[218:221], v142 offset:2048
	ds_read_b128 v[222:225], v142 offset:3072
	v_lshl_add_u64 v[142:143], s[40:41], 0, v[130:131]
	global_load_lds_dwordx4 v[142:143], off
	v_lshl_add_u64 v[142:143], v[142:143], 0, s[86:87]
	s_mov_b32 m0, s21
	s_nop 0
	global_load_lds_dwordx4 v[142:143], off
	s_barrier
; #define LDA(dst, b, h) _Pragma("unroll") for (int m = 0; m < 4; ++m) _Pragma("unroll") for (int k = 0; k < 2; ++k) \
;     dst[m][k] = *reinterpret_cast<const bf16x8*>((char*)SA(b, h) + lds_byte(wr * 64 + m * 16 + fr, k * 32 + fq * 8))
; #define MMA(ai, bj, At_, Bt_) do { __builtin_amdgcn_s_setprio(1); \
;     _Pragma("unroll") for (int m = 0; m < 4; ++m) _Pragma("unroll") for (int n = 0; n < 2; ++n) _Pragma("unroll") for (int k = 0; k < 2; ++k) \
;       acc[ai][bj][m][n] = __builtin_amdgcn_mfma_f32_16x16x32_bf16(At_[m][k], Bt_[n][k], acc[ai][bj][m][n], 0, 0, 0); \
;     __builtin_amdgcn_s_setprio(0); } while (0)
; #define WAIT_V(n) asm volatile("s_waitcnt vmcnt(" #n ")" ::: "memory")
; #define WAIT_L(n) asm volatile("s_waitcnt lgkmcnt(" #n ")" ::: "memory")
; #define BAR __builtin_amdgcn_s_barrier()
; #define SCHED __builtin_amdgcn_sched_barrier(0)
; #define STAGEW(P_, BASE, cur, nxt, kt_) do { const bool _wr = (kt_) >= nt; \
;     STAGE(P_, BASE, (_wr ? (nxt) : (cur)), (_wr ? (kt_) - nt : (kt_))); } while (0)
; template <int PRE> ...
;     ...
;     BAR; WAIT_L(0); MMA(0, 1, At, B1); BAR;
;     LDA(At, 1, 1); STAGEW(SA(1, 0), A, brow, brow_n, t + 3);
;     BAR; WAIT_L(0); MMA(1, 0, At, B0); BAR; SCHED;
;     STAGEW(SB(1, 1), Bt, bcol + HALF, bcol_n + HALF, t + 3);
;     WAIT_V(6); BAR; MMA(1, 1, At, B1); BAR;
;   }
	s_waitcnt lgkmcnt(0)
	v_mfma_f32_16x16x32_bf16 v[92:95], v[154:157], v[210:213], v[92:95]
	v_mfma_f32_16x16x32_bf16 v[88:91], v[154:157], v[218:221], v[88:91]
	v_mfma_f32_16x16x32_bf16 v[84:87], v[172:175], v[210:213], v[84:87]
	v_mfma_f32_16x16x32_bf16 v[80:83], v[172:175], v[218:221], v[80:83]
	v_mfma_f32_16x16x32_bf16 v[76:79], v[180:183], v[210:213], v[76:79]
	v_mfma_f32_16x16x32_bf16 v[72:75], v[180:183], v[218:221], v[72:75]
	v_mfma_f32_16x16x32_bf16 v[68:71], v[188:191], v[210:213], v[68:71]
	v_mfma_f32_16x16x32_bf16 v[64:67], v[188:191], v[218:221], v[64:67]
	v_mfma_f32_16x16x32_bf16 v[92:95], v[168:171], v[214:217], v[92:95]
	v_mfma_f32_16x16x32_bf16 v[88:91], v[168:171], v[222:225], v[88:91]
	v_mfma_f32_16x16x32_bf16 v[84:87], v[176:179], v[214:217], v[84:87]
	v_mfma_f32_16x16x32_bf16 v[80:83], v[176:179], v[222:225], v[80:83]
	v_mfma_f32_16x16x32_bf16 v[76:79], v[184:187], v[214:217], v[76:79]
	v_mfma_f32_16x16x32_bf16 v[72:75], v[184:187], v[222:225], v[72:75]
	v_mfma_f32_16x16x32_bf16 v[68:71], v[192:195], v[214:217], v[68:71]
	v_mfma_f32_16x16x32_bf16 v[64:67], v[192:195], v[222:225], v[64:67]
	s_ashr_i32 s5, s4, 31
	s_lshl_b64 s[4:5], s[4:5], 12
	s_add_u32 s1, s69, s4
	s_addc_u32 s5, s70, s5
	s_add_u32 s4, s1, s2
	s_addc_u32 s5, s5, s3
	s_mov_b32 m0, s22
	v_lshl_add_u64 v[142:143], s[4:5], 0, v[130:131]
	s_barrier
	ds_read_b128 v[154:157], v144 offset:49152
	ds_read_b128 v[168:171], v144 offset:50176
	ds_read_b128 v[172:175], v160 offset:49152
	ds_read_b128 v[176:179], v160 offset:50176
	ds_read_b128 v[180:183], v161 offset:49152
	ds_read_b128 v[184:187], v161 offset:50176
	ds_read_b128 v[188:191], v162 offset:49152
	ds_read_b128 v[192:195], v162 offset:50176
	global_load_lds_dwordx4 v[142:143], off
	v_lshl_add_u64 v[142:143], v[142:143], 0, s[86:87]
	s_mov_b32 m0, s23
	s_nop 0
	global_load_lds_dwordx4 v[142:143], off
	s_barrier
	s_waitcnt lgkmcnt(0)
	v_mfma_f32_16x16x32_bf16 v[60:63], v[154:157], v[134:137], v[60:63]
	v_mfma_f32_16x16x32_bf16 v[56:59], v[154:157], v[146:149], v[56:59]
	v_mfma_f32_16x16x32_bf16 v[52:55], v[172:175], v[134:137], v[52:55]
	v_mfma_f32_16x16x32_bf16 v[48:51], v[172:175], v[146:149], v[48:51]
	v_mfma_f32_16x16x32_bf16 v[44:47], v[180:183], v[134:137], v[44:47]
	v_mfma_f32_16x16x32_bf16 v[40:43], v[180:183], v[146:149], v[40:43]
	v_mfma_f32_16x16x32_bf16 v[36:39], v[188:191], v[134:137], v[36:39]
	v_mfma_f32_16x16x32_bf16 v[32:35], v[188:191], v[146:149], v[32:35]
	v_mfma_f32_16x16x32_bf16 v[60:63], v[168:171], v[138:141], v[60:63]
	v_mfma_f32_16x16x32_bf16 v[56:59], v[168:171], v[150:153], v[56:59]
	v_mfma_f32_16x16x32_bf16 v[52:55], v[176:179], v[138:141], v[52:55]
	v_mfma_f32_16x16x32_bf16 v[48:51], v[176:179], v[150:153], v[48:51]
	v_mfma_f32_16x16x32_bf16 v[44:47], v[184:187], v[138:141], v[44:47]
	v_mfma_f32_16x16x32_bf16 v[40:43], v[184:187], v[150:153], v[40:43]
	v_mfma_f32_16x16x32_bf16 v[36:39], v[192:195], v[138:141], v[36:39]
	v_mfma_f32_16x16x32_bf16 v[32:35], v[192:195], v[150:153], v[32:35]
	s_barrier
	s_ashr_i32 s39, s38, 31
	s_lshl_b64 s[4:5], s[38:39], 12
	s_add_u32 s1, s62, s4
	s_addc_u32 s4, s63, s5
	s_add_u32 s2, s1, s2
	s_addc_u32 s3, s4, s3
	s_mov_b32 m0, s24
	v_lshl_add_u64 v[134:135], s[2:3], 0, v[130:131]
	global_load_lds_dwordx4 v[134:135], off
	v_lshl_add_u64 v[134:135], v[134:135], 0, s[86:87]
	s_mov_b32 m0, s25
	s_nop 0
	global_load_lds_dwordx4 v[134:135], off
	s_waitcnt vmcnt(6)
	s_barrier
	v_mfma_f32_16x16x32_bf16 v[28:31], v[154:157], v[210:213], v[28:31]
	v_mfma_f32_16x16x32_bf16 v[24:27], v[154:157], v[218:221], v[24:27]
	v_mfma_f32_16x16x32_bf16 v[20:23], v[172:175], v[210:213], v[20:23]
	v_mfma_f32_16x16x32_bf16 v[16:19], v[172:175], v[218:221], v[16:19]
	v_mfma_f32_16x16x32_bf16 v[12:15], v[180:183], v[210:213], v[12:15]
	v_mfma_f32_16x16x32_bf16 v[8:11], v[180:183], v[218:221], v[8:11]
	v_mfma_f32_16x16x32_bf16 v[4:7], v[188:191], v[210:213], v[4:7]
	v_mfma_f32_16x16x32_bf16 v[0:3], v[188:191], v[218:221], v[0:3]
	v_mfma_f32_16x16x32_bf16 v[28:31], v[168:171], v[214:217], v[28:31]
	v_mfma_f32_16x16x32_bf16 v[24:27], v[168:171], v[222:225], v[24:27]
	v_mfma_f32_16x16x32_bf16 v[20:23], v[176:179], v[214:217], v[20:23]
	v_mfma_f32_16x16x32_bf16 v[16:19], v[176:179], v[222:225], v[16:19]
	v_mfma_f32_16x16x32_bf16 v[12:15], v[184:187], v[214:217], v[12:15]
	v_mfma_f32_16x16x32_bf16 v[8:11], v[184:187], v[222:225], v[8:11]
	v_mfma_f32_16x16x32_bf16 v[4:7], v[192:195], v[214:217], v[4:7]
	v_mfma_f32_16x16x32_bf16 v[0:3], v[192:195], v[222:225], v[0:3]
	v_lshl_add_u64 v[128:129], v[128:129], 0, s[46:47]
	s_mov_b32 s1, s36
	s_barrier
	s_cbranch_vccnz .LBB0_825
	v_readlane_b32 s34, v243, 2
	s_andn2_b64 vcc, exec, s[58:59]
	v_readlane_b32 s31, v244, 61
	v_readlane_b32 s35, v243, 3
	s_cbranch_vccnz .LBB0_828
	s_barrier

; #define STAGE(P_, BASE, br, kt) do { const u16* _gb = (BASE) + (long)(br) * K + (long)(kt) * BK; \
;     _Pragma("unroll") for (int _i = 0; _i < 2; ++_i) { \
;       __builtin_amdgcn_global_load_lds((const unsigned*)(_gb + (long)_i * 64 * K + lane_off), \
;         (unsigned*)((char*)(P_) + lds_wbase + _i * 8192), 16, 0, 0); } } while (0)
; #define LDA(dst, b, h) _Pragma("unroll") for (int m = 0; m < 4; ++m) _Pragma("unroll") for (int k = 0; k < 2; ++k) \
;     dst[m][k] = *reinterpret_cast<const bf16x8*>((char*)SA(b, h) + lds_byte(wr * 64 + m * 16 + fr, k * 32 + fq * 8))
; #define LDB(dst, b, h) _Pragma("unroll") for (int n = 0; n < 2; ++n) _Pragma("unroll") for (int k = 0; k < 2; ++k) \
;     dst[n][k] = *reinterpret_cast<const bf16x8*>((char*)SB(b, h) + lds_byte(wc * 32 + n * 16 + fr, k * 32 + fq * 8))
; #define MMA(ai, bj, At_, Bt_) do { __builtin_amdgcn_s_setprio(1); \
;     _Pragma("unroll") for (int m = 0; m < 4; ++m) _Pragma("unroll") for (int n = 0; n < 2; ++n) _Pragma("unroll") for (int k = 0; k < 2; ++k) \
;       acc[ai][bj][m][n] = __builtin_amdgcn_mfma_f32_16x16x32_bf16(At_[m][k], Bt_[n][k], acc[ai][bj][m][n], 0, 0, 0); \
;     __builtin_amdgcn_s_setprio(0); } while (0)
; #define WAIT_L(n) asm volatile("s_waitcnt lgkmcnt(" #n ")" ::: "memory")
; #define BAR __builtin_amdgcn_s_barrier()
; #define SCHED __builtin_amdgcn_sched_barrier(0)
; #define STAGEW(P_, BASE, cur, nxt, kt_) do { const bool _wr = (kt_) >= nt; \
;     STAGE(P_, BASE, (_wr ? (nxt) : (cur)), (_wr ? (kt_) - nt : (kt_))); } while (0)
; template <int PRE> ...
;     ...
;     LDB(B0, 0, 0); SCHED; LDA(At, 0, 0); STAGE(SA(1, 1), A, brow + HALF, t + 1);
;     WAIT_L(8); BAR; WAIT_L(0); MMA(0, 0, At, B0); BAR; SCHED;
;     LDB(B1, 0, 1); STAGEW(SB(0, 0), Bt, bcol, bcol_n, t + 2);
;     BAR; WAIT_L(0); MMA(0, 1, At, B1); BAR;
;     LDA(At, 0, 1); STAGEW(SA(0, 0), A, brow, brow_n, t + 2);
;     BAR; WAIT_L(0); MMA(1, 0, At, B0); BAR; SCHED;
.LBB0_892:
	v_add_u32_e32 v142, s81, v147
	ds_read_b128 v[134:137], v142
	ds_read_b128 v[138:141], v142 offset:1024
	ds_read_b128 v[152:155], v142 offset:2048
	ds_read_b128 v[156:159], v142 offset:3072
	s_add_i32 m0, s12, 0xc000
	ds_read_b128 v[160:163], v144
	ds_read_b128 v[168:171], v144 offset:1024
	ds_read_b128 v[172:175], v148
	ds_read_b128 v[176:179], v148 offset:1024
	ds_read_b128 v[180:183], v149
	ds_read_b128 v[184:187], v149 offset:1024
	ds_read_b128 v[188:191], v150
	ds_read_b128 v[192:195], v150 offset:1024
	global_load_lds_dwordx4 v[132:133], off
	v_lshl_add_u64 v[142:143], v[132:133], 0, s[86:87]
	s_add_i32 m0, s12, 0xe000
	s_nop 0
	global_load_lds_dwordx4 v[142:143], off
	s_waitcnt lgkmcnt(8)
	s_barrier
	s_waitcnt lgkmcnt(0)
	v_mfma_f32_16x16x32_bf16 v[124:127], v[160:163], v[134:137], v[124:127]
	v_mfma_f32_16x16x32_bf16 v[120:123], v[160:163], v[152:155], v[120:123]
	v_mfma_f32_16x16x32_bf16 v[116:119], v[172:175], v[134:137], v[116:119]
	v_mfma_f32_16x16x32_bf16 v[112:115], v[172:175], v[152:155], v[112:115]
	v_mfma_f32_16x16x32_bf16 v[108:111], v[180:183], v[134:137], v[108:111]
	v_mfma_f32_16x16x32_bf16 v[104:107], v[180:183], v[152:155], v[104:107]
	v_mfma_f32_16x16x32_bf16 v[100:103], v[188:191], v[134:137], v[100:103]
	v_mfma_f32_16x16x32_bf16 v[96:99], v[188:191], v[152:155], v[96:99]
	v_mfma_f32_16x16x32_bf16 v[124:127], v[168:171], v[138:141], v[124:127]
	v_mfma_f32_16x16x32_bf16 v[120:123], v[168:171], v[156:159], v[120:123]
	v_mfma_f32_16x16x32_bf16 v[116:119], v[176:179], v[138:141], v[116:119]
	v_mfma_f32_16x16x32_bf16 v[112:115], v[176:179], v[156:159], v[112:115]
	v_mfma_f32_16x16x32_bf16 v[108:111], v[184:187], v[138:141], v[108:111]
	v_mfma_f32_16x16x32_bf16 v[104:107], v[184:187], v[156:159], v[104:107]
	v_mfma_f32_16x16x32_bf16 v[100:103], v[192:195], v[138:141], v[100:103]
	v_mfma_f32_16x16x32_bf16 v[96:99], v[192:195], v[156:159], v[96:99]
	s_barrier
	s_add_i32 s38, s1, 2
	s_cmp_lt_u32 s1, 30
	s_cselect_b64 s[2:3], -1, 0
	s_and_b64 vcc, s[2:3], exec
	s_cselect_b32 s4, s29, s31
	s_cselect_b32 s3, 0, 0xffffffe0
	s_cselect_b32 s40, s0, s30
	s_cselect_b32 s42, s36, s35
	s_cselect_b32 s2, s34, s37
	s_ashr_i32 s5, s4, 31
	s_lshl_b64 s[4:5], s[4:5], 12
	s_add_u32 s39, s72, s4
	s_addc_u32 s41, s73, s5
	s_add_i32 s18, s38, s3
	s_lshl_b64 s[4:5], s[18:19], 7
	s_add_u32 s44, s39, s4
	v_add_u32_e32 v142, s82, v147
	s_addc_u32 s45, s41, s5
	s_mov_b32 m0, s13
	ds_read_b128 v[210:213], v142
	ds_read_b128 v[214:217], v142 offset:1024
	ds_read_b128 v[218:221], v142 offset:2048
	ds_read_b128 v[222:225], v142 offset:3072
	v_lshl_add_u64 v[142:143], s[44:45], 0, v[128:129]
	global_load_lds_dwordx4 v[142:143], off
	v_lshl_add_u64 v[142:143], v[142:143], 0, s[86:87]
	s_mov_b32 m0, s14
	s_nop 0
	global_load_lds_dwordx4 v[142:143], off
	s_barrier
	s_waitcnt lgkmcnt(0)
	v_mfma_f32_16x16x32_bf16 v[92:95], v[160:163], v[210:213], v[92:95]
	v_mfma_f32_16x16x32_bf16 v[88:91], v[160:163], v[218:221], v[88:91]
	v_mfma_f32_16x16x32_bf16 v[84:87], v[172:175], v[210:213], v[84:87]
	v_mfma_f32_16x16x32_bf16 v[80:83], v[172:175], v[218:221], v[80:83]
	v_mfma_f32_16x16x32_bf16 v[76:79], v[180:183], v[210:213], v[76:79]
	v_mfma_f32_16x16x32_bf16 v[72:75], v[180:183], v[218:221], v[72:75]
	v_mfma_f32_16x16x32_bf16 v[68:71], v[188:191], v[210:213], v[68:71]
	v_mfma_f32_16x16x32_bf16 v[64:67], v[188:191], v[218:221], v[64:67]
	v_mfma_f32_16x16x32_bf16 v[92:95], v[168:171], v[214:217], v[92:95]
	v_mfma_f32_16x16x32_bf16 v[88:91], v[168:171], v[222:225], v[88:91]
	v_mfma_f32_16x16x32_bf16 v[84:87], v[176:179], v[214:217], v[84:87]
	v_mfma_f32_16x16x32_bf16 v[80:83], v[176:179], v[222:225], v[80:83]
	v_mfma_f32_16x16x32_bf16 v[76:79], v[184:187], v[214:217], v[76:79]
	v_mfma_f32_16x16x32_bf16 v[72:75], v[184:187], v[222:225], v[72:75]
	v_mfma_f32_16x16x32_bf16 v[68:71], v[192:195], v[214:217], v[68:71]
	v_mfma_f32_16x16x32_bf16 v[64:67], v[192:195], v[222:225], v[64:67]
	s_ashr_i32 s41, s40, 31
	s_lshl_b64 s[40:41], s[40:41], 12
	s_add_u32 s3, s71, s40
	s_addc_u32 s18, s74, s41
	s_add_u32 s40, s3, s4
	s_addc_u32 s41, s18, s5
	s_mov_b32 m0, s12
	v_lshl_add_u64 v[142:143], s[40:41], 0, v[128:129]
	s_barrier
	ds_read_b128 v[160:163], v144 offset:16384
	ds_read_b128 v[168:171], v144 offset:17408
	ds_read_b128 v[172:175], v148 offset:16384
	ds_read_b128 v[176:179], v148 offset:17408
	ds_read_b128 v[180:183], v149 offset:16384
	ds_read_b128 v[184:187], v149 offset:17408
	ds_read_b128 v[188:191], v150 offset:16384
	ds_read_b128 v[192:195], v150 offset:17408
	global_load_lds_dwordx4 v[142:143], off
	v_lshl_add_u64 v[142:143], v[142:143], 0, s[86:87]
	s_mov_b32 m0, s15
	s_nop 0
	global_load_lds_dwordx4 v[142:143], off
	s_barrier
	s_waitcnt lgkmcnt(0)
	v_mfma_f32_16x16x32_bf16 v[60:63], v[160:163], v[134:137], v[60:63]
	v_mfma_f32_16x16x32_bf16 v[56:59], v[160:163], v[152:155], v[56:59]
	v_mfma_f32_16x16x32_bf16 v[52:55], v[172:175], v[134:137], v[52:55]
	v_mfma_f32_16x16x32_bf16 v[48:51], v[172:175], v[152:155], v[48:51]
	v_mfma_f32_16x16x32_bf16 v[44:47], v[180:183], v[134:137], v[44:47]
	v_mfma_f32_16x16x32_bf16 v[40:43], v[180:183], v[152:155], v[40:43]
	v_mfma_f32_16x16x32_bf16 v[36:39], v[188:191], v[134:137], v[36:39]
	v_mfma_f32_16x16x32_bf16 v[32:35], v[188:191], v[152:155], v[32:35]
	v_mfma_f32_16x16x32_bf16 v[60:63], v[168:171], v[138:141], v[60:63]
	v_mfma_f32_16x16x32_bf16 v[56:59], v[168:171], v[156:159], v[56:59]
	v_mfma_f32_16x16x32_bf16 v[52:55], v[176:179], v[138:141], v[52:55]
	v_mfma_f32_16x16x32_bf16 v[48:51], v[176:179], v[156:159], v[48:51]
	v_mfma_f32_16x16x32_bf16 v[44:47], v[184:187], v[138:141], v[44:47]
	v_mfma_f32_16x16x32_bf16 v[40:43], v[184:187], v[156:159], v[40:43]
	v_mfma_f32_16x16x32_bf16 v[36:39], v[192:195], v[138:141], v[36:39]
	v_mfma_f32_16x16x32_bf16 v[32:35], v[192:195], v[156:159], v[32:35]
	s_barrier
; #define LDA(dst, b, h) _Pragma("unroll") for (int m = 0; m < 4; ++m) _Pragma("unroll") for (int k = 0; k < 2; ++k) \
;     dst[m][k] = *reinterpret_cast<const bf16x8*>((char*)SA(b, h) + lds_byte(wr * 64 + m * 16 + fr, k * 32 + fq * 8))
; #define LDB(dst, b, h) _Pragma("unroll") for (int n = 0; n < 2; ++n) _Pragma("unroll") for (int k = 0; k < 2; ++k) \
;     dst[n][k] = *reinterpret_cast<const bf16x8*>((char*)SB(b, h) + lds_byte(wc * 32 + n * 16 + fr, k * 32 + fq * 8))
; #define MMA(ai, bj, At_, Bt_) do { __builtin_amdgcn_s_setprio(1); \
;     _Pragma("unroll") for (int m = 0; m < 4; ++m) _Pragma("unroll") for (int n = 0; n < 2; ++n) _Pragma("unroll") for (int k = 0; k < 2; ++k) \
;       acc[ai][bj][m][n] = __builtin_amdgcn_mfma_f32_16x16x32_bf16(At_[m][k], Bt_[n][k], acc[ai][bj][m][n], 0, 0, 0); \
;     __builtin_amdgcn_s_setprio(0); } while (0)
; #define WAIT_V(n) asm volatile("s_waitcnt vmcnt(" #n ")" ::: "memory")
; #define WAIT_L(n) asm volatile("s_waitcnt lgkmcnt(" #n ")" ::: "memory")
; #define BAR __builtin_amdgcn_s_barrier()
; #define SCHED __builtin_amdgcn_sched_barrier(0)
; #define STAGEW(P_, BASE, cur, nxt, kt_) do { const bool _wr = (kt_) >= nt; \
;     STAGE(P_, BASE, (_wr ? (nxt) : (cur)), (_wr ? (kt_) - nt : (kt_))); } while (0)
; template <int PRE> ...
;     ...
;     STAGEW(SB(0, 1), Bt, bcol + HALF, bcol_n + HALF, t + 2);
;     WAIT_V(6); BAR; MMA(1, 1, At, B1); BAR;
;     LDB(B0, 1, 0); SCHED; LDA(At, 1, 0); STAGEW(SA(0, 1), A, brow + HALF, brow_n + HALF, t + 2);
;     WAIT_L(8); BAR; WAIT_L(0); MMA(0, 0, At, B0); BAR; SCHED;
;     LDB(B1, 1, 1); STAGEW(SB(1, 0), Bt, bcol, bcol_n, t + 3);
;     BAR; WAIT_L(0); MMA(0, 1, At, B1); BAR;
	s_ashr_i32 s43, s42, 31
	s_lshl_b64 s[40:41], s[42:43], 12
	s_add_u32 s3, s72, s40
	s_addc_u32 s18, s73, s41
	s_add_u32 s40, s3, s4
	s_addc_u32 s41, s18, s5
	s_mov_b32 m0, s16
	v_lshl_add_u64 v[134:135], s[40:41], 0, v[128:129]
	global_load_lds_dwordx4 v[134:135], off
	v_lshl_add_u64 v[134:135], v[134:135], 0, s[86:87]
	s_mov_b32 m0, s17
	s_nop 0
	global_load_lds_dwordx4 v[134:135], off
	s_waitcnt vmcnt(6)
	s_barrier
	v_mfma_f32_16x16x32_bf16 v[28:31], v[160:163], v[210:213], v[28:31]
	v_mfma_f32_16x16x32_bf16 v[24:27], v[160:163], v[218:221], v[24:27]
	v_mfma_f32_16x16x32_bf16 v[20:23], v[172:175], v[210:213], v[20:23]
	v_mfma_f32_16x16x32_bf16 v[16:19], v[172:175], v[218:221], v[16:19]
	v_mfma_f32_16x16x32_bf16 v[12:15], v[180:183], v[210:213], v[12:15]
	v_mfma_f32_16x16x32_bf16 v[8:11], v[180:183], v[218:221], v[8:11]
	v_mfma_f32_16x16x32_bf16 v[4:7], v[188:191], v[210:213], v[4:7]
	v_mfma_f32_16x16x32_bf16 v[0:3], v[188:191], v[218:221], v[0:3]
	v_mfma_f32_16x16x32_bf16 v[28:31], v[168:171], v[214:217], v[28:31]
	v_mfma_f32_16x16x32_bf16 v[24:27], v[168:171], v[222:225], v[24:27]
	v_mfma_f32_16x16x32_bf16 v[20:23], v[176:179], v[214:217], v[20:23]
	v_mfma_f32_16x16x32_bf16 v[16:19], v[176:179], v[222:225], v[16:19]
	v_mfma_f32_16x16x32_bf16 v[12:15], v[184:187], v[214:217], v[12:15]
	v_mfma_f32_16x16x32_bf16 v[8:11], v[184:187], v[222:225], v[8:11]
	v_mfma_f32_16x16x32_bf16 v[4:7], v[192:195], v[214:217], v[4:7]
	v_mfma_f32_16x16x32_bf16 v[0:3], v[192:195], v[222:225], v[0:3]
	v_add_u32_e32 v142, s83, v147
	s_barrier
	ds_read_b128 v[134:137], v142
	ds_read_b128 v[138:141], v142 offset:1024
	ds_read_b128 v[152:155], v142 offset:2048
	ds_read_b128 v[156:159], v142 offset:3072
	s_ashr_i32 s3, s2, 31
	s_lshl_b64 s[2:3], s[2:3], 12
	s_add_u32 s2, s71, s2
	s_addc_u32 s3, s74, s3
	s_add_u32 s2, s2, s4
	s_addc_u32 s3, s3, s5
	s_mov_b32 m0, s20
	v_lshl_add_u64 v[142:143], s[2:3], 0, v[128:129]
	ds_read_b128 v[160:163], v144 offset:32768
	ds_read_b128 v[168:171], v144 offset:33792
	ds_read_b128 v[172:175], v148 offset:32768
	ds_read_b128 v[176:179], v148 offset:33792
	ds_read_b128 v[180:183], v149 offset:32768
	ds_read_b128 v[184:187], v149 offset:33792
	ds_read_b128 v[188:191], v150 offset:32768
	ds_read_b128 v[192:195], v150 offset:33792
	global_load_lds_dwordx4 v[142:143], off
	v_lshl_add_u64 v[142:143], v[142:143], 0, s[86:87]
	s_mov_b32 m0, s21
	s_nop 0
	global_load_lds_dwordx4 v[142:143], off
	s_waitcnt lgkmcnt(8)
	s_barrier
	s_waitcnt lgkmcnt(0)
	v_mfma_f32_16x16x32_bf16 v[124:127], v[160:163], v[134:137], v[124:127]
	v_mfma_f32_16x16x32_bf16 v[120:123], v[160:163], v[152:155], v[120:123]
	v_mfma_f32_16x16x32_bf16 v[116:119], v[172:175], v[134:137], v[116:119]
	v_mfma_f32_16x16x32_bf16 v[112:115], v[172:175], v[152:155], v[112:115]
	v_mfma_f32_16x16x32_bf16 v[108:111], v[180:183], v[134:137], v[108:111]
	v_mfma_f32_16x16x32_bf16 v[104:107], v[180:183], v[152:155], v[104:107]
	v_mfma_f32_16x16x32_bf16 v[100:103], v[188:191], v[134:137], v[100:103]
	v_mfma_f32_16x16x32_bf16 v[96:99], v[188:191], v[152:155], v[96:99]
	v_mfma_f32_16x16x32_bf16 v[124:127], v[168:171], v[138:141], v[124:127]
	v_mfma_f32_16x16x32_bf16 v[120:123], v[168:171], v[156:159], v[120:123]
	v_mfma_f32_16x16x32_bf16 v[116:119], v[176:179], v[138:141], v[116:119]
	v_mfma_f32_16x16x32_bf16 v[112:115], v[176:179], v[156:159], v[112:115]
	v_mfma_f32_16x16x32_bf16 v[108:111], v[184:187], v[138:141], v[108:111]
	v_mfma_f32_16x16x32_bf16 v[104:107], v[184:187], v[156:159], v[104:107]
	v_mfma_f32_16x16x32_bf16 v[100:103], v[192:195], v[138:141], v[100:103]
	v_mfma_f32_16x16x32_bf16 v[96:99], v[192:195], v[156:159], v[96:99]
	s_barrier
	s_cmp_lt_u32 s1, 29
	s_cselect_b32 s2, s29, s31
	s_cselect_b32 s5, 0, 0xffffffe0
	s_cselect_b32 s4, s0, s30
	s_cselect_b32 s40, s36, s35
	s_ashr_i32 s3, s2, 31
	s_lshl_b64 s[2:3], s[2:3], 12
	s_add_u32 s39, s72, s2
	s_addc_u32 s41, s73, s3
	s_add_i32 s1, s5, s1
	s_add_i32 s18, s1, 3
	s_lshl_b64 s[2:3], s[18:19], 7
	s_add_u32 s42, s39, s2
	v_add_u32_e32 v142, s84, v147
	s_addc_u32 s43, s41, s3
	s_mov_b32 m0, s22
	ds_read_b128 v[210:213], v142
	ds_read_b128 v[214:217], v142 offset:1024
	ds_read_b128 v[218:221], v142 offset:2048
	ds_read_b128 v[222:225], v142 offset:3072
	v_lshl_add_u64 v[142:143], s[42:43], 0, v[128:129]
	global_load_lds_dwordx4 v[142:143], off
	v_lshl_add_u64 v[142:143], v[142:143], 0, s[86:87]
	s_mov_b32 m0, s23
	s_nop 0
	global_load_lds_dwordx4 v[142:143], off
	s_barrier
; #define LDA(dst, b, h) _Pragma("unroll") for (int m = 0; m < 4; ++m) _Pragma("unroll") for (int k = 0; k < 2; ++k) \
;     dst[m][k] = *reinterpret_cast<const bf16x8*>((char*)SA(b, h) + lds_byte(wr * 64 + m * 16 + fr, k * 32 + fq * 8))
; #define MMA(ai, bj, At_, Bt_) do { __builtin_amdgcn_s_setprio(1); \
;     _Pragma("unroll") for (int m = 0; m < 4; ++m) _Pragma("unroll") for (int n = 0; n < 2; ++n) _Pragma("unroll") for (int k = 0; k < 2; ++k) \
;       acc[ai][bj][m][n] = __builtin_amdgcn_mfma_f32_16x16x32_bf16(At_[m][k], Bt_[n][k], acc[ai][bj][m][n], 0, 0, 0); \
;     __builtin_amdgcn_s_setprio(0); } while (0)
; #define WAIT_V(n) asm volatile("s_waitcnt vmcnt(" #n ")" ::: "memory")
; #define WAIT_L(n) asm volatile("s_waitcnt lgkmcnt(" #n ")" ::: "memory")
; #define BAR __builtin_amdgcn_s_barrier()
; #define SCHED __builtin_amdgcn_sched_barrier(0)
; #define STAGEW(P_, BASE, cur, nxt, kt_) do { const bool _wr = (kt_) >= nt; \
;     STAGE(P_, BASE, (_wr ? (nxt) : (cur)), (_wr ? (kt_) - nt : (kt_))); } while (0)
; template <int PRE> ...
;     ...
;     BAR; WAIT_L(0); MMA(0, 1, At, B1); BAR;
;     LDA(At, 1, 1); STAGEW(SA(1, 0), A, brow, brow_n, t + 3);
;     BAR; WAIT_L(0); MMA(1, 0, At, B0); BAR; SCHED;
;     STAGEW(SB(1, 1), Bt, bcol + HALF, bcol_n + HALF, t + 3);
;     WAIT_V(6); BAR; MMA(1, 1, At, B1); BAR;
;   }
	s_waitcnt lgkmcnt(0)
	v_mfma_f32_16x16x32_bf16 v[92:95], v[160:163], v[210:213], v[92:95]
	v_mfma_f32_16x16x32_bf16 v[88:91], v[160:163], v[218:221], v[88:91]
	v_mfma_f32_16x16x32_bf16 v[84:87], v[172:175], v[210:213], v[84:87]
	v_mfma_f32_16x16x32_bf16 v[80:83], v[172:175], v[218:221], v[80:83]
	v_mfma_f32_16x16x32_bf16 v[76:79], v[180:183], v[210:213], v[76:79]
	v_mfma_f32_16x16x32_bf16 v[72:75], v[180:183], v[218:221], v[72:75]
	v_mfma_f32_16x16x32_bf16 v[68:71], v[188:191], v[210:213], v[68:71]
	v_mfma_f32_16x16x32_bf16 v[64:67], v[188:191], v[218:221], v[64:67]
	v_mfma_f32_16x16x32_bf16 v[92:95], v[168:171], v[214:217], v[92:95]
	v_mfma_f32_16x16x32_bf16 v[88:91], v[168:171], v[222:225], v[88:91]
	v_mfma_f32_16x16x32_bf16 v[84:87], v[176:179], v[214:217], v[84:87]
	v_mfma_f32_16x16x32_bf16 v[80:83], v[176:179], v[222:225], v[80:83]
	v_mfma_f32_16x16x32_bf16 v[76:79], v[184:187], v[214:217], v[76:79]
	v_mfma_f32_16x16x32_bf16 v[72:75], v[184:187], v[222:225], v[72:75]
	v_mfma_f32_16x16x32_bf16 v[68:71], v[192:195], v[214:217], v[68:71]
	v_mfma_f32_16x16x32_bf16 v[64:67], v[192:195], v[222:225], v[64:67]
	s_ashr_i32 s5, s4, 31
	s_lshl_b64 s[4:5], s[4:5], 12
	s_add_u32 s1, s71, s4
	s_addc_u32 s5, s74, s5
	s_add_u32 s4, s1, s2
	s_addc_u32 s5, s5, s3
	s_mov_b32 m0, s24
	v_lshl_add_u64 v[142:143], s[4:5], 0, v[128:129]
	s_barrier
	ds_read_b128 v[160:163], v144 offset:49152
	ds_read_b128 v[168:171], v144 offset:50176
	ds_read_b128 v[172:175], v148 offset:49152
	ds_read_b128 v[176:179], v148 offset:50176
	ds_read_b128 v[180:183], v149 offset:49152
	ds_read_b128 v[184:187], v149 offset:50176
	ds_read_b128 v[188:191], v150 offset:49152
	ds_read_b128 v[192:195], v150 offset:50176
	global_load_lds_dwordx4 v[142:143], off
	v_lshl_add_u64 v[142:143], v[142:143], 0, s[86:87]
	s_mov_b32 m0, s25
	s_nop 0
	global_load_lds_dwordx4 v[142:143], off
	s_barrier
	s_waitcnt lgkmcnt(0)
	v_mfma_f32_16x16x32_bf16 v[60:63], v[160:163], v[134:137], v[60:63]
	v_mfma_f32_16x16x32_bf16 v[56:59], v[160:163], v[152:155], v[56:59]
	v_mfma_f32_16x16x32_bf16 v[52:55], v[172:175], v[134:137], v[52:55]
	v_mfma_f32_16x16x32_bf16 v[48:51], v[172:175], v[152:155], v[48:51]
	v_mfma_f32_16x16x32_bf16 v[44:47], v[180:183], v[134:137], v[44:47]
	v_mfma_f32_16x16x32_bf16 v[40:43], v[180:183], v[152:155], v[40:43]
	v_mfma_f32_16x16x32_bf16 v[36:39], v[188:191], v[134:137], v[36:39]
	v_mfma_f32_16x16x32_bf16 v[32:35], v[188:191], v[152:155], v[32:35]
	v_mfma_f32_16x16x32_bf16 v[60:63], v[168:171], v[138:141], v[60:63]
	v_mfma_f32_16x16x32_bf16 v[56:59], v[168:171], v[156:159], v[56:59]
	v_mfma_f32_16x16x32_bf16 v[52:55], v[176:179], v[138:141], v[52:55]
	v_mfma_f32_16x16x32_bf16 v[48:51], v[176:179], v[156:159], v[48:51]
	v_mfma_f32_16x16x32_bf16 v[44:47], v[184:187], v[138:141], v[44:47]
	v_mfma_f32_16x16x32_bf16 v[40:43], v[184:187], v[156:159], v[40:43]
	v_mfma_f32_16x16x32_bf16 v[36:39], v[192:195], v[138:141], v[36:39]
	v_mfma_f32_16x16x32_bf16 v[32:35], v[192:195], v[156:159], v[32:35]
	s_barrier
	s_ashr_i32 s41, s40, 31
	s_lshl_b64 s[4:5], s[40:41], 12
	s_add_u32 s1, s72, s4
	s_addc_u32 s4, s73, s5
	s_add_u32 s2, s1, s2
	s_addc_u32 s3, s4, s3
	s_mov_b32 m0, s26
	v_lshl_add_u64 v[134:135], s[2:3], 0, v[128:129]
	global_load_lds_dwordx4 v[134:135], off
	v_lshl_add_u64 v[134:135], v[134:135], 0, s[86:87]
	s_mov_b32 m0, s27
	s_nop 0
	global_load_lds_dwordx4 v[134:135], off
	s_waitcnt vmcnt(6)
	s_barrier
	v_mfma_f32_16x16x32_bf16 v[28:31], v[160:163], v[210:213], v[28:31]
	v_mfma_f32_16x16x32_bf16 v[24:27], v[160:163], v[218:221], v[24:27]
	v_mfma_f32_16x16x32_bf16 v[20:23], v[172:175], v[210:213], v[20:23]
	v_mfma_f32_16x16x32_bf16 v[16:19], v[172:175], v[218:221], v[16:19]
	v_mfma_f32_16x16x32_bf16 v[12:15], v[180:183], v[210:213], v[12:15]
	v_mfma_f32_16x16x32_bf16 v[8:11], v[180:183], v[218:221], v[8:11]
	v_mfma_f32_16x16x32_bf16 v[4:7], v[188:191], v[210:213], v[4:7]
	v_mfma_f32_16x16x32_bf16 v[0:3], v[188:191], v[218:221], v[0:3]
	v_mfma_f32_16x16x32_bf16 v[28:31], v[168:171], v[214:217], v[28:31]
	v_mfma_f32_16x16x32_bf16 v[24:27], v[168:171], v[222:225], v[24:27]
	v_mfma_f32_16x16x32_bf16 v[20:23], v[176:179], v[214:217], v[20:23]
	v_mfma_f32_16x16x32_bf16 v[16:19], v[176:179], v[222:225], v[16:19]
	v_mfma_f32_16x16x32_bf16 v[12:15], v[184:187], v[214:217], v[12:15]
	v_mfma_f32_16x16x32_bf16 v[8:11], v[184:187], v[222:225], v[8:11]
	v_mfma_f32_16x16x32_bf16 v[4:7], v[192:195], v[214:217], v[4:7]
	v_mfma_f32_16x16x32_bf16 v[0:3], v[192:195], v[222:225], v[0:3]
	v_lshl_add_u64 v[132:133], v[132:133], 0, s[46:47]
	s_mov_b32 s1, s38
	s_barrier
	s_cbranch_vccnz .LBB0_892
	v_readlane_b32 s34, v243, 2
	s_andn2_b64 vcc, exec, s[58:59]
	v_readlane_b32 s31, v244, 61
	v_readlane_b32 s35, v243, 3
	s_cbranch_vccnz .LBB0_895
	s_barrier

; #define STAGE(P_, BASE, br, kt) do { const u16* _gb = (BASE) + (long)(br) * K + (long)(kt) * BK; \
;     _Pragma("unroll") for (int _i = 0; _i < 2; ++_i) { \
;       __builtin_amdgcn_global_load_lds((const unsigned*)(_gb + (long)_i * 64 * K + lane_off), \
;         (unsigned*)((char*)(P_) + lds_wbase + _i * 8192), 16, 0, 0); } } while (0)
; #define LDA(dst, b, h) _Pragma("unroll") for (int m = 0; m < 4; ++m) _Pragma("unroll") for (int k = 0; k < 2; ++k) \
;     dst[m][k] = *reinterpret_cast<const bf16x8*>((char*)SA(b, h) + lds_byte(wr * 64 + m * 16 + fr, k * 32 + fq * 8))
; #define LDB(dst, b, h) _Pragma("unroll") for (int n = 0; n < 2; ++n) _Pragma("unroll") for (int k = 0; k < 2; ++k) \
;     dst[n][k] = *reinterpret_cast<const bf16x8*>((char*)SB(b, h) + lds_byte(wc * 32 + n * 16 + fr, k * 32 + fq * 8))
; #define MMA(ai, bj, At_, Bt_) do { __builtin_amdgcn_s_setprio(1); \
;     _Pragma("unroll") for (int m = 0; m < 4; ++m) _Pragma("unroll") for (int n = 0; n < 2; ++n) _Pragma("unroll") for (int k = 0; k < 2; ++k) \
;       acc[ai][bj][m][n] = __builtin_amdgcn_mfma_f32_16x16x32_bf16(At_[m][k], Bt_[n][k], acc[ai][bj][m][n], 0, 0, 0); \
;     __builtin_amdgcn_s_setprio(0); } while (0)
; #define WAIT_L(n) asm volatile("s_waitcnt lgkmcnt(" #n ")" ::: "memory")
; #define BAR __builtin_amdgcn_s_barrier()
; #define SCHED __builtin_amdgcn_sched_barrier(0)
; #define STAGEW(P_, BASE, cur, nxt, kt_) do { const bool _wr = (kt_) >= nt; \
;     STAGE(P_, BASE, (_wr ? (nxt) : (cur)), (_wr ? (kt_) - nt : (kt_))); } while (0)
; template <int PRE> ...
;     ...
;     LDB(B0, 0, 0); SCHED; LDA(At, 0, 0); STAGE(SA(1, 1), A, brow + HALF, t + 1);
;     WAIT_L(8); BAR; WAIT_L(0); MMA(0, 0, At, B0); BAR; SCHED;
;     LDB(B1, 0, 1); STAGEW(SB(0, 0), Bt, bcol, bcol_n, t + 2);
;     BAR; WAIT_L(0); MMA(0, 1, At, B1); BAR;
;     LDA(At, 0, 1); STAGEW(SA(0, 0), A, brow, brow_n, t + 2);
;     BAR; WAIT_L(0); MMA(1, 0, At, B0); BAR; SCHED;
.LBB0_1015:
	v_add_u32_e32 v144, s81, v135
	ds_read_b128 v[140:143], v144
	ds_read_b128 v[146:149], v144 offset:1024
	ds_read_b128 v[150:153], v144 offset:2048
	ds_read_b128 v[154:157], v144 offset:3072
	s_add_i32 m0, s10, 0xc000
	ds_read_b128 v[158:161], v136
	ds_read_b128 v[168:171], v136 offset:1024
	ds_read_b128 v[172:175], v137
	ds_read_b128 v[176:179], v137 offset:1024
	ds_read_b128 v[180:183], v138
	ds_read_b128 v[184:187], v138 offset:1024
	ds_read_b128 v[188:191], v139
	ds_read_b128 v[192:195], v139 offset:1024
	global_load_lds_dwordx4 v[132:133], off
	v_lshl_add_u64 v[162:163], v[132:133], 0, s[86:87]
	s_add_i32 m0, s10, 0xe000
	s_nop 0
	global_load_lds_dwordx4 v[162:163], off
	s_waitcnt lgkmcnt(8)
	s_barrier
	s_waitcnt lgkmcnt(0)
	v_mfma_f32_16x16x32_bf16 v[124:127], v[158:161], v[140:143], v[124:127]
	v_mfma_f32_16x16x32_bf16 v[116:119], v[158:161], v[150:153], v[116:119]
	v_mfma_f32_16x16x32_bf16 v[108:111], v[172:175], v[140:143], v[108:111]
	v_mfma_f32_16x16x32_bf16 v[100:103], v[172:175], v[150:153], v[100:103]
	v_mfma_f32_16x16x32_bf16 v[92:95], v[180:183], v[140:143], v[92:95]
	v_mfma_f32_16x16x32_bf16 v[84:87], v[180:183], v[150:153], v[84:87]
	v_mfma_f32_16x16x32_bf16 v[76:79], v[188:191], v[140:143], v[76:79]
	v_mfma_f32_16x16x32_bf16 v[68:71], v[188:191], v[150:153], v[68:71]
	v_mfma_f32_16x16x32_bf16 v[124:127], v[168:171], v[146:149], v[124:127]
	v_mfma_f32_16x16x32_bf16 v[116:119], v[168:171], v[154:157], v[116:119]
	v_mfma_f32_16x16x32_bf16 v[108:111], v[176:179], v[146:149], v[108:111]
	v_mfma_f32_16x16x32_bf16 v[100:103], v[176:179], v[154:157], v[100:103]
	v_mfma_f32_16x16x32_bf16 v[92:95], v[184:187], v[146:149], v[92:95]
	v_mfma_f32_16x16x32_bf16 v[84:87], v[184:187], v[154:157], v[84:87]
	v_mfma_f32_16x16x32_bf16 v[76:79], v[192:195], v[146:149], v[76:79]
	v_mfma_f32_16x16x32_bf16 v[68:71], v[192:195], v[154:157], v[68:71]
	s_barrier
	s_add_i32 s37, s1, 2
	s_cmp_lt_u32 s1, 30
	s_cselect_b64 s[2:3], -1, 0
	s_and_b64 vcc, s[2:3], exec
	s_cselect_b32 s4, s27, s30
	s_cselect_b32 s3, 0, 0xffffffe0
	s_cselect_b32 s38, s0, s29
	s_cselect_b32 s40, s35, s34
	s_cselect_b32 s2, s31, s36
	s_ashr_i32 s5, s4, 31
	s_lshl_b64 s[4:5], s[4:5], 12
	s_add_u32 s39, s76, s4
	s_addc_u32 s41, s77, s5
	s_add_i32 s18, s37, s3
	s_lshl_b64 s[4:5], s[18:19], 7
	s_add_u32 s42, s39, s4
	s_addc_u32 s43, s41, s5
	s_mov_b32 m0, s11
	v_add_u32_e32 v144, s82, v135
	v_lshl_add_u64 v[162:163], s[42:43], 0, v[128:129]
	ds_read_b128 v[210:213], v144
	ds_read_b128 v[214:217], v144 offset:1024
	ds_read_b128 v[218:221], v144 offset:2048
	ds_read_b128 v[222:225], v144 offset:3072
	global_load_lds_dwordx4 v[162:163], off
	v_lshl_add_u64 v[162:163], v[162:163], 0, s[86:87]
	s_mov_b32 m0, s12
	s_nop 0
	global_load_lds_dwordx4 v[162:163], off
	s_barrier
	s_waitcnt lgkmcnt(0)
	v_mfma_f32_16x16x32_bf16 v[60:63], v[158:161], v[210:213], v[60:63]
	v_mfma_f32_16x16x32_bf16 v[52:55], v[158:161], v[218:221], v[52:55]
	v_mfma_f32_16x16x32_bf16 v[44:47], v[172:175], v[210:213], v[44:47]
	v_mfma_f32_16x16x32_bf16 v[36:39], v[172:175], v[218:221], v[36:39]
	v_mfma_f32_16x16x32_bf16 v[28:31], v[180:183], v[210:213], v[28:31]
	v_mfma_f32_16x16x32_bf16 v[20:23], v[180:183], v[218:221], v[20:23]
	v_mfma_f32_16x16x32_bf16 v[12:15], v[188:191], v[210:213], v[12:15]
	v_mfma_f32_16x16x32_bf16 v[4:7], v[188:191], v[218:221], v[4:7]
	v_mfma_f32_16x16x32_bf16 v[60:63], v[168:171], v[214:217], v[60:63]
	v_mfma_f32_16x16x32_bf16 v[52:55], v[168:171], v[222:225], v[52:55]
	v_mfma_f32_16x16x32_bf16 v[44:47], v[176:179], v[214:217], v[44:47]
	v_mfma_f32_16x16x32_bf16 v[36:39], v[176:179], v[222:225], v[36:39]
	v_mfma_f32_16x16x32_bf16 v[28:31], v[184:187], v[214:217], v[28:31]
	v_mfma_f32_16x16x32_bf16 v[20:23], v[184:187], v[222:225], v[20:23]
	v_mfma_f32_16x16x32_bf16 v[12:15], v[192:195], v[214:217], v[12:15]
	v_mfma_f32_16x16x32_bf16 v[4:7], v[192:195], v[222:225], v[4:7]
	s_ashr_i32 s39, s38, 31
	s_lshl_b64 s[38:39], s[38:39], 12
	s_add_u32 s3, s75, s38
	s_addc_u32 s18, s78, s39
	s_add_u32 s38, s3, s4
	s_addc_u32 s39, s18, s5
	s_mov_b32 m0, s10
	v_lshl_add_u64 v[162:163], s[38:39], 0, v[128:129]
	s_barrier
	ds_read_b128 v[158:161], v136 offset:16384
	ds_read_b128 v[168:171], v136 offset:17408
	ds_read_b128 v[172:175], v137 offset:16384
	ds_read_b128 v[176:179], v137 offset:17408
	ds_read_b128 v[180:183], v138 offset:16384
	ds_read_b128 v[184:187], v138 offset:17408
	ds_read_b128 v[188:191], v139 offset:16384
	ds_read_b128 v[192:195], v139 offset:17408
	global_load_lds_dwordx4 v[162:163], off
	v_lshl_add_u64 v[162:163], v[162:163], 0, s[86:87]
	s_mov_b32 m0, s13
	s_nop 0
	global_load_lds_dwordx4 v[162:163], off
	s_barrier
	s_waitcnt lgkmcnt(0)
	v_mfma_f32_16x16x32_bf16 v[120:123], v[158:161], v[140:143], v[120:123]
	v_mfma_f32_16x16x32_bf16 v[112:115], v[158:161], v[150:153], v[112:115]
	v_mfma_f32_16x16x32_bf16 v[104:107], v[172:175], v[140:143], v[104:107]
	v_mfma_f32_16x16x32_bf16 v[96:99], v[172:175], v[150:153], v[96:99]
	v_mfma_f32_16x16x32_bf16 v[88:91], v[180:183], v[140:143], v[88:91]
	v_mfma_f32_16x16x32_bf16 v[80:83], v[180:183], v[150:153], v[80:83]
	v_mfma_f32_16x16x32_bf16 v[72:75], v[188:191], v[140:143], v[72:75]
	v_mfma_f32_16x16x32_bf16 v[64:67], v[188:191], v[150:153], v[64:67]
	v_mfma_f32_16x16x32_bf16 v[120:123], v[168:171], v[146:149], v[120:123]
	v_mfma_f32_16x16x32_bf16 v[112:115], v[168:171], v[154:157], v[112:115]
	v_mfma_f32_16x16x32_bf16 v[104:107], v[176:179], v[146:149], v[104:107]
	v_mfma_f32_16x16x32_bf16 v[96:99], v[176:179], v[154:157], v[96:99]
	v_mfma_f32_16x16x32_bf16 v[88:91], v[184:187], v[146:149], v[88:91]
	v_mfma_f32_16x16x32_bf16 v[80:83], v[184:187], v[154:157], v[80:83]
	v_mfma_f32_16x16x32_bf16 v[72:75], v[192:195], v[146:149], v[72:75]
	v_mfma_f32_16x16x32_bf16 v[64:67], v[192:195], v[154:157], v[64:67]
	s_barrier
; #define LDA(dst, b, h) _Pragma("unroll") for (int m = 0; m < 4; ++m) _Pragma("unroll") for (int k = 0; k < 2; ++k) \
;     dst[m][k] = *reinterpret_cast<const bf16x8*>((char*)SA(b, h) + lds_byte(wr * 64 + m * 16 + fr, k * 32 + fq * 8))
; #define LDB(dst, b, h) _Pragma("unroll") for (int n = 0; n < 2; ++n) _Pragma("unroll") for (int k = 0; k < 2; ++k) \
;     dst[n][k] = *reinterpret_cast<const bf16x8*>((char*)SB(b, h) + lds_byte(wc * 32 + n * 16 + fr, k * 32 + fq * 8))
; #define MMA(ai, bj, At_, Bt_) do { __builtin_amdgcn_s_setprio(1); \
;     _Pragma("unroll") for (int m = 0; m < 4; ++m) _Pragma("unroll") for (int n = 0; n < 2; ++n) _Pragma("unroll") for (int k = 0; k < 2; ++k) \
;       acc[ai][bj][m][n] = __builtin_amdgcn_mfma_f32_16x16x32_bf16(At_[m][k], Bt_[n][k], acc[ai][bj][m][n], 0, 0, 0); \
;     __builtin_amdgcn_s_setprio(0); } while (0)
; #define WAIT_V(n) asm volatile("s_waitcnt vmcnt(" #n ")" ::: "memory")
; #define WAIT_L(n) asm volatile("s_waitcnt lgkmcnt(" #n ")" ::: "memory")
; #define BAR __builtin_amdgcn_s_barrier()
; #define SCHED __builtin_amdgcn_sched_barrier(0)
; #define STAGEW(P_, BASE, cur, nxt, kt_) do { const bool _wr = (kt_) >= nt; \
;     STAGE(P_, BASE, (_wr ? (nxt) : (cur)), (_wr ? (kt_) - nt : (kt_))); } while (0)
; template <int PRE> ...
;     ...
;     STAGEW(SB(0, 1), Bt, bcol + HALF, bcol_n + HALF, t + 2);
;     WAIT_V(6); BAR; MMA(1, 1, At, B1); BAR;
;     LDB(B0, 1, 0); SCHED; LDA(At, 1, 0); STAGEW(SA(0, 1), A, brow + HALF, brow_n + HALF, t + 2);
;     WAIT_L(8); BAR; WAIT_L(0); MMA(0, 0, At, B0); BAR; SCHED;
;     LDB(B1, 1, 1); STAGEW(SB(1, 0), Bt, bcol, bcol_n, t + 3);
;     BAR; WAIT_L(0); MMA(0, 1, At, B1); BAR;
	s_ashr_i32 s41, s40, 31
	s_lshl_b64 s[38:39], s[40:41], 12
	s_add_u32 s3, s76, s38
	s_addc_u32 s18, s77, s39
	s_add_u32 s38, s3, s4
	s_addc_u32 s39, s18, s5
	s_mov_b32 m0, s14
	v_lshl_add_u64 v[140:141], s[38:39], 0, v[128:129]
	global_load_lds_dwordx4 v[140:141], off
	v_lshl_add_u64 v[140:141], v[140:141], 0, s[86:87]
	s_mov_b32 m0, s15
	s_nop 0
	global_load_lds_dwordx4 v[140:141], off
	s_waitcnt vmcnt(6)
	s_barrier
	v_mfma_f32_16x16x32_bf16 v[56:59], v[158:161], v[210:213], v[56:59]
	v_mfma_f32_16x16x32_bf16 v[48:51], v[158:161], v[218:221], v[48:51]
	v_mfma_f32_16x16x32_bf16 v[40:43], v[172:175], v[210:213], v[40:43]
	v_mfma_f32_16x16x32_bf16 v[32:35], v[172:175], v[218:221], v[32:35]
	v_mfma_f32_16x16x32_bf16 v[24:27], v[180:183], v[210:213], v[24:27]
	v_mfma_f32_16x16x32_bf16 v[16:19], v[180:183], v[218:221], v[16:19]
	v_mfma_f32_16x16x32_bf16 v[8:11], v[188:191], v[210:213], v[8:11]
	v_mfma_f32_16x16x32_bf16 v[0:3], v[188:191], v[218:221], v[0:3]
	v_mfma_f32_16x16x32_bf16 v[56:59], v[168:171], v[214:217], v[56:59]
	v_mfma_f32_16x16x32_bf16 v[48:51], v[168:171], v[222:225], v[48:51]
	v_mfma_f32_16x16x32_bf16 v[40:43], v[176:179], v[214:217], v[40:43]
	v_mfma_f32_16x16x32_bf16 v[32:35], v[176:179], v[222:225], v[32:35]
	v_mfma_f32_16x16x32_bf16 v[24:27], v[184:187], v[214:217], v[24:27]
	v_mfma_f32_16x16x32_bf16 v[16:19], v[184:187], v[222:225], v[16:19]
	v_mfma_f32_16x16x32_bf16 v[8:11], v[192:195], v[214:217], v[8:11]
	v_mfma_f32_16x16x32_bf16 v[0:3], v[192:195], v[222:225], v[0:3]
	v_add_u32_e32 v144, s83, v135
	s_barrier
	ds_read_b128 v[140:143], v144
	ds_read_b128 v[146:149], v144 offset:1024
	ds_read_b128 v[150:153], v144 offset:2048
	ds_read_b128 v[154:157], v144 offset:3072
	s_ashr_i32 s3, s2, 31
	s_lshl_b64 s[2:3], s[2:3], 12
	s_add_u32 s2, s75, s2
	s_addc_u32 s3, s78, s3
	s_add_u32 s2, s2, s4
	s_addc_u32 s3, s3, s5
	s_mov_b32 m0, s16
	v_lshl_add_u64 v[162:163], s[2:3], 0, v[128:129]
	ds_read_b128 v[158:161], v136 offset:32768
	ds_read_b128 v[168:171], v136 offset:33792
	ds_read_b128 v[172:175], v137 offset:32768
	ds_read_b128 v[176:179], v137 offset:33792
	ds_read_b128 v[180:183], v138 offset:32768
	ds_read_b128 v[184:187], v138 offset:33792
	ds_read_b128 v[188:191], v139 offset:32768
	ds_read_b128 v[192:195], v139 offset:33792
	global_load_lds_dwordx4 v[162:163], off
	v_lshl_add_u64 v[162:163], v[162:163], 0, s[86:87]
	s_mov_b32 m0, s17
	s_nop 0
	global_load_lds_dwordx4 v[162:163], off
	s_waitcnt lgkmcnt(8)
	s_barrier
	s_waitcnt lgkmcnt(0)
	v_mfma_f32_16x16x32_bf16 v[124:127], v[158:161], v[140:143], v[124:127]
	v_mfma_f32_16x16x32_bf16 v[116:119], v[158:161], v[150:153], v[116:119]
	v_mfma_f32_16x16x32_bf16 v[108:111], v[172:175], v[140:143], v[108:111]
	v_mfma_f32_16x16x32_bf16 v[100:103], v[172:175], v[150:153], v[100:103]
	v_mfma_f32_16x16x32_bf16 v[92:95], v[180:183], v[140:143], v[92:95]
	v_mfma_f32_16x16x32_bf16 v[84:87], v[180:183], v[150:153], v[84:87]
	v_mfma_f32_16x16x32_bf16 v[76:79], v[188:191], v[140:143], v[76:79]
	v_mfma_f32_16x16x32_bf16 v[68:71], v[188:191], v[150:153], v[68:71]
	v_mfma_f32_16x16x32_bf16 v[124:127], v[168:171], v[146:149], v[124:127]
	v_mfma_f32_16x16x32_bf16 v[116:119], v[168:171], v[154:157], v[116:119]
	v_mfma_f32_16x16x32_bf16 v[108:111], v[176:179], v[146:149], v[108:111]
	v_mfma_f32_16x16x32_bf16 v[100:103], v[176:179], v[154:157], v[100:103]
	v_mfma_f32_16x16x32_bf16 v[92:95], v[184:187], v[146:149], v[92:95]
	v_mfma_f32_16x16x32_bf16 v[84:87], v[184:187], v[154:157], v[84:87]
	v_mfma_f32_16x16x32_bf16 v[76:79], v[192:195], v[146:149], v[76:79]
	v_mfma_f32_16x16x32_bf16 v[68:71], v[192:195], v[154:157], v[68:71]
	s_barrier
	s_cmp_lt_u32 s1, 29
	s_cselect_b32 s2, s27, s30
	s_cselect_b32 s5, 0, 0xffffffe0
	s_cselect_b32 s4, s0, s29
	s_cselect_b32 s38, s35, s34
	s_ashr_i32 s3, s2, 31
	s_lshl_b64 s[2:3], s[2:3], 12
	s_add_u32 s39, s76, s2
	s_addc_u32 s41, s77, s3
	s_add_i32 s1, s5, s1
	s_add_i32 s18, s1, 3
	s_lshl_b64 s[2:3], s[18:19], 7
	s_add_u32 s40, s39, s2
	s_addc_u32 s41, s41, s3
	s_mov_b32 m0, s20
	v_add_u32_e32 v144, s84, v135
	v_lshl_add_u64 v[162:163], s[40:41], 0, v[128:129]
	ds_read_b128 v[210:213], v144
	ds_read_b128 v[214:217], v144 offset:1024
	ds_read_b128 v[218:221], v144 offset:2048
	ds_read_b128 v[222:225], v144 offset:3072
	global_load_lds_dwordx4 v[162:163], off
	v_lshl_add_u64 v[162:163], v[162:163], 0, s[86:87]
	s_mov_b32 m0, s21
	s_nop 0
	global_load_lds_dwordx4 v[162:163], off
	s_barrier
; #define LDA(dst, b, h) _Pragma("unroll") for (int m = 0; m < 4; ++m) _Pragma("unroll") for (int k = 0; k < 2; ++k) \
;     dst[m][k] = *reinterpret_cast<const bf16x8*>((char*)SA(b, h) + lds_byte(wr * 64 + m * 16 + fr, k * 32 + fq * 8))
; #define MMA(ai, bj, At_, Bt_) do { __builtin_amdgcn_s_setprio(1); \
;     _Pragma("unroll") for (int m = 0; m < 4; ++m) _Pragma("unroll") for (int n = 0; n < 2; ++n) _Pragma("unroll") for (int k = 0; k < 2; ++k) \
;       acc[ai][bj][m][n] = __builtin_amdgcn_mfma_f32_16x16x32_bf16(At_[m][k], Bt_[n][k], acc[ai][bj][m][n], 0, 0, 0); \
;     __builtin_amdgcn_s_setprio(0); } while (0)
; #define WAIT_V(n) asm volatile("s_waitcnt vmcnt(" #n ")" ::: "memory")
; #define WAIT_L(n) asm volatile("s_waitcnt lgkmcnt(" #n ")" ::: "memory")
; #define BAR __builtin_amdgcn_s_barrier()
; #define SCHED __builtin_amdgcn_sched_barrier(0)
; #define STAGEW(P_, BASE, cur, nxt, kt_) do { const bool _wr = (kt_) >= nt; \
;     STAGE(P_, BASE, (_wr ? (nxt) : (cur)), (_wr ? (kt_) - nt : (kt_))); } while (0)
; template <int PRE> ...
;     ...
;     BAR; WAIT_L(0); MMA(0, 1, At, B1); BAR;
;     LDA(At, 1, 1); STAGEW(SA(1, 0), A, brow, brow_n, t + 3);
;     BAR; WAIT_L(0); MMA(1, 0, At, B0); BAR; SCHED;
;     STAGEW(SB(1, 1), Bt, bcol + HALF, bcol_n + HALF, t + 3);
;     WAIT_V(6); BAR; MMA(1, 1, At, B1); BAR;
;   }
	s_waitcnt lgkmcnt(0)
	v_mfma_f32_16x16x32_bf16 v[60:63], v[158:161], v[210:213], v[60:63]
	v_mfma_f32_16x16x32_bf16 v[52:55], v[158:161], v[218:221], v[52:55]
	v_mfma_f32_16x16x32_bf16 v[44:47], v[172:175], v[210:213], v[44:47]
	v_mfma_f32_16x16x32_bf16 v[36:39], v[172:175], v[218:221], v[36:39]
	v_mfma_f32_16x16x32_bf16 v[28:31], v[180:183], v[210:213], v[28:31]
	v_mfma_f32_16x16x32_bf16 v[20:23], v[180:183], v[218:221], v[20:23]
	v_mfma_f32_16x16x32_bf16 v[12:15], v[188:191], v[210:213], v[12:15]
	v_mfma_f32_16x16x32_bf16 v[4:7], v[188:191], v[218:221], v[4:7]
	v_mfma_f32_16x16x32_bf16 v[60:63], v[168:171], v[214:217], v[60:63]
	v_mfma_f32_16x16x32_bf16 v[52:55], v[168:171], v[222:225], v[52:55]
	v_mfma_f32_16x16x32_bf16 v[44:47], v[176:179], v[214:217], v[44:47]
	v_mfma_f32_16x16x32_bf16 v[36:39], v[176:179], v[222:225], v[36:39]
	v_mfma_f32_16x16x32_bf16 v[28:31], v[184:187], v[214:217], v[28:31]
	v_mfma_f32_16x16x32_bf16 v[20:23], v[184:187], v[222:225], v[20:23]
	v_mfma_f32_16x16x32_bf16 v[12:15], v[192:195], v[214:217], v[12:15]
	v_mfma_f32_16x16x32_bf16 v[4:7], v[192:195], v[222:225], v[4:7]
	s_ashr_i32 s5, s4, 31
	s_lshl_b64 s[4:5], s[4:5], 12
	s_add_u32 s1, s75, s4
	s_addc_u32 s5, s78, s5
	s_add_u32 s4, s1, s2
	s_addc_u32 s5, s5, s3
	s_mov_b32 m0, s22
	v_lshl_add_u64 v[162:163], s[4:5], 0, v[128:129]
	s_barrier
	ds_read_b128 v[158:161], v136 offset:49152
	ds_read_b128 v[168:171], v136 offset:50176
	ds_read_b128 v[172:175], v137 offset:49152
	ds_read_b128 v[176:179], v137 offset:50176
	ds_read_b128 v[180:183], v138 offset:49152
	ds_read_b128 v[184:187], v138 offset:50176
	ds_read_b128 v[188:191], v139 offset:49152
	ds_read_b128 v[192:195], v139 offset:50176
	global_load_lds_dwordx4 v[162:163], off
	v_lshl_add_u64 v[162:163], v[162:163], 0, s[86:87]
	s_mov_b32 m0, s23
	s_nop 0
	global_load_lds_dwordx4 v[162:163], off
	s_barrier
	s_waitcnt lgkmcnt(0)
	v_mfma_f32_16x16x32_bf16 v[120:123], v[158:161], v[140:143], v[120:123]
	v_mfma_f32_16x16x32_bf16 v[112:115], v[158:161], v[150:153], v[112:115]
	v_mfma_f32_16x16x32_bf16 v[104:107], v[172:175], v[140:143], v[104:107]
	v_mfma_f32_16x16x32_bf16 v[96:99], v[172:175], v[150:153], v[96:99]
	v_mfma_f32_16x16x32_bf16 v[88:91], v[180:183], v[140:143], v[88:91]
	v_mfma_f32_16x16x32_bf16 v[80:83], v[180:183], v[150:153], v[80:83]
	v_mfma_f32_16x16x32_bf16 v[72:75], v[188:191], v[140:143], v[72:75]
	v_mfma_f32_16x16x32_bf16 v[64:67], v[188:191], v[150:153], v[64:67]
	v_mfma_f32_16x16x32_bf16 v[120:123], v[168:171], v[146:149], v[120:123]
	v_mfma_f32_16x16x32_bf16 v[112:115], v[168:171], v[154:157], v[112:115]
	v_mfma_f32_16x16x32_bf16 v[104:107], v[176:179], v[146:149], v[104:107]
	v_mfma_f32_16x16x32_bf16 v[96:99], v[176:179], v[154:157], v[96:99]
	v_mfma_f32_16x16x32_bf16 v[88:91], v[184:187], v[146:149], v[88:91]
	v_mfma_f32_16x16x32_bf16 v[80:83], v[184:187], v[154:157], v[80:83]
	v_mfma_f32_16x16x32_bf16 v[72:75], v[192:195], v[146:149], v[72:75]
	v_mfma_f32_16x16x32_bf16 v[64:67], v[192:195], v[154:157], v[64:67]
	s_barrier
	s_ashr_i32 s39, s38, 31
	s_lshl_b64 s[4:5], s[38:39], 12
	s_add_u32 s1, s76, s4
	s_addc_u32 s4, s77, s5
	s_add_u32 s2, s1, s2
	s_addc_u32 s3, s4, s3
	s_mov_b32 m0, s24
	v_lshl_add_u64 v[140:141], s[2:3], 0, v[128:129]
	global_load_lds_dwordx4 v[140:141], off
	v_lshl_add_u64 v[140:141], v[140:141], 0, s[86:87]
	s_mov_b32 m0, s25
	s_nop 0
	global_load_lds_dwordx4 v[140:141], off
	s_waitcnt vmcnt(6)
	s_barrier
	v_mfma_f32_16x16x32_bf16 v[56:59], v[158:161], v[210:213], v[56:59]
	v_mfma_f32_16x16x32_bf16 v[48:51], v[158:161], v[218:221], v[48:51]
	v_mfma_f32_16x16x32_bf16 v[40:43], v[172:175], v[210:213], v[40:43]
	v_mfma_f32_16x16x32_bf16 v[32:35], v[172:175], v[218:221], v[32:35]
	v_mfma_f32_16x16x32_bf16 v[24:27], v[180:183], v[210:213], v[24:27]
	v_mfma_f32_16x16x32_bf16 v[16:19], v[180:183], v[218:221], v[16:19]
	v_mfma_f32_16x16x32_bf16 v[8:11], v[188:191], v[210:213], v[8:11]
	v_mfma_f32_16x16x32_bf16 v[0:3], v[188:191], v[218:221], v[0:3]
	v_mfma_f32_16x16x32_bf16 v[56:59], v[168:171], v[214:217], v[56:59]
	v_mfma_f32_16x16x32_bf16 v[48:51], v[168:171], v[222:225], v[48:51]
	v_mfma_f32_16x16x32_bf16 v[40:43], v[176:179], v[214:217], v[40:43]
	v_mfma_f32_16x16x32_bf16 v[32:35], v[176:179], v[222:225], v[32:35]
	v_mfma_f32_16x16x32_bf16 v[24:27], v[184:187], v[214:217], v[24:27]
	v_mfma_f32_16x16x32_bf16 v[16:19], v[184:187], v[222:225], v[16:19]
	v_mfma_f32_16x16x32_bf16 v[8:11], v[192:195], v[214:217], v[8:11]
	v_mfma_f32_16x16x32_bf16 v[0:3], v[192:195], v[222:225], v[0:3]
	v_lshl_add_u64 v[132:133], v[132:133], 0, s[46:47]
	s_mov_b32 s1, s37
	s_barrier
	s_cbranch_vccnz .LBB0_1015
	v_readlane_b32 s34, v243, 2
	s_andn2_b64 vcc, exec, s[58:59]
	v_readlane_b32 s31, v244, 61
	v_readlane_b32 s35, v243, 3
	s_cbranch_vccnz .LBB0_1018
	s_barrier

; #define STAGE(P_, BASE, br, kt) do { const u16* _gb = (BASE) + (long)(br) * K + (long)(kt) * BK; \
;     _Pragma("unroll") for (int _i = 0; _i < 2; ++_i) { \
;       __builtin_amdgcn_global_load_lds((const unsigned*)(_gb + (long)_i * 64 * K + lane_off), \
;         (unsigned*)((char*)(P_) + lds_wbase + _i * 8192), 16, 0, 0); } } while (0)
; #define LDA(dst, b, h) _Pragma("unroll") for (int m = 0; m < 4; ++m) _Pragma("unroll") for (int k = 0; k < 2; ++k) \
;     dst[m][k] = *reinterpret_cast<const bf16x8*>((char*)SA(b, h) + lds_byte(wr * 64 + m * 16 + fr, k * 32 + fq * 8))
; #define LDB(dst, b, h) _Pragma("unroll") for (int n = 0; n < 2; ++n) _Pragma("unroll") for (int k = 0; k < 2; ++k) \
;     dst[n][k] = *reinterpret_cast<const bf16x8*>((char*)SB(b, h) + lds_byte(wc * 32 + n * 16 + fr, k * 32 + fq * 8))
; #define MMA(ai, bj, At_, Bt_) do { __builtin_amdgcn_s_setprio(1); \
;     _Pragma("unroll") for (int m = 0; m < 4; ++m) _Pragma("unroll") for (int n = 0; n < 2; ++n) _Pragma("unroll") for (int k = 0; k < 2; ++k) \
;       acc[ai][bj][m][n] = __builtin_amdgcn_mfma_f32_16x16x32_bf16(At_[m][k], Bt_[n][k], acc[ai][bj][m][n], 0, 0, 0); \
;     __builtin_amdgcn_s_setprio(0); } while (0)
; #define WAIT_L(n) asm volatile("s_waitcnt lgkmcnt(" #n ")" ::: "memory")
; #define BAR __builtin_amdgcn_s_barrier()
; #define SCHED __builtin_amdgcn_sched_barrier(0)
; #define STAGEW(P_, BASE, cur, nxt, kt_) do { const bool _wr = (kt_) >= nt; \
;     STAGE(P_, BASE, (_wr ? (nxt) : (cur)), (_wr ? (kt_) - nt : (kt_))); } while (0)
; template <int PRE> ...
;     ...
;     LDB(B0, 0, 0); SCHED; LDA(At, 0, 0); STAGE(SA(1, 1), A, brow + HALF, t + 1);
;     WAIT_L(8); BAR; WAIT_L(0); MMA(0, 0, At, B0); BAR; SCHED;
;     LDB(B1, 0, 1); STAGEW(SB(0, 0), Bt, bcol, bcol_n, t + 2);
;     BAR; WAIT_L(0); MMA(0, 1, At, B1); BAR;
;     LDA(At, 0, 1); STAGEW(SA(0, 0), A, brow, brow_n, t + 2);
;     BAR; WAIT_L(0); MMA(1, 0, At, B0); BAR; SCHED;
.LBB0_1083:
	v_add_u32_e32 v142, s81, v151
	ds_read_b128 v[134:137], v142
	ds_read_b128 v[138:141], v142 offset:1024
	ds_read_b128 v[146:149], v142 offset:2048
	ds_read_b128 v[156:159], v142 offset:3072
	s_add_i32 m0, s2, 0xc000
	ds_read_b128 v[160:163], v144
	ds_read_b128 v[168:171], v144 offset:1024
	ds_read_b128 v[172:175], v152
	ds_read_b128 v[176:179], v152 offset:1024
	ds_read_b128 v[180:183], v153
	ds_read_b128 v[184:187], v153 offset:1024
	ds_read_b128 v[188:191], v154
	ds_read_b128 v[192:195], v154 offset:1024
	global_load_lds_dwordx4 v[128:129], off
	v_lshl_add_u64 v[142:143], v[128:129], 0, s[40:41]
	s_add_i32 m0, s2, 0xe000
	s_nop 0
	global_load_lds_dwordx4 v[142:143], off
	s_waitcnt lgkmcnt(8)
	s_barrier
	s_waitcnt lgkmcnt(0)
	v_mfma_f32_16x16x32_bf16 v[124:127], v[160:163], v[134:137], v[124:127]
	v_mfma_f32_16x16x32_bf16 v[120:123], v[160:163], v[146:149], v[120:123]
	v_mfma_f32_16x16x32_bf16 v[116:119], v[172:175], v[134:137], v[116:119]
	v_mfma_f32_16x16x32_bf16 v[112:115], v[172:175], v[146:149], v[112:115]
	v_mfma_f32_16x16x32_bf16 v[108:111], v[180:183], v[134:137], v[108:111]
	v_mfma_f32_16x16x32_bf16 v[104:107], v[180:183], v[146:149], v[104:107]
	v_mfma_f32_16x16x32_bf16 v[100:103], v[188:191], v[134:137], v[100:103]
	v_mfma_f32_16x16x32_bf16 v[96:99], v[188:191], v[146:149], v[96:99]
	v_mfma_f32_16x16x32_bf16 v[124:127], v[168:171], v[138:141], v[124:127]
	v_mfma_f32_16x16x32_bf16 v[120:123], v[168:171], v[156:159], v[120:123]
	v_mfma_f32_16x16x32_bf16 v[116:119], v[176:179], v[138:141], v[116:119]
	v_mfma_f32_16x16x32_bf16 v[112:115], v[176:179], v[156:159], v[112:115]
	v_mfma_f32_16x16x32_bf16 v[108:111], v[184:187], v[138:141], v[108:111]
	v_mfma_f32_16x16x32_bf16 v[104:107], v[184:187], v[156:159], v[104:107]
	v_mfma_f32_16x16x32_bf16 v[100:103], v[192:195], v[138:141], v[100:103]
	v_mfma_f32_16x16x32_bf16 v[96:99], v[192:195], v[156:159], v[96:99]
	s_barrier
	s_add_i32 s34, s31, 2
	s_cmpk_lt_u32 s31, 0x56
	s_cselect_b64 s[0:1], -1, 0
	s_and_b64 vcc, s[0:1], exec
	s_cselect_b32 s0, s24, s26
	s_mulk_i32 s0, 0x1600
	s_cselect_b32 s18, 0, 0xffffffa8
	s_cselect_b32 s35, s23, s25
	s_cselect_b32 s38, s29, s28
	s_cselect_b32 s39, s27, s30
	s_ashr_i32 s1, s0, 31
	s_lshl_b64 s[0:1], s[0:1], 1
	s_add_u32 s36, s66, s0
	s_addc_u32 s37, s67, s1
	s_add_i32 s18, s34, s18
	s_lshl_b64 s[0:1], s[18:19], 7
	s_add_u32 s36, s36, s0
	v_add_u32_e32 v142, s82, v151
	s_addc_u32 s37, s37, s1
	s_mov_b32 m0, s3
	ds_read_b128 v[210:213], v142
	ds_read_b128 v[214:217], v142 offset:1024
	ds_read_b128 v[218:221], v142 offset:2048
	ds_read_b128 v[222:225], v142 offset:3072
	v_lshl_add_u64 v[142:143], s[36:37], 0, v[130:131]
	global_load_lds_dwordx4 v[142:143], off
	v_lshl_add_u64 v[142:143], v[142:143], 0, s[40:41]
	s_mov_b32 m0, s4
	s_nop 0
	global_load_lds_dwordx4 v[142:143], off
	s_barrier
	s_waitcnt lgkmcnt(0)
	v_mfma_f32_16x16x32_bf16 v[92:95], v[160:163], v[210:213], v[92:95]
	v_mfma_f32_16x16x32_bf16 v[88:91], v[160:163], v[218:221], v[88:91]
	v_mfma_f32_16x16x32_bf16 v[84:87], v[172:175], v[210:213], v[84:87]
	v_mfma_f32_16x16x32_bf16 v[80:83], v[172:175], v[218:221], v[80:83]
	v_mfma_f32_16x16x32_bf16 v[76:79], v[180:183], v[210:213], v[76:79]
	v_mfma_f32_16x16x32_bf16 v[72:75], v[180:183], v[218:221], v[72:75]
	v_mfma_f32_16x16x32_bf16 v[68:71], v[188:191], v[210:213], v[68:71]
	v_mfma_f32_16x16x32_bf16 v[64:67], v[188:191], v[218:221], v[64:67]
	v_mfma_f32_16x16x32_bf16 v[92:95], v[168:171], v[214:217], v[92:95]
	v_mfma_f32_16x16x32_bf16 v[88:91], v[168:171], v[222:225], v[88:91]
	v_mfma_f32_16x16x32_bf16 v[84:87], v[176:179], v[214:217], v[84:87]
	v_mfma_f32_16x16x32_bf16 v[80:83], v[176:179], v[222:225], v[80:83]
	v_mfma_f32_16x16x32_bf16 v[76:79], v[184:187], v[214:217], v[76:79]
	v_mfma_f32_16x16x32_bf16 v[72:75], v[184:187], v[222:225], v[72:75]
	v_mfma_f32_16x16x32_bf16 v[68:71], v[192:195], v[214:217], v[68:71]
	v_mfma_f32_16x16x32_bf16 v[64:67], v[192:195], v[222:225], v[64:67]
	s_mul_hi_i32 s18, s35, 0x2c00
	s_mulk_i32 s35, 0x2c00
	s_add_u32 s35, s79, s35
	s_addc_u32 s18, s80, s18
	s_add_u32 s36, s35, s0
	s_addc_u32 s37, s18, s1
	s_mov_b32 m0, s2
	v_lshl_add_u64 v[142:143], s[36:37], 0, v[130:131]
	s_barrier
	ds_read_b128 v[160:163], v144 offset:16384
	ds_read_b128 v[168:171], v144 offset:17408
	ds_read_b128 v[172:175], v152 offset:16384
	ds_read_b128 v[176:179], v152 offset:17408
	ds_read_b128 v[180:183], v153 offset:16384
	ds_read_b128 v[184:187], v153 offset:17408
	ds_read_b128 v[188:191], v154 offset:16384
	ds_read_b128 v[192:195], v154 offset:17408
	global_load_lds_dwordx4 v[142:143], off
	v_lshl_add_u64 v[142:143], v[142:143], 0, s[40:41]
	s_mov_b32 m0, s5
	s_nop 0
	global_load_lds_dwordx4 v[142:143], off
	s_barrier
	s_waitcnt lgkmcnt(0)
	v_mfma_f32_16x16x32_bf16 v[60:63], v[160:163], v[134:137], v[60:63]
	v_mfma_f32_16x16x32_bf16 v[56:59], v[160:163], v[146:149], v[56:59]
	v_mfma_f32_16x16x32_bf16 v[52:55], v[172:175], v[134:137], v[52:55]
	v_mfma_f32_16x16x32_bf16 v[48:51], v[172:175], v[146:149], v[48:51]
	v_mfma_f32_16x16x32_bf16 v[44:47], v[180:183], v[134:137], v[44:47]
	v_mfma_f32_16x16x32_bf16 v[40:43], v[180:183], v[146:149], v[40:43]
	v_mfma_f32_16x16x32_bf16 v[36:39], v[188:191], v[134:137], v[36:39]
	v_mfma_f32_16x16x32_bf16 v[32:35], v[188:191], v[146:149], v[32:35]
	v_mfma_f32_16x16x32_bf16 v[60:63], v[168:171], v[138:141], v[60:63]
	v_mfma_f32_16x16x32_bf16 v[56:59], v[168:171], v[156:159], v[56:59]
	v_mfma_f32_16x16x32_bf16 v[52:55], v[176:179], v[138:141], v[52:55]
	v_mfma_f32_16x16x32_bf16 v[48:51], v[176:179], v[156:159], v[48:51]
	v_mfma_f32_16x16x32_bf16 v[44:47], v[184:187], v[138:141], v[44:47]
	v_mfma_f32_16x16x32_bf16 v[40:43], v[184:187], v[156:159], v[40:43]
	v_mfma_f32_16x16x32_bf16 v[36:39], v[192:195], v[138:141], v[36:39]
	v_mfma_f32_16x16x32_bf16 v[32:35], v[192:195], v[156:159], v[32:35]
	s_barrier
; #define LDA(dst, b, h) _Pragma("unroll") for (int m = 0; m < 4; ++m) _Pragma("unroll") for (int k = 0; k < 2; ++k) \
;     dst[m][k] = *reinterpret_cast<const bf16x8*>((char*)SA(b, h) + lds_byte(wr * 64 + m * 16 + fr, k * 32 + fq * 8))
; #define LDB(dst, b, h) _Pragma("unroll") for (int n = 0; n < 2; ++n) _Pragma("unroll") for (int k = 0; k < 2; ++k) \
;     dst[n][k] = *reinterpret_cast<const bf16x8*>((char*)SB(b, h) + lds_byte(wc * 32 + n * 16 + fr, k * 32 + fq * 8))
; #define MMA(ai, bj, At_, Bt_) do { __builtin_amdgcn_s_setprio(1); \
;     _Pragma("unroll") for (int m = 0; m < 4; ++m) _Pragma("unroll") for (int n = 0; n < 2; ++n) _Pragma("unroll") for (int k = 0; k < 2; ++k) \
;       acc[ai][bj][m][n] = __builtin_amdgcn_mfma_f32_16x16x32_bf16(At_[m][k], Bt_[n][k], acc[ai][bj][m][n], 0, 0, 0); \
;     __builtin_amdgcn_s_setprio(0); } while (0)
; #define WAIT_V(n) asm volatile("s_waitcnt vmcnt(" #n ")" ::: "memory")
; #define WAIT_L(n) asm volatile("s_waitcnt lgkmcnt(" #n ")" ::: "memory")
; #define BAR __builtin_amdgcn_s_barrier()
; #define SCHED __builtin_amdgcn_sched_barrier(0)
; #define STAGEW(P_, BASE, cur, nxt, kt_) do { const bool _wr = (kt_) >= nt; \
;     STAGE(P_, BASE, (_wr ? (nxt) : (cur)), (_wr ? (kt_) - nt : (kt_))); } while (0)
; template <int PRE> ...
;     ...
;     STAGEW(SB(0, 1), Bt, bcol + HALF, bcol_n + HALF, t + 2);
;     WAIT_V(6); BAR; MMA(1, 1, At, B1); BAR;
;     LDB(B0, 1, 0); SCHED; LDA(At, 1, 0); STAGEW(SA(0, 1), A, brow + HALF, brow_n + HALF, t + 2);
;     WAIT_L(8); BAR; WAIT_L(0); MMA(0, 0, At, B0); BAR; SCHED;
;     LDB(B1, 1, 1); STAGEW(SB(1, 0), Bt, bcol, bcol_n, t + 3);
;     BAR; WAIT_L(0); MMA(0, 1, At, B1); BAR;
	s_mul_i32 s36, s38, 0x1600
	s_ashr_i32 s37, s36, 31
	s_lshl_b64 s[36:37], s[36:37], 1
	s_add_u32 s18, s66, s36
	s_addc_u32 s35, s67, s37
	s_add_u32 s36, s18, s0
	s_addc_u32 s37, s35, s1
	s_mov_b32 m0, s10
	v_lshl_add_u64 v[134:135], s[36:37], 0, v[130:131]
	global_load_lds_dwordx4 v[134:135], off
	v_lshl_add_u64 v[134:135], v[134:135], 0, s[40:41]
	s_mov_b32 m0, s11
	s_nop 0
	global_load_lds_dwordx4 v[134:135], off
	s_waitcnt vmcnt(6)
	s_barrier
	v_mfma_f32_16x16x32_bf16 v[28:31], v[160:163], v[210:213], v[28:31]
	v_mfma_f32_16x16x32_bf16 v[24:27], v[160:163], v[218:221], v[24:27]
	v_mfma_f32_16x16x32_bf16 v[20:23], v[172:175], v[210:213], v[20:23]
	v_mfma_f32_16x16x32_bf16 v[16:19], v[172:175], v[218:221], v[16:19]
	v_mfma_f32_16x16x32_bf16 v[12:15], v[180:183], v[210:213], v[12:15]
	v_mfma_f32_16x16x32_bf16 v[8:11], v[180:183], v[218:221], v[8:11]
	v_mfma_f32_16x16x32_bf16 v[4:7], v[188:191], v[210:213], v[4:7]
	v_mfma_f32_16x16x32_bf16 v[0:3], v[188:191], v[218:221], v[0:3]
	v_mfma_f32_16x16x32_bf16 v[28:31], v[168:171], v[214:217], v[28:31]
	v_mfma_f32_16x16x32_bf16 v[24:27], v[168:171], v[222:225], v[24:27]
	v_mfma_f32_16x16x32_bf16 v[20:23], v[176:179], v[214:217], v[20:23]
	v_mfma_f32_16x16x32_bf16 v[16:19], v[176:179], v[222:225], v[16:19]
	v_mfma_f32_16x16x32_bf16 v[12:15], v[184:187], v[214:217], v[12:15]
	v_mfma_f32_16x16x32_bf16 v[8:11], v[184:187], v[222:225], v[8:11]
	v_mfma_f32_16x16x32_bf16 v[4:7], v[192:195], v[214:217], v[4:7]
	v_mfma_f32_16x16x32_bf16 v[0:3], v[192:195], v[222:225], v[0:3]
	v_add_u32_e32 v142, s83, v151
	s_barrier
	ds_read_b128 v[134:137], v142
	ds_read_b128 v[138:141], v142 offset:1024
	ds_read_b128 v[146:149], v142 offset:2048
	ds_read_b128 v[156:159], v142 offset:3072
	s_mul_hi_i32 s18, s39, 0x2c00
	s_mulk_i32 s39, 0x2c00
	s_add_u32 s35, s79, s39
	s_addc_u32 s18, s80, s18
	s_add_u32 s0, s35, s0
	s_addc_u32 s1, s18, s1
	s_mov_b32 m0, s12
	v_lshl_add_u64 v[142:143], s[0:1], 0, v[130:131]
	ds_read_b128 v[160:163], v144 offset:32768
	ds_read_b128 v[168:171], v144 offset:33792
	ds_read_b128 v[172:175], v152 offset:32768
	ds_read_b128 v[176:179], v152 offset:33792
	ds_read_b128 v[180:183], v153 offset:32768
	ds_read_b128 v[184:187], v153 offset:33792
	ds_read_b128 v[188:191], v154 offset:32768
	ds_read_b128 v[192:195], v154 offset:33792
	global_load_lds_dwordx4 v[142:143], off
	v_lshl_add_u64 v[142:143], v[142:143], 0, s[40:41]
	s_mov_b32 m0, s13
	s_nop 0
	global_load_lds_dwordx4 v[142:143], off
	s_waitcnt lgkmcnt(8)
	s_barrier
	s_waitcnt lgkmcnt(0)
	v_mfma_f32_16x16x32_bf16 v[124:127], v[160:163], v[134:137], v[124:127]
	v_mfma_f32_16x16x32_bf16 v[120:123], v[160:163], v[146:149], v[120:123]
	v_mfma_f32_16x16x32_bf16 v[116:119], v[172:175], v[134:137], v[116:119]
	v_mfma_f32_16x16x32_bf16 v[112:115], v[172:175], v[146:149], v[112:115]
	v_mfma_f32_16x16x32_bf16 v[108:111], v[180:183], v[134:137], v[108:111]
	v_mfma_f32_16x16x32_bf16 v[104:107], v[180:183], v[146:149], v[104:107]
	v_mfma_f32_16x16x32_bf16 v[100:103], v[188:191], v[134:137], v[100:103]
	v_mfma_f32_16x16x32_bf16 v[96:99], v[188:191], v[146:149], v[96:99]
	v_mfma_f32_16x16x32_bf16 v[124:127], v[168:171], v[138:141], v[124:127]
	v_mfma_f32_16x16x32_bf16 v[120:123], v[168:171], v[156:159], v[120:123]
	v_mfma_f32_16x16x32_bf16 v[116:119], v[176:179], v[138:141], v[116:119]
	v_mfma_f32_16x16x32_bf16 v[112:115], v[176:179], v[156:159], v[112:115]
	v_mfma_f32_16x16x32_bf16 v[108:111], v[184:187], v[138:141], v[108:111]
	v_mfma_f32_16x16x32_bf16 v[104:107], v[184:187], v[156:159], v[104:107]
	v_mfma_f32_16x16x32_bf16 v[100:103], v[192:195], v[138:141], v[100:103]
	v_mfma_f32_16x16x32_bf16 v[96:99], v[192:195], v[156:159], v[96:99]
	s_barrier
	s_cmpk_lt_u32 s31, 0x55
	s_cselect_b32 s0, s24, s26
	s_mulk_i32 s0, 0x1600
	s_cselect_b32 s18, 0, 0xffffffa8
	s_cselect_b32 s35, s23, s25
	s_cselect_b32 s38, s29, s28
	s_ashr_i32 s1, s0, 31
	s_lshl_b64 s[0:1], s[0:1], 1
	s_add_u32 s36, s66, s0
	s_addc_u32 s37, s67, s1
	s_add_i32 s0, s18, s31
	s_add_i32 s18, s0, 3
	s_lshl_b64 s[0:1], s[18:19], 7
	s_add_u32 s36, s36, s0
	v_add_u32_e32 v142, s84, v151
	s_addc_u32 s37, s37, s1
	s_mov_b32 m0, s14
	ds_read_b128 v[210:213], v142
	ds_read_b128 v[214:217], v142 offset:1024
	ds_read_b128 v[218:221], v142 offset:2048
	ds_read_b128 v[222:225], v142 offset:3072
	v_lshl_add_u64 v[142:143], s[36:37], 0, v[130:131]
	global_load_lds_dwordx4 v[142:143], off
	v_lshl_add_u64 v[142:143], v[142:143], 0, s[40:41]
	s_mov_b32 m0, s15
	s_nop 0
	global_load_lds_dwordx4 v[142:143], off
	s_barrier
; #define LDA(dst, b, h) _Pragma("unroll") for (int m = 0; m < 4; ++m) _Pragma("unroll") for (int k = 0; k < 2; ++k) \
;     dst[m][k] = *reinterpret_cast<const bf16x8*>((char*)SA(b, h) + lds_byte(wr * 64 + m * 16 + fr, k * 32 + fq * 8))
; #define MMA(ai, bj, At_, Bt_) do { __builtin_amdgcn_s_setprio(1); \
;     _Pragma("unroll") for (int m = 0; m < 4; ++m) _Pragma("unroll") for (int n = 0; n < 2; ++n) _Pragma("unroll") for (int k = 0; k < 2; ++k) \
;       acc[ai][bj][m][n] = __builtin_amdgcn_mfma_f32_16x16x32_bf16(At_[m][k], Bt_[n][k], acc[ai][bj][m][n], 0, 0, 0); \
;     __builtin_amdgcn_s_setprio(0); } while (0)
; #define WAIT_V(n) asm volatile("s_waitcnt vmcnt(" #n ")" ::: "memory")
; #define WAIT_L(n) asm volatile("s_waitcnt lgkmcnt(" #n ")" ::: "memory")
; #define BAR __builtin_amdgcn_s_barrier()
; #define SCHED __builtin_amdgcn_sched_barrier(0)
; #define STAGEW(P_, BASE, cur, nxt, kt_) do { const bool _wr = (kt_) >= nt; \
;     STAGE(P_, BASE, (_wr ? (nxt) : (cur)), (_wr ? (kt_) - nt : (kt_))); } while (0)
; template <int PRE> ...
;     ...
;     BAR; WAIT_L(0); MMA(0, 1, At, B1); BAR;
;     LDA(At, 1, 1); STAGEW(SA(1, 0), A, brow, brow_n, t + 3);
;     BAR; WAIT_L(0); MMA(1, 0, At, B0); BAR; SCHED;
;     STAGEW(SB(1, 1), Bt, bcol + HALF, bcol_n + HALF, t + 3);
;     WAIT_V(6); BAR; MMA(1, 1, At, B1); BAR;
;   }
	s_waitcnt lgkmcnt(0)
	v_mfma_f32_16x16x32_bf16 v[92:95], v[160:163], v[210:213], v[92:95]
	v_mfma_f32_16x16x32_bf16 v[88:91], v[160:163], v[218:221], v[88:91]
	v_mfma_f32_16x16x32_bf16 v[84:87], v[172:175], v[210:213], v[84:87]
	v_mfma_f32_16x16x32_bf16 v[80:83], v[172:175], v[218:221], v[80:83]
	v_mfma_f32_16x16x32_bf16 v[76:79], v[180:183], v[210:213], v[76:79]
	v_mfma_f32_16x16x32_bf16 v[72:75], v[180:183], v[218:221], v[72:75]
	v_mfma_f32_16x16x32_bf16 v[68:71], v[188:191], v[210:213], v[68:71]
	v_mfma_f32_16x16x32_bf16 v[64:67], v[188:191], v[218:221], v[64:67]
	v_mfma_f32_16x16x32_bf16 v[92:95], v[168:171], v[214:217], v[92:95]
	v_mfma_f32_16x16x32_bf16 v[88:91], v[168:171], v[222:225], v[88:91]
	v_mfma_f32_16x16x32_bf16 v[84:87], v[176:179], v[214:217], v[84:87]
	v_mfma_f32_16x16x32_bf16 v[80:83], v[176:179], v[222:225], v[80:83]
	v_mfma_f32_16x16x32_bf16 v[76:79], v[184:187], v[214:217], v[76:79]
	v_mfma_f32_16x16x32_bf16 v[72:75], v[184:187], v[222:225], v[72:75]
	v_mfma_f32_16x16x32_bf16 v[68:71], v[192:195], v[214:217], v[68:71]
	v_mfma_f32_16x16x32_bf16 v[64:67], v[192:195], v[222:225], v[64:67]
	s_mul_hi_i32 s18, s35, 0x2c00
	s_mulk_i32 s35, 0x2c00
	s_add_u32 s31, s79, s35
	s_addc_u32 s18, s80, s18
	s_add_u32 s36, s31, s0
	s_addc_u32 s37, s18, s1
	s_mov_b32 m0, s16
	v_lshl_add_u64 v[142:143], s[36:37], 0, v[130:131]
	s_barrier
	ds_read_b128 v[160:163], v144 offset:49152
	ds_read_b128 v[168:171], v144 offset:50176
	ds_read_b128 v[172:175], v152 offset:49152
	ds_read_b128 v[176:179], v152 offset:50176
	ds_read_b128 v[180:183], v153 offset:49152
	ds_read_b128 v[184:187], v153 offset:50176
	ds_read_b128 v[188:191], v154 offset:49152
	ds_read_b128 v[192:195], v154 offset:50176
	global_load_lds_dwordx4 v[142:143], off
	v_lshl_add_u64 v[142:143], v[142:143], 0, s[40:41]
	s_mov_b32 m0, s17
	s_nop 0
	global_load_lds_dwordx4 v[142:143], off
	s_barrier
	s_waitcnt lgkmcnt(0)
	v_mfma_f32_16x16x32_bf16 v[60:63], v[160:163], v[134:137], v[60:63]
	v_mfma_f32_16x16x32_bf16 v[56:59], v[160:163], v[146:149], v[56:59]
	v_mfma_f32_16x16x32_bf16 v[52:55], v[172:175], v[134:137], v[52:55]
	v_mfma_f32_16x16x32_bf16 v[48:51], v[172:175], v[146:149], v[48:51]
	v_mfma_f32_16x16x32_bf16 v[44:47], v[180:183], v[134:137], v[44:47]
	v_mfma_f32_16x16x32_bf16 v[40:43], v[180:183], v[146:149], v[40:43]
	v_mfma_f32_16x16x32_bf16 v[36:39], v[188:191], v[134:137], v[36:39]
	v_mfma_f32_16x16x32_bf16 v[32:35], v[188:191], v[146:149], v[32:35]
	v_mfma_f32_16x16x32_bf16 v[60:63], v[168:171], v[138:141], v[60:63]
	v_mfma_f32_16x16x32_bf16 v[56:59], v[168:171], v[156:159], v[56:59]
	v_mfma_f32_16x16x32_bf16 v[52:55], v[176:179], v[138:141], v[52:55]
	v_mfma_f32_16x16x32_bf16 v[48:51], v[176:179], v[156:159], v[48:51]
	v_mfma_f32_16x16x32_bf16 v[44:47], v[184:187], v[138:141], v[44:47]
	v_mfma_f32_16x16x32_bf16 v[40:43], v[184:187], v[156:159], v[40:43]
	v_mfma_f32_16x16x32_bf16 v[36:39], v[192:195], v[138:141], v[36:39]
	v_mfma_f32_16x16x32_bf16 v[32:35], v[192:195], v[156:159], v[32:35]
	s_barrier
	s_mul_i32 s36, s38, 0x1600
	s_ashr_i32 s37, s36, 31
	s_lshl_b64 s[36:37], s[36:37], 1
	s_add_u32 s18, s66, s36
	s_addc_u32 s31, s67, s37
	s_add_u32 s0, s18, s0
	s_addc_u32 s1, s31, s1
	s_mov_b32 m0, s20
	v_lshl_add_u64 v[134:135], s[0:1], 0, v[130:131]
	global_load_lds_dwordx4 v[134:135], off
	v_lshl_add_u64 v[134:135], v[134:135], 0, s[40:41]
	s_mov_b32 m0, s21
	s_nop 0
	global_load_lds_dwordx4 v[134:135], off
	s_waitcnt vmcnt(6)
	s_barrier
	v_mfma_f32_16x16x32_bf16 v[28:31], v[160:163], v[210:213], v[28:31]
	v_mfma_f32_16x16x32_bf16 v[24:27], v[160:163], v[218:221], v[24:27]
	v_mfma_f32_16x16x32_bf16 v[20:23], v[172:175], v[210:213], v[20:23]
	v_mfma_f32_16x16x32_bf16 v[16:19], v[172:175], v[218:221], v[16:19]
	v_mfma_f32_16x16x32_bf16 v[12:15], v[180:183], v[210:213], v[12:15]
	v_mfma_f32_16x16x32_bf16 v[8:11], v[180:183], v[218:221], v[8:11]
	v_mfma_f32_16x16x32_bf16 v[4:7], v[188:191], v[210:213], v[4:7]
	v_mfma_f32_16x16x32_bf16 v[0:3], v[188:191], v[218:221], v[0:3]
	v_mfma_f32_16x16x32_bf16 v[28:31], v[168:171], v[214:217], v[28:31]
	v_mfma_f32_16x16x32_bf16 v[24:27], v[168:171], v[222:225], v[24:27]
	v_mfma_f32_16x16x32_bf16 v[20:23], v[176:179], v[214:217], v[20:23]
	v_mfma_f32_16x16x32_bf16 v[16:19], v[176:179], v[222:225], v[16:19]
	v_mfma_f32_16x16x32_bf16 v[12:15], v[184:187], v[214:217], v[12:15]
	v_mfma_f32_16x16x32_bf16 v[8:11], v[184:187], v[222:225], v[8:11]
	v_mfma_f32_16x16x32_bf16 v[4:7], v[192:195], v[214:217], v[4:7]
	v_mfma_f32_16x16x32_bf16 v[0:3], v[192:195], v[222:225], v[0:3]
	v_lshl_add_u64 v[128:129], v[128:129], 0, s[46:47]
	s_mov_b32 s31, s34
	s_barrier
	s_cbranch_vccnz .LBB0_1083
	s_andn2_b64 vcc, exec, s[58:59]
	s_cbranch_vccnz .LBB0_1086
	s_barrier
